# attention: row-sum add chain split into 4 independent partial sums in every step (GQA+MLA, loop+tail)
# speedup vs baseline: 1.0088x; 1.0088x over previous
.LBB0_1232:
	s_or_b64 exec, exec, s[28:29]
	s_waitcnt lgkmcnt(0)
	ds_read_b128 v[2:5], v212 offset:128
	ds_read_b128 v[6:9], v212 offset:160
	s_lshl_b32 s4, s27, 12
	s_add_i32 s4, s4, 0
	s_add_i32 s4, s4, 0x10800
	s_waitcnt lgkmcnt(1)
	v_rcp_f32_e32 v10, v2
	v_rcp_f32_e32 v11, v3
	v_lshlrev_b32_e32 v68, 9, v215
	v_lshlrev_b32_e32 v69, 1, v214
	v_mul_f32_e32 v32, v32, v10
	v_mul_f32_e32 v10, v48, v10
	v_add3_u32 v68, s4, v68, v69
	v_cvt_pk_bf16_f32 v10, v10, s0
	v_rcp_f32_e32 v12, v4
	ds_write_b16 v68, v10 offset:64
	v_mul_f32_e32 v10, v33, v11
	v_cvt_pk_bf16_f32 v10, v10, s0
	ds_write_b16 v68, v10 offset:128
	v_mul_f32_e32 v10, v49, v11
	v_cvt_pk_bf16_f32 v10, v10, s0
	v_rcp_f32_e32 v13, v5
	ds_write_b16 v68, v10 offset:192
	v_mul_f32_e32 v10, v34, v12
	v_cvt_pk_bf16_f32 v10, v10, s0
	ds_write_b16 v68, v10 offset:256
	v_mul_f32_e32 v10, v50, v12
	v_cvt_pk_bf16_f32 v10, v10, s0
	s_waitcnt lgkmcnt(4)
	v_rcp_f32_e32 v64, v6
	ds_write_b16 v68, v10 offset:320
	v_mul_f32_e32 v10, v35, v13
	v_cvt_pk_bf16_f32 v10, v10, s0
	ds_write_b16 v68, v10 offset:384
	v_mul_f32_e32 v10, v51, v13
	v_cvt_pk_bf16_f32 v10, v10, s0
	v_rcp_f32_e32 v65, v7
	ds_write_b16 v68, v10 offset:448
	v_mul_f32_e32 v10, v36, v64
	v_cvt_pk_bf16_f32 v10, v10, s0
	ds_write_b16 v68, v10 offset:1024
	v_mul_f32_e32 v10, v52, v64
	v_cvt_pk_bf16_f32 v10, v10, s0
	v_rcp_f32_e32 v66, v8
	ds_write_b16 v68, v10 offset:1088
	v_mul_f32_e32 v10, v37, v65
	v_cvt_pk_bf16_f32 v10, v10, s0
	ds_write_b16 v68, v10 offset:1152
	v_mul_f32_e32 v10, v53, v65
	ds_read_b128 v[2:5], v212 offset:192
	v_cvt_pk_bf16_f32 v10, v10, s0
	v_rcp_f32_e32 v67, v9
	ds_write_b16 v68, v10 offset:1216
	v_mul_f32_e32 v10, v38, v66
	v_cvt_pk_bf16_f32 v10, v10, s0
	ds_write_b16 v68, v10 offset:1280
	v_mul_f32_e32 v10, v54, v66
	v_cvt_pk_bf16_f32 v10, v10, s0
	ds_read_b128 v[6:9], v212 offset:224
	s_waitcnt lgkmcnt(3)
	v_rcp_f32_e32 v2, v2
	ds_write_b16 v68, v10 offset:1344
	v_mul_f32_e32 v10, v39, v67
	v_cvt_pk_bf16_f32 v10, v10, s0
	v_rcp_f32_e32 v3, v3
	ds_write_b16 v68, v10 offset:1408
	v_mul_f32_e32 v10, v55, v67
	v_cvt_pk_bf16_f32 v10, v10, s0
	ds_write_b16 v68, v10 offset:1472
	v_mul_f32_e32 v10, v40, v2
	v_mul_f32_e32 v2, v56, v2
	v_cvt_pk_bf16_f32 v2, v2, s0
	v_rcp_f32_e32 v4, v4
	ds_write_b16 v68, v2 offset:2112
	v_mul_f32_e32 v2, v41, v3
	v_cvt_pk_bf16_f32 v2, v2, s0
	ds_write_b16 v68, v2 offset:2176
	v_mul_f32_e32 v2, v57, v3
	v_cvt_pk_bf16_f32 v2, v2, s0
	v_rcp_f32_e32 v5, v5
	ds_write_b16 v68, v2 offset:2240
	v_mul_f32_e32 v2, v42, v4
	v_cvt_pk_bf16_f32 v2, v2, s0
	ds_write_b16 v68, v2 offset:2304
	v_mul_f32_e32 v2, v58, v4
	v_cvt_pk_bf16_f32 v2, v2, s0
	s_waitcnt lgkmcnt(7)
	v_rcp_f32_e32 v6, v6
	ds_write_b16 v68, v2 offset:2368
	v_mul_f32_e32 v2, v43, v5
	v_cvt_pk_bf16_f32 v2, v2, s0
	ds_write_b16 v68, v2 offset:2432
	v_mul_f32_e32 v2, v59, v5
	v_cvt_pk_bf16_f32 v2, v2, s0
	v_rcp_f32_e32 v7, v7
	ds_write_b16 v68, v2 offset:2496
	v_mul_f32_e32 v2, v44, v6
	v_cvt_pk_bf16_f32 v2, v2, s0
	ds_write_b16 v68, v2 offset:3072
	v_mul_f32_e32 v2, v60, v6
	v_cvt_pk_bf16_f32 v2, v2, s0
	v_rcp_f32_e32 v8, v8
	ds_write_b16 v68, v2 offset:3136
	v_mul_f32_e32 v2, v45, v7
	v_cvt_pk_bf16_f32 v2, v2, s0
	ds_write_b16 v68, v2 offset:3200
	v_mul_f32_e32 v2, v61, v7
	v_cvt_pk_bf16_f32 v2, v2, s0
	v_rcp_f32_e32 v9, v9
	ds_write_b16 v68, v2 offset:3264
	v_mul_f32_e32 v2, v46, v8
	v_cvt_pk_bf16_f32 v2, v2, s0
	ds_write_b16 v68, v2 offset:3328
	v_mul_f32_e32 v2, v62, v8
	v_cvt_pk_bf16_f32 v2, v2, s0
	ds_write_b16 v68, v2 offset:3392
	v_mul_f32_e32 v2, v47, v9
	s_waitcnt vmcnt(3)
	v_lshlrev_b32_e32 v12, 16, v140
	v_cvt_pk_bf16_f32 v2, v2, s0
	v_and_b32_e32 v13, 0xffff0000, v140
	v_mul_f32_e32 v4, 0xbfb8aa3b, v12
	ds_write_b16 v68, v2 offset:3456
	v_mul_f32_e32 v2, v63, v9
	v_exp_f32_e32 v8, v4
	v_mul_f32_e32 v4, 0xbfb8aa3b, v13
	v_cvt_pk_bf16_f32 v32, v32, s0
	v_cvt_pk_bf16_f32 v10, v10, s0
	v_cvt_pk_bf16_f32 v2, v2, s0
	v_add_u32_e32 v36, s4, v0
	s_add_u32 s4, s50, s8
	v_exp_f32_e32 v9, v4
	ds_write_b16 v68, v32
	ds_write_b16 v68, v10 offset:2048
	ds_write_b16 v68, v2 offset:3520
	s_addc_u32 s5, s51, 0
	s_waitcnt lgkmcnt(0)
	v_lshl_add_u64 v[2:3], s[4:5], 0, v[0:1]
	v_lshl_add_u32 v0, v200, 7, v36
	ds_read_b128 v[4:7], v0
	v_add_f32_e32 v0, 1.0, v8
	v_rcp_f32_e32 v32, v0
	v_add_f32_e32 v0, 1.0, v9
	v_rcp_f32_e32 v33, v0
	s_waitcnt lgkmcnt(0)
	v_lshlrev_b32_e32 v34, 16, v4
	v_and_b32_e32 v35, 0xffff0000, v4
	v_or_b32_e32 v0, 8, v200
	v_pk_mul_f32 v[12:13], v[32:33], v[12:13]
	v_lshlrev_b32_e32 v32, 16, v141
	v_and_b32_e32 v33, 0xffff0000, v141
	v_mul_f32_e32 v4, 0xbfb8aa3b, v32
	v_exp_f32_e32 v4, v4
	v_mul_f32_e32 v37, 0xbfb8aa3b, v33
	v_exp_f32_e32 v37, v37
	v_pk_mul_f32 v[12:13], v[12:13], v[34:35]
	v_add_f32_e32 v4, 1.0, v4
	v_rcp_f32_e32 v34, v4
	v_add_f32_e32 v4, 1.0, v37
	v_rcp_f32_e32 v35, v4
	v_cvt_pk_bf16_f32 v4, v12, v13
	v_lshlrev_b32_e32 v12, 16, v5
	v_and_b32_e32 v13, 0xffff0000, v5
	v_pk_mul_f32 v[32:33], v[34:35], v[32:33]
	v_lshlrev_b32_e32 v34, 16, v142
	v_and_b32_e32 v35, 0xffff0000, v142
	v_mul_f32_e32 v5, 0xbfb8aa3b, v34
	v_exp_f32_e32 v5, v5
	v_mul_f32_e32 v37, 0xbfb8aa3b, v35
	v_exp_f32_e32 v37, v37
	v_pk_mul_f32 v[12:13], v[32:33], v[12:13]
	v_add_f32_e32 v5, 1.0, v5
	v_rcp_f32_e32 v32, v5
	v_add_f32_e32 v5, 1.0, v37
	v_rcp_f32_e32 v33, v5
	v_cvt_pk_bf16_f32 v5, v12, v13
	v_lshlrev_b32_e32 v12, 16, v6
	v_and_b32_e32 v13, 0xffff0000, v6
	v_pk_mul_f32 v[32:33], v[32:33], v[34:35]
	v_lshlrev_b32_e32 v34, 16, v143
	v_and_b32_e32 v35, 0xffff0000, v143
	v_mul_f32_e32 v6, 0xbfb8aa3b, v34
	v_exp_f32_e32 v6, v6
	v_mul_f32_e32 v37, 0xbfb8aa3b, v35
	v_exp_f32_e32 v37, v37
	v_pk_mul_f32 v[12:13], v[32:33], v[12:13]
	v_add_f32_e32 v6, 1.0, v6
	v_rcp_f32_e32 v32, v6
	v_add_f32_e32 v6, 1.0, v37
	v_rcp_f32_e32 v33, v6
	v_cvt_pk_bf16_f32 v6, v12, v13
	v_lshlrev_b32_e32 v12, 16, v7
	v_and_b32_e32 v13, 0xffff0000, v7
	v_pk_mul_f32 v[32:33], v[32:33], v[34:35]
	v_lshl_add_u32 v8, v0, 7, v36
	v_pk_mul_f32 v[12:13], v[32:33], v[12:13]
	ds_read_b128 v[8:11], v8
	v_cvt_pk_bf16_f32 v7, v12, v13
	v_lshl_add_u64 v[12:13], v[2:3], 0, v[14:15]
	global_store_dwordx4 v[12:13], v[4:7], off
	s_waitcnt lgkmcnt(0)
	v_lshlrev_b32_e32 v14, 16, v8
	s_waitcnt vmcnt(3)
	v_lshlrev_b32_e32 v6, 16, v136
	v_and_b32_e32 v7, 0xffff0000, v136
	v_mul_f32_e32 v4, 0xbfb8aa3b, v6
	v_exp_f32_e32 v5, v4
	v_mul_f32_e32 v4, 0xbfb8aa3b, v7
	v_exp_f32_e32 v13, v4
	v_or_b32_e32 v4, s6, v0
	v_add_f32_e32 v0, 1.0, v5
	v_rcp_f32_e32 v12, v0
	v_add_f32_e32 v0, 1.0, v13
	v_rcp_f32_e32 v13, v0
	v_and_b32_e32 v15, 0xffff0000, v8
	v_mov_b32_e32 v5, s7
	v_pk_mul_f32 v[6:7], v[12:13], v[6:7]
	v_lshlrev_b32_e32 v12, 16, v137
	v_and_b32_e32 v13, 0xffff0000, v137
	v_mul_f32_e32 v0, 0xbfb8aa3b, v12
	v_exp_f32_e32 v0, v0
	v_mul_f32_e32 v8, 0xbfb8aa3b, v13
	v_exp_f32_e32 v8, v8
	v_pk_mul_f32 v[6:7], v[6:7], v[14:15]
	v_add_f32_e32 v0, 1.0, v0
	v_rcp_f32_e32 v14, v0
	v_add_f32_e32 v0, 1.0, v8
	v_rcp_f32_e32 v15, v0
	v_cvt_pk_bf16_f32 v6, v6, v7
	v_lshlrev_b32_e32 v8, 16, v9
	v_and_b32_e32 v9, 0xffff0000, v9
	v_pk_mul_f32 v[12:13], v[14:15], v[12:13]
	v_lshlrev_b32_e32 v14, 16, v138
	v_and_b32_e32 v15, 0xffff0000, v138
	v_mul_f32_e32 v0, 0xbfb8aa3b, v14
	v_exp_f32_e32 v0, v0
	v_mul_f32_e32 v7, 0xbfb8aa3b, v15
	v_exp_f32_e32 v7, v7
	v_pk_mul_f32 v[8:9], v[12:13], v[8:9]
	v_add_f32_e32 v0, 1.0, v0
	v_rcp_f32_e32 v12, v0
	v_add_f32_e32 v0, 1.0, v7
	v_rcp_f32_e32 v13, v0
	v_cvt_pk_bf16_f32 v7, v8, v9
	v_lshlrev_b32_e32 v8, 16, v10
	v_and_b32_e32 v9, 0xffff0000, v10
	v_pk_mul_f32 v[12:13], v[12:13], v[14:15]
	v_lshlrev_b32_e32 v14, 16, v139
	v_and_b32_e32 v15, 0xffff0000, v139
	v_mul_f32_e32 v0, 0xbfb8aa3b, v14
	v_exp_f32_e32 v0, v0
	v_mul_f32_e32 v10, 0xbfb8aa3b, v15
	v_exp_f32_e32 v10, v10
	v_pk_mul_f32 v[8:9], v[12:13], v[8:9]
	v_add_f32_e32 v0, 1.0, v0
	v_rcp_f32_e32 v12, v0
	v_add_f32_e32 v0, 1.0, v10
	v_rcp_f32_e32 v13, v0
	v_lshlrev_b32_e32 v10, 16, v11
	v_and_b32_e32 v11, 0xffff0000, v11
	v_cvt_pk_bf16_f32 v8, v8, v9
	v_pk_mul_f32 v[12:13], v[12:13], v[14:15]
	v_or_b32_e32 v0, 16, v200
	v_pk_mul_f32 v[10:11], v[12:13], v[10:11]
	s_waitcnt vmcnt(2)
	v_lshlrev_b32_e32 v14, 16, v132
	v_cvt_pk_bf16_f32 v9, v10, v11
	v_lshlrev_b64 v[10:11], 11, v[4:5]
	v_lshl_add_u64 v[10:11], v[2:3], 0, v[10:11]
	v_lshl_add_u32 v4, v0, 7, v36
	global_store_dwordx4 v[10:11], v[6:9], off
	ds_read_b128 v[6:9], v4
	v_and_b32_e32 v15, 0xffff0000, v132
	v_mul_f32_e32 v4, 0xbfb8aa3b, v14
	v_exp_f32_e32 v10, v4
	v_mul_f32_e32 v4, 0xbfb8aa3b, v15
	v_exp_f32_e32 v11, v4
	v_or_b32_e32 v4, s6, v0
	v_add_f32_e32 v0, 1.0, v10
	v_rcp_f32_e32 v32, v0
	v_add_f32_e32 v0, 1.0, v11
	v_rcp_f32_e32 v33, v0
	v_or_b32_e32 v0, 24, v200
	s_waitcnt lgkmcnt(0)
	v_lshlrev_b32_e32 v34, 16, v6
	v_and_b32_e32 v35, 0xffff0000, v6
	v_pk_mul_f32 v[14:15], v[32:33], v[14:15]
	v_lshlrev_b32_e32 v32, 16, v133
	v_and_b32_e32 v33, 0xffff0000, v133
	v_mul_f32_e32 v6, 0xbfb8aa3b, v32
	v_lshl_add_u32 v10, v0, 7, v36
	v_exp_f32_e32 v6, v6
	v_mul_f32_e32 v36, 0xbfb8aa3b, v33
	v_exp_f32_e32 v36, v36
	v_pk_mul_f32 v[14:15], v[14:15], v[34:35]
	v_add_f32_e32 v6, 1.0, v6
	v_rcp_f32_e32 v34, v6
	v_add_f32_e32 v6, 1.0, v36
	v_rcp_f32_e32 v35, v6
	v_cvt_pk_bf16_f32 v6, v14, v15
	v_lshlrev_b32_e32 v14, 16, v7
	v_and_b32_e32 v15, 0xffff0000, v7
	v_pk_mul_f32 v[32:33], v[34:35], v[32:33]
	v_lshlrev_b32_e32 v34, 16, v134
	v_and_b32_e32 v35, 0xffff0000, v134
	v_mul_f32_e32 v7, 0xbfb8aa3b, v34
	v_exp_f32_e32 v7, v7
	v_mul_f32_e32 v36, 0xbfb8aa3b, v35
	v_exp_f32_e32 v36, v36
	v_pk_mul_f32 v[14:15], v[32:33], v[14:15]
	v_add_f32_e32 v7, 1.0, v7
	v_rcp_f32_e32 v32, v7
	v_add_f32_e32 v7, 1.0, v36
	v_rcp_f32_e32 v33, v7
	v_cvt_pk_bf16_f32 v7, v14, v15
	v_lshlrev_b32_e32 v14, 16, v8
	v_and_b32_e32 v15, 0xffff0000, v8
	v_pk_mul_f32 v[32:33], v[32:33], v[34:35]
	v_lshlrev_b32_e32 v34, 16, v135
	v_and_b32_e32 v35, 0xffff0000, v135
	v_mul_f32_e32 v8, 0xbfb8aa3b, v34
	v_exp_f32_e32 v8, v8
	v_mul_f32_e32 v36, 0xbfb8aa3b, v35
	v_exp_f32_e32 v36, v36
	v_pk_mul_f32 v[14:15], v[32:33], v[14:15]
	v_add_f32_e32 v8, 1.0, v8
	v_rcp_f32_e32 v32, v8
	v_add_f32_e32 v8, 1.0, v36
	v_rcp_f32_e32 v33, v8
	v_cvt_pk_bf16_f32 v8, v14, v15
	v_lshlrev_b32_e32 v14, 16, v9
	v_and_b32_e32 v15, 0xffff0000, v9
	v_pk_mul_f32 v[32:33], v[32:33], v[34:35]
	ds_read_b128 v[10:13], v10
	v_pk_mul_f32 v[14:15], v[32:33], v[14:15]
	s_waitcnt vmcnt(2)
	v_lshlrev_b32_e32 v32, 16, v128
	v_cvt_pk_bf16_f32 v9, v14, v15
	v_lshlrev_b64 v[14:15], 11, v[4:5]
	v_and_b32_e32 v33, 0xffff0000, v128
	v_mul_f32_e32 v4, 0xbfb8aa3b, v32
	v_exp_f32_e32 v4, v4
	v_mul_f32_e32 v34, 0xbfb8aa3b, v33
	v_exp_f32_e32 v34, v34
	v_lshl_add_u64 v[14:15], v[2:3], 0, v[14:15]
	v_add_f32_e32 v4, 1.0, v4
	global_store_dwordx4 v[14:15], v[6:9], off
	v_lshlrev_b32_e32 v14, 16, v129
	v_and_b32_e32 v15, 0xffff0000, v129
	v_rcp_f32_e32 v6, v4
	v_add_f32_e32 v4, 1.0, v34
	v_rcp_f32_e32 v7, v4
	v_or_b32_e32 v4, s6, v0
	v_mul_f32_e32 v0, 0xbfb8aa3b, v14
	s_waitcnt lgkmcnt(0)
	v_lshlrev_b32_e32 v8, 16, v10
	v_and_b32_e32 v9, 0xffff0000, v10
	v_exp_f32_e32 v0, v0
	v_mul_f32_e32 v10, 0xbfb8aa3b, v15
	v_exp_f32_e32 v10, v10
	v_pk_mul_f32 v[6:7], v[6:7], v[32:33]
	v_add_f32_e32 v0, 1.0, v0
	v_pk_mul_f32 v[6:7], v[6:7], v[8:9]
	v_rcp_f32_e32 v8, v0
	v_add_f32_e32 v0, 1.0, v10
	v_rcp_f32_e32 v9, v0
	v_cvt_pk_bf16_f32 v6, v6, v7
	v_lshlrev_b32_e32 v10, 16, v11
	v_and_b32_e32 v11, 0xffff0000, v11
	v_pk_mul_f32 v[8:9], v[8:9], v[14:15]
	v_lshlrev_b32_e32 v14, 16, v130
	v_and_b32_e32 v15, 0xffff0000, v130
	v_mul_f32_e32 v0, 0xbfb8aa3b, v14
	v_exp_f32_e32 v0, v0
	v_mul_f32_e32 v7, 0xbfb8aa3b, v15
	v_exp_f32_e32 v7, v7
	v_pk_mul_f32 v[8:9], v[8:9], v[10:11]
	v_add_f32_e32 v0, 1.0, v0
	v_rcp_f32_e32 v10, v0
	v_add_f32_e32 v0, 1.0, v7
	v_rcp_f32_e32 v11, v0
	v_cvt_pk_bf16_f32 v7, v8, v9
	v_lshlrev_b32_e32 v8, 16, v12
	v_and_b32_e32 v9, 0xffff0000, v12
	v_pk_mul_f32 v[10:11], v[10:11], v[14:15]
	v_lshlrev_b32_e32 v14, 16, v131
	v_and_b32_e32 v15, 0xffff0000, v131
	v_mul_f32_e32 v0, 0xbfb8aa3b, v14
	v_exp_f32_e32 v0, v0
	v_mul_f32_e32 v12, 0xbfb8aa3b, v15
	v_exp_f32_e32 v12, v12
	v_pk_mul_f32 v[8:9], v[10:11], v[8:9]
	v_add_f32_e32 v0, 1.0, v0
	v_rcp_f32_e32 v10, v0
	v_add_f32_e32 v0, 1.0, v12
	v_rcp_f32_e32 v11, v0
	v_lshlrev_b32_e32 v12, 16, v13
	v_and_b32_e32 v13, 0xffff0000, v13
	v_lshlrev_b64 v[4:5], 11, v[4:5]
	v_pk_mul_f32 v[10:11], v[10:11], v[14:15]
	v_cvt_pk_bf16_f32 v8, v8, v9
	v_pk_mul_f32 v[10:11], v[10:11], v[12:13]
	v_lshl_add_u64 v[2:3], v[2:3], 0, v[4:5]
	v_cvt_pk_bf16_f32 v9, v10, v11
	global_store_dwordx4 v[2:3], v[6:9], off
	s_waitcnt vmcnt(0) lgkmcnt(0)
	s_barrier

.LBB0_1258:
	s_mov_b32 s73, s61
	s_mov_b32 s43, s60
	v_add_u32_e32 v0, s43, v247
	ds_read_b64_tr_b16 v[220:221], v0 offset:49152
	ds_read_b64_tr_b16 v[222:223], v0 offset:49664
	s_waitcnt lgkmcnt(13)
	v_mfma_f32_32x32x16_bf16 v[128:143], v[112:115], v[180:183], v[64:79]
	v_add_f32_e32 v250, v96, v97
	v_add_f32_e32 v251, v98, v99
	v_add_f32_e32 v252, v100, v101
	v_add_f32_e32 v253, v102, v103
	v_add_f32_e32 v250, v104, v250
	v_cvt_pk_bf16_f32 v184, v96, v97
	v_cvt_pk_bf16_f32 v185, v98, v99
	ds_read_b64_tr_b16 v[216:217], v0 offset:53248
	ds_read_b64_tr_b16 v[218:219], v0 offset:53760
	s_waitcnt lgkmcnt(14)
	v_mfma_f32_32x32x16_bf16 v[112:127], v[208:211], v[180:183], v[64:79]
	v_add_f32_e32 v251, v105, v251
	v_add_f32_e32 v252, v106, v252
	v_add_f32_e32 v253, v107, v253
	v_add_f32_e32 v250, v108, v250
	v_cvt_pk_bf16_f32 v186, v100, v101
	v_cvt_pk_bf16_f32 v187, v102, v103
	ds_read_b64_tr_b16 v[96:97], v0 offset:50176
	ds_read_b64_tr_b16 v[98:99], v0 offset:50688
	s_waitcnt lgkmcnt(14)
	v_mfma_f32_32x32x16_bf16 v[128:143], v[212:215], v[176:179], v[128:143]
	v_add_f32_e32 v251, v109, v251
	v_add_f32_e32 v252, v110, v252
	v_add_f32_e32 v253, v111, v253
	v_add_f32_e32 v250, v80, v250
	v_cvt_pk_bf16_f32 v10, v104, v105
	v_cvt_pk_bf16_f32 v11, v106, v107
	ds_read_b64_tr_b16 v[100:101], v0 offset:54272
	ds_read_b64_tr_b16 v[102:103], v0 offset:54784
	v_mfma_f32_32x32x16_bf16 v[112:127], v[204:207], v[176:179], v[112:127]
	v_add_f32_e32 v251, v81, v251
	v_add_f32_e32 v252, v82, v252
	v_add_f32_e32 v253, v83, v253
	v_add_f32_e32 v250, v84, v250
	v_cvt_pk_bf16_f32 v12, v108, v109
	v_cvt_pk_bf16_f32 v13, v110, v111
	ds_read_b64_tr_b16 v[104:105], v0 offset:51200
	ds_read_b64_tr_b16 v[106:107], v0 offset:51712
	s_waitcnt lgkmcnt(14)
	v_mfma_f32_32x32x16_bf16 v[128:143], v[200:203], v[172:175], v[128:143]
	v_add_f32_e32 v251, v85, v251
	v_add_f32_e32 v252, v86, v252
	v_add_f32_e32 v253, v87, v253
	v_add_f32_e32 v250, v88, v250
	v_cvt_pk_bf16_f32 v6, v80, v81
	v_cvt_pk_bf16_f32 v7, v82, v83
	ds_read_b64_tr_b16 v[80:81], v0 offset:55296
	ds_read_b64_tr_b16 v[82:83], v0 offset:55808
	v_mfma_f32_32x32x16_bf16 v[112:127], v[196:199], v[172:175], v[112:127]
	v_add_f32_e32 v251, v89, v251
	v_add_f32_e32 v252, v90, v252
	v_add_f32_e32 v253, v91, v253
	v_add_f32_e32 v250, v92, v250
	v_cvt_pk_bf16_f32 v8, v84, v85
	v_cvt_pk_bf16_f32 v9, v86, v87
	ds_read_b64_tr_b16 v[84:85], v0 offset:52224
	ds_read_b64_tr_b16 v[86:87], v0 offset:52736
	v_mfma_f32_32x32x16_bf16 v[128:143], v[192:195], v[168:171], v[128:143]
	v_add_f32_e32 v251, v93, v251
	v_add_f32_e32 v252, v94, v252
	v_add_f32_e32 v253, v95, v253
	v_add_f32_e32 v250, v251, v250
	v_cvt_pk_bf16_f32 v2, v88, v89
	v_cvt_pk_bf16_f32 v3, v90, v91
	ds_read_b64_tr_b16 v[88:89], v0 offset:56320
	ds_read_b64_tr_b16 v[90:91], v0 offset:56832
	v_mfma_f32_32x32x16_bf16 v[112:127], v[188:191], v[168:171], v[112:127]
	v_add_f32_e32 v252, v253, v252
	v_add_f32_e32 v0, v252, v250
	v_cvt_pk_bf16_f32 v4, v92, v93
	v_cvt_pk_bf16_f32 v5, v94, v95
	s_waitcnt lgkmcnt(14)
	v_mfma_f32_32x32x16_bf16 v[128:143], v[148:151], v[164:167], v[128:143]
	v_mfma_f32_32x32x16_bf16 v[112:127], v[144:147], v[164:167], v[112:127]
	v_mfma_f32_32x32x16_bf16 v[128:143], v[156:159], v[160:163], v[128:143]
	v_mfma_f32_32x32x16_bf16 v[112:127], v[152:155], v[160:163], v[112:127]
	s_lshr_b32 s60, s61, 1
	s_add_i32 s60, s60, s61
	s_add_i32 s61, s60, s47
	s_mov_b32 s62, m0
	s_mov_b32 m0, s61
	s_nop 0
	global_load_lds_dwordx4 v[230:231], off
	s_mov_b32 m0, s62
	s_and_b64 vcc, exec, s[6:7]
	s_cbranch_vccnz .LBB0_1260
	v_lshl_add_u64 v[14:15], s[30:31], 1, v[230:231]
	s_add_i32 s60, s60, s67
	v_lshl_add_u64 v[14:15], v[14:15], 0, s[10:11]
	s_mov_b32 s61, m0
	s_mov_b32 m0, s60
	s_nop 0
	global_load_lds_dwordx4 v[14:15], off
	s_mov_b32 m0, s61

.LBB0_1265:
	v_add_u32_e32 v14, s73, v247
	ds_read_b64_tr_b16 v[148:149], v14 offset:49152
	ds_read_b64_tr_b16 v[150:151], v14 offset:49664
	s_waitcnt lgkmcnt(13)
	v_mfma_f32_32x32x16_bf16 v[96:111], v[92:95], v[180:183], v[64:79]
	v_add_f32_e32 v250, v128, v129
	v_add_f32_e32 v251, v130, v131
	v_add_f32_e32 v252, v132, v133
	v_add_f32_e32 v253, v134, v135
	v_add_f32_e32 v250, v136, v250
	v_cvt_pk_bf16_f32 v184, v128, v129
	v_cvt_pk_bf16_f32 v185, v130, v131
	ds_read_b64_tr_b16 v[144:145], v14 offset:53248
	ds_read_b64_tr_b16 v[146:147], v14 offset:53760
	s_waitcnt lgkmcnt(14)
	v_mfma_f32_32x32x16_bf16 v[80:95], v[216:219], v[180:183], v[64:79]
	v_add_f32_e32 v251, v137, v251
	v_add_f32_e32 v252, v138, v252
	v_add_f32_e32 v253, v139, v253
	v_add_f32_e32 v250, v140, v250
	v_cvt_pk_bf16_f32 v186, v132, v133
	v_cvt_pk_bf16_f32 v187, v134, v135
	ds_read_b64_tr_b16 v[128:129], v14 offset:50176
	ds_read_b64_tr_b16 v[130:131], v14 offset:50688
	s_waitcnt lgkmcnt(14)
	v_mfma_f32_32x32x16_bf16 v[96:111], v[220:223], v[176:179], v[96:111]
	v_add_f32_e32 v251, v141, v251
	v_add_f32_e32 v252, v142, v252
	v_add_f32_e32 v253, v143, v253
	v_add_f32_e32 v250, v112, v250
	v_cvt_pk_bf16_f32 v10, v136, v137
	v_cvt_pk_bf16_f32 v11, v138, v139
	ds_read_b64_tr_b16 v[132:133], v14 offset:54272
	ds_read_b64_tr_b16 v[134:135], v14 offset:54784
	v_mfma_f32_32x32x16_bf16 v[80:95], v[212:215], v[176:179], v[80:95]
	v_add_f32_e32 v251, v113, v251
	v_add_f32_e32 v252, v114, v252
	v_add_f32_e32 v253, v115, v253
	v_add_f32_e32 v250, v116, v250
	v_cvt_pk_bf16_f32 v12, v140, v141
	v_cvt_pk_bf16_f32 v13, v142, v143
	ds_read_b64_tr_b16 v[136:137], v14 offset:51200
	ds_read_b64_tr_b16 v[138:139], v14 offset:51712
	s_waitcnt lgkmcnt(14)
	v_mfma_f32_32x32x16_bf16 v[96:111], v[208:211], v[172:175], v[96:111]
	v_add_f32_e32 v251, v117, v251
	v_add_f32_e32 v252, v118, v252
	v_add_f32_e32 v253, v119, v253
	v_add_f32_e32 v250, v120, v250
	v_cvt_pk_bf16_f32 v6, v112, v113
	v_cvt_pk_bf16_f32 v7, v114, v115
	ds_read_b64_tr_b16 v[140:141], v14 offset:55296
	ds_read_b64_tr_b16 v[142:143], v14 offset:55808
	v_mfma_f32_32x32x16_bf16 v[80:95], v[204:207], v[172:175], v[80:95]
	v_add_f32_e32 v251, v121, v251
	v_add_f32_e32 v252, v122, v252
	v_add_f32_e32 v253, v123, v253
	v_add_f32_e32 v250, v124, v250
	v_cvt_pk_bf16_f32 v8, v116, v117
	v_cvt_pk_bf16_f32 v9, v118, v119
	ds_read_b64_tr_b16 v[116:117], v14 offset:52224
	ds_read_b64_tr_b16 v[118:119], v14 offset:52736
	v_mfma_f32_32x32x16_bf16 v[96:111], v[200:203], v[168:171], v[96:111]
	v_add_f32_e32 v251, v125, v251
	v_add_f32_e32 v252, v126, v252
	v_add_f32_e32 v253, v127, v253
	v_add_f32_e32 v250, v251, v250
	v_cvt_pk_bf16_f32 v2, v120, v121
	v_cvt_pk_bf16_f32 v3, v122, v123
	ds_read_b64_tr_b16 v[120:121], v14 offset:56320
	ds_read_b64_tr_b16 v[122:123], v14 offset:56832
	v_mfma_f32_32x32x16_bf16 v[80:95], v[156:159], v[168:171], v[80:95]
	v_add_f32_e32 v252, v253, v252
	v_add_f32_e32 v112, v252, v250
	v_cvt_pk_bf16_f32 v4, v124, v125
	v_cvt_pk_bf16_f32 v5, v126, v127
	s_waitcnt lgkmcnt(14)
	v_mfma_f32_32x32x16_bf16 v[96:111], v[188:191], v[164:167], v[96:111]
	v_mfma_f32_32x32x16_bf16 v[80:95], v[152:155], v[164:167], v[80:95]
	v_mfma_f32_32x32x16_bf16 v[96:111], v[196:199], v[160:163], v[96:111]
	v_mfma_f32_32x32x16_bf16 v[80:95], v[192:195], v[160:163], v[80:95]
	v_lshl_add_u64 v[14:15], v[230:231], 0, s[12:13]
	s_add_i32 s60, s66, s47
	s_mov_b32 s61, m0
	s_mov_b32 m0, s60
	s_nop 0
	global_load_lds_dwordx4 v[14:15], off
	s_mov_b32 m0, s61
	s_and_b64 vcc, exec, s[6:7]
	s_cbranch_vccnz .LBB0_1267
	v_lshl_add_u64 v[14:15], s[30:31], 1, v[14:15]
	s_add_i32 s60, s66, s67
	v_lshl_add_u64 v[14:15], v[14:15], 0, s[10:11]
	s_mov_b32 s61, m0
	s_mov_b32 m0, s60
	s_nop 0
	global_load_lds_dwordx4 v[14:15], off
	s_mov_b32 m0, s61

.LBB0_1284:
	v_add_u32_e32 v248, 0xc000, v247
	ds_read_b64_tr_b16 v[220:221], v248 offset:16384
	ds_read_b64_tr_b16 v[222:223], v248 offset:16896
	s_waitcnt lgkmcnt(13)
	v_mfma_f32_32x32x16_bf16 v[128:143], v[112:115], v[180:183], v[64:79]
	v_add_f32_e32 v250, v96, v97
	v_add_f32_e32 v251, v98, v99
	v_add_f32_e32 v252, v100, v101
	v_add_f32_e32 v253, v102, v103
	v_add_f32_e32 v250, v104, v250
	v_cvt_pk_bf16_f32 v184, v96, v97
	v_cvt_pk_bf16_f32 v185, v98, v99
	ds_read_b64_tr_b16 v[216:217], v248 offset:20480
	ds_read_b64_tr_b16 v[218:219], v248 offset:20992
	s_waitcnt lgkmcnt(14)
	v_mfma_f32_32x32x16_bf16 v[112:127], v[208:211], v[180:183], v[64:79]
	v_add_f32_e32 v251, v105, v251
	v_add_f32_e32 v252, v106, v252
	v_add_f32_e32 v253, v107, v253
	v_add_f32_e32 v250, v108, v250
	v_cvt_pk_bf16_f32 v186, v100, v101
	v_cvt_pk_bf16_f32 v187, v102, v103
	ds_read_b64_tr_b16 v[96:97], v248 offset:17408
	ds_read_b64_tr_b16 v[98:99], v248 offset:17920
	s_waitcnt lgkmcnt(14)
	v_mfma_f32_32x32x16_bf16 v[128:143], v[212:215], v[176:179], v[128:143]
	v_add_f32_e32 v251, v109, v251
	v_add_f32_e32 v252, v110, v252
	v_add_f32_e32 v253, v111, v253
	v_add_f32_e32 v250, v80, v250
	v_cvt_pk_bf16_f32 v10, v104, v105
	v_cvt_pk_bf16_f32 v11, v106, v107
	ds_read_b64_tr_b16 v[100:101], v248 offset:21504
	ds_read_b64_tr_b16 v[102:103], v248 offset:22016
	v_mfma_f32_32x32x16_bf16 v[112:127], v[204:207], v[176:179], v[112:127]
	v_add_f32_e32 v251, v81, v251
	v_add_f32_e32 v252, v82, v252
	v_add_f32_e32 v253, v83, v253
	v_add_f32_e32 v250, v84, v250
	v_cvt_pk_bf16_f32 v12, v108, v109
	v_cvt_pk_bf16_f32 v13, v110, v111
	ds_read_b64_tr_b16 v[104:105], v248 offset:18432
	ds_read_b64_tr_b16 v[106:107], v248 offset:18944
	s_waitcnt lgkmcnt(14)
	v_mfma_f32_32x32x16_bf16 v[128:143], v[200:203], v[172:175], v[128:143]
	v_add_f32_e32 v251, v85, v251
	v_add_f32_e32 v252, v86, v252
	v_add_f32_e32 v253, v87, v253
	v_add_f32_e32 v250, v88, v250
	v_cvt_pk_bf16_f32 v6, v80, v81
	v_cvt_pk_bf16_f32 v7, v82, v83
	ds_read_b64_tr_b16 v[80:81], v248 offset:22528
	ds_read_b64_tr_b16 v[82:83], v248 offset:23040
	v_mfma_f32_32x32x16_bf16 v[112:127], v[196:199], v[172:175], v[112:127]
	v_add_f32_e32 v251, v89, v251
	v_add_f32_e32 v252, v90, v252
	v_add_f32_e32 v253, v91, v253
	v_add_f32_e32 v250, v92, v250
	v_cvt_pk_bf16_f32 v8, v84, v85
	v_cvt_pk_bf16_f32 v9, v86, v87
	ds_read_b64_tr_b16 v[84:85], v248 offset:19456
	ds_read_b64_tr_b16 v[86:87], v248 offset:19968
	v_mfma_f32_32x32x16_bf16 v[128:143], v[192:195], v[168:171], v[128:143]
	v_add_f32_e32 v251, v93, v251
	v_add_f32_e32 v252, v94, v252
	v_add_f32_e32 v253, v95, v253
	v_add_f32_e32 v250, v251, v250
	v_cvt_pk_bf16_f32 v2, v88, v89
	v_cvt_pk_bf16_f32 v3, v90, v91
	ds_read_b64_tr_b16 v[88:89], v248 offset:23552
	ds_read_b64_tr_b16 v[90:91], v248 offset:24064
	v_mfma_f32_32x32x16_bf16 v[112:127], v[188:191], v[168:171], v[112:127]
	v_add_f32_e32 v252, v253, v252
	v_add_f32_e32 v0, v252, v250
	v_cvt_pk_bf16_f32 v4, v92, v93
	v_cvt_pk_bf16_f32 v5, v94, v95
	s_waitcnt lgkmcnt(14)
	v_mfma_f32_32x32x16_bf16 v[128:143], v[148:151], v[164:167], v[128:143]
	v_mfma_f32_32x32x16_bf16 v[112:127], v[144:147], v[164:167], v[112:127]
	v_mfma_f32_32x32x16_bf16 v[128:143], v[156:159], v[160:163], v[128:143]
	v_mfma_f32_32x32x16_bf16 v[112:127], v[152:155], v[160:163], v[112:127]
	s_mov_b64 s[20:21], 0x648000
	v_lshl_add_u64 v[14:15], v[224:225], 0, s[20:21]
	s_and_b64 vcc, exec, s[6:7]
	s_mov_b32 s6, m0
	s_mov_b32 m0, s45
	s_nop 0
	global_load_lds_dwordx4 v[14:15], off
	s_mov_b32 m0, s6
	s_cbranch_vccnz .LBB0_1286
	s_cmp_lg_u32 0, -1
	s_cselect_b32 s6, 0, 0
	v_lshl_add_u64 v[14:15], s[30:31], 1, v[14:15]
	s_add_i32 s6, s6, s44
	v_lshl_add_u64 v[14:15], v[14:15], 0, s[10:11]
	s_add_i32 s6, s6, 0xb000
	s_mov_b32 s7, m0
	s_mov_b32 m0, s6
	s_nop 0
	global_load_lds_dwordx4 v[14:15], off
	s_mov_b32 m0, s7

.LBB0_1291:
	ds_read_b64_tr_b16 v[188:189], v248 offset:24576
	ds_read_b64_tr_b16 v[190:191], v248 offset:25088
	s_waitcnt lgkmcnt(13)
	v_mfma_f32_32x32x16_bf16 v[144:159], v[92:95], v[180:183], v[64:79]
	v_add_f32_e32 v250, v128, v129
	v_add_f32_e32 v251, v130, v131
	v_add_f32_e32 v252, v132, v133
	v_add_f32_e32 v253, v134, v135
	v_add_f32_e32 v250, v136, v250
	v_cvt_pk_bf16_f32 v184, v128, v129
	v_cvt_pk_bf16_f32 v185, v130, v131
	ds_read_b64_tr_b16 v[104:105], v248 offset:28672
	ds_read_b64_tr_b16 v[106:107], v248 offset:29184
	s_waitcnt lgkmcnt(14)
	v_mfma_f32_32x32x16_bf16 v[80:95], v[224:227], v[180:183], v[64:79]
	v_add_f32_e32 v251, v137, v251
	v_add_f32_e32 v252, v138, v252
	v_add_f32_e32 v253, v139, v253
	v_add_f32_e32 v250, v140, v250
	v_cvt_pk_bf16_f32 v186, v132, v133
	v_cvt_pk_bf16_f32 v187, v134, v135
	ds_read_b64_tr_b16 v[96:97], v248 offset:25600
	ds_read_b64_tr_b16 v[98:99], v248 offset:26112
	s_waitcnt lgkmcnt(14)
	v_mfma_f32_32x32x16_bf16 v[144:159], v[228:231], v[176:179], v[144:159]
	v_add_f32_e32 v251, v141, v251
	v_add_f32_e32 v252, v142, v252
	v_add_f32_e32 v253, v143, v253
	v_add_f32_e32 v250, v112, v250
	v_cvt_pk_bf16_f32 v10, v136, v137
	v_cvt_pk_bf16_f32 v11, v138, v139
	ds_read_b64_tr_b16 v[100:101], v248 offset:29696
	ds_read_b64_tr_b16 v[102:103], v248 offset:30208
	v_mfma_f32_32x32x16_bf16 v[80:95], v[108:111], v[176:179], v[80:95]
	v_add_f32_e32 v251, v113, v251
	v_add_f32_e32 v252, v114, v252
	v_add_f32_e32 v253, v115, v253
	v_add_f32_e32 v250, v116, v250
	v_cvt_pk_bf16_f32 v12, v140, v141
	v_cvt_pk_bf16_f32 v13, v142, v143
	ds_read_b64_tr_b16 v[108:109], v248 offset:26624
	ds_read_b64_tr_b16 v[110:111], v248 offset:27136
	s_waitcnt lgkmcnt(14)
	v_mfma_f32_32x32x16_bf16 v[144:159], v[220:223], v[172:175], v[144:159]
	v_add_f32_e32 v251, v117, v251
	v_add_f32_e32 v252, v118, v252
	v_add_f32_e32 v253, v119, v253
	v_add_f32_e32 v250, v120, v250
	v_cvt_pk_bf16_f32 v6, v112, v113
	v_cvt_pk_bf16_f32 v7, v114, v115
	ds_read_b64_tr_b16 v[112:113], v248 offset:30720
	ds_read_b64_tr_b16 v[114:115], v248 offset:31232
	v_mfma_f32_32x32x16_bf16 v[80:95], v[216:219], v[172:175], v[80:95]
	v_add_f32_e32 v251, v121, v251
	v_add_f32_e32 v252, v122, v252
	v_add_f32_e32 v253, v123, v253
	v_add_f32_e32 v250, v124, v250
	v_cvt_pk_bf16_f32 v8, v116, v117
	v_cvt_pk_bf16_f32 v9, v118, v119
	ds_read_b64_tr_b16 v[116:117], v248 offset:27648
	ds_read_b64_tr_b16 v[118:119], v248 offset:28160
	v_mfma_f32_32x32x16_bf16 v[144:159], v[212:215], v[168:171], v[144:159]
	v_add_f32_e32 v251, v125, v251
	v_add_f32_e32 v252, v126, v252
	v_add_f32_e32 v253, v127, v253
	v_add_f32_e32 v250, v251, v250
	v_cvt_pk_bf16_f32 v2, v120, v121
	v_cvt_pk_bf16_f32 v3, v122, v123
	ds_read_b64_tr_b16 v[120:121], v248 offset:31744
	ds_read_b64_tr_b16 v[122:123], v248 offset:32256
	v_mfma_f32_32x32x16_bf16 v[80:95], v[196:199], v[168:171], v[80:95]
	v_add_f32_e32 v252, v253, v252
	v_add_f32_e32 v14, v252, v250
	v_cvt_pk_bf16_f32 v4, v124, v125
	v_cvt_pk_bf16_f32 v5, v126, v127
	s_waitcnt lgkmcnt(14)
	v_mfma_f32_32x32x16_bf16 v[144:159], v[200:203], v[164:167], v[144:159]
	v_mfma_f32_32x32x16_bf16 v[80:95], v[192:195], v[164:167], v[80:95]
	v_mfma_f32_32x32x16_bf16 v[144:159], v[208:211], v[160:163], v[144:159]
	v_mfma_f32_32x32x16_bf16 v[80:95], v[204:207], v[160:163], v[80:95]
	s_mov_b64 s[6:7], 0x420000
	s_cmp_lg_u32 0, -1
	v_add_f32_e32 v0, v0, v14
	v_lshl_add_u64 v[14:15], v[232:233], 0, s[6:7]
	s_cselect_b32 s6, 0, 0
	s_add_i32 s6, s6, s97
	s_add_i32 s6, s6, 0x10000
	s_mov_b32 s7, m0
	s_mov_b32 m0, s6
	s_nop 0
	global_load_lds_dwordx4 v[14:15], off
	s_mov_b32 m0, s7
	s_nop 3
	v_max_f32_e32 v14, v144, v144
	v_max_f32_e32 v14, 0xff800000, v14
	v_max3_f32 v15, v146, s69, v147
	v_max3_f32 v14, v14, v145, v80
	v_max3_f32 v15, v15, v82, v83
	v_max3_f32 v14, v14, v81, v148
	v_max3_f32 v15, v15, v150, v151
	v_max3_f32 v14, v14, v149, v84
	v_max3_f32 v15, v15, v86, v87
	v_max3_f32 v14, v14, v85, v152
	v_max3_f32 v15, v15, v154, v155
	v_max3_f32 v14, v14, v153, v88
	v_max3_f32 v15, v15, v90, v91
	v_max3_f32 v14, v14, v89, v156
	v_max3_f32 v15, v15, v158, v159
	v_max3_f32 v14, v14, v157, v92
	v_max3_f32 v15, v15, v94, v95
	v_max3_f32 v14, v14, v93, v15
	v_mov_b32_e32 v15, v14
	s_nop 1
	v_permlane32_swap_b32_e32 v14, v15
	v_max3_f32 v14, v14, s69, v15
	v_cmp_lt_f32_e32 vcc, s72, v14
	s_cmp_lg_u64 vcc, 0
	s_cselect_b64 s[6:7], -1, 0
	s_cbranch_vccnz .LBB0_1359

.LBB0_1296:
	ds_read_b64_tr_b16 v[188:189], v247 offset:49152
	ds_read_b64_tr_b16 v[190:191], v247 offset:49664
	s_waitcnt lgkmcnt(13)
	v_mfma_f32_32x32x16_bf16 v[128:143], v[104:107], v[180:183], v[64:79]
	v_add_f32_e32 v250, v144, v145
	v_add_f32_e32 v251, v146, v147
	v_add_f32_e32 v252, v148, v149
	v_add_f32_e32 v253, v150, v151
	v_add_f32_e32 v250, v152, v250
	v_cvt_pk_bf16_f32 v184, v144, v145
	v_cvt_pk_bf16_f32 v185, v146, v147
	ds_read_b64_tr_b16 v[120:121], v247 offset:53248
	ds_read_b64_tr_b16 v[122:123], v247 offset:53760
	s_waitcnt lgkmcnt(14)
	v_mfma_f32_32x32x16_bf16 v[96:111], v[224:227], v[180:183], v[64:79]
	v_add_f32_e32 v251, v153, v251
	v_add_f32_e32 v252, v154, v252
	v_add_f32_e32 v253, v155, v253
	v_add_f32_e32 v250, v156, v250
	v_cvt_pk_bf16_f32 v186, v148, v149
	v_cvt_pk_bf16_f32 v187, v150, v151
	ds_read_b64_tr_b16 v[112:113], v247 offset:50176
	ds_read_b64_tr_b16 v[114:115], v247 offset:50688
	s_waitcnt lgkmcnt(14)
	v_mfma_f32_32x32x16_bf16 v[128:143], v[228:231], v[176:179], v[128:143]
	v_add_f32_e32 v251, v157, v251
	v_add_f32_e32 v252, v158, v252
	v_add_f32_e32 v253, v159, v253
	v_add_f32_e32 v250, v80, v250
	v_cvt_pk_bf16_f32 v10, v152, v153
	v_cvt_pk_bf16_f32 v11, v154, v155
	ds_read_b64_tr_b16 v[116:117], v247 offset:54272
	ds_read_b64_tr_b16 v[118:119], v247 offset:54784
	v_mfma_f32_32x32x16_bf16 v[96:111], v[124:127], v[176:179], v[96:111]
	v_add_f32_e32 v251, v81, v251
	v_add_f32_e32 v252, v82, v252
	v_add_f32_e32 v253, v83, v253
	v_add_f32_e32 v250, v84, v250
	v_cvt_pk_bf16_f32 v12, v156, v157
	v_cvt_pk_bf16_f32 v13, v158, v159
	ds_read_b64_tr_b16 v[124:125], v247 offset:51200
	ds_read_b64_tr_b16 v[126:127], v247 offset:51712
	s_waitcnt lgkmcnt(14)
	v_mfma_f32_32x32x16_bf16 v[128:143], v[220:223], v[172:175], v[128:143]
	v_add_f32_e32 v251, v85, v251
	v_add_f32_e32 v252, v86, v252
	v_add_f32_e32 v253, v87, v253
	v_add_f32_e32 v250, v88, v250
	v_cvt_pk_bf16_f32 v6, v80, v81
	v_cvt_pk_bf16_f32 v7, v82, v83
	ds_read_b64_tr_b16 v[80:81], v247 offset:55296
	ds_read_b64_tr_b16 v[82:83], v247 offset:55808
	v_mfma_f32_32x32x16_bf16 v[96:111], v[216:219], v[172:175], v[96:111]
	v_add_f32_e32 v251, v89, v251
	v_add_f32_e32 v252, v90, v252
	v_add_f32_e32 v253, v91, v253
	v_add_f32_e32 v250, v92, v250
	v_cvt_pk_bf16_f32 v8, v84, v85
	v_cvt_pk_bf16_f32 v9, v86, v87
	ds_read_b64_tr_b16 v[84:85], v247 offset:52224
	ds_read_b64_tr_b16 v[86:87], v247 offset:52736
	v_mfma_f32_32x32x16_bf16 v[128:143], v[212:215], v[168:171], v[128:143]
	v_add_f32_e32 v251, v93, v251
	v_add_f32_e32 v252, v94, v252
	v_add_f32_e32 v253, v95, v253
	v_add_f32_e32 v250, v251, v250
	v_cvt_pk_bf16_f32 v2, v88, v89
	v_cvt_pk_bf16_f32 v3, v90, v91
	ds_read_b64_tr_b16 v[88:89], v247 offset:56320
	ds_read_b64_tr_b16 v[90:91], v247 offset:56832
	v_mfma_f32_32x32x16_bf16 v[96:111], v[196:199], v[168:171], v[96:111]
	v_add_f32_e32 v252, v253, v252
	v_add_f32_e32 v14, v252, v250
	v_cvt_pk_bf16_f32 v4, v92, v93
	v_cvt_pk_bf16_f32 v5, v94, v95
	s_waitcnt lgkmcnt(14)
	v_mfma_f32_32x32x16_bf16 v[128:143], v[200:203], v[164:167], v[128:143]
	v_mfma_f32_32x32x16_bf16 v[96:111], v[192:195], v[164:167], v[96:111]
	v_mfma_f32_32x32x16_bf16 v[128:143], v[208:211], v[160:163], v[128:143]
	v_mfma_f32_32x32x16_bf16 v[96:111], v[204:207], v[160:163], v[96:111]
	s_mov_b64 s[6:7], 0x430000
	s_cmp_lg_u32 0, -1
	v_add_f32_e32 v0, v0, v14
	v_lshl_add_u64 v[14:15], v[232:233], 0, s[6:7]
	s_cselect_b32 s6, 0, 0
	s_add_i32 s6, s6, s97
	s_add_i32 s6, s6, 0x12000
	s_mov_b32 s7, m0
	s_mov_b32 m0, s6
	s_nop 0
	global_load_lds_dwordx4 v[14:15], off
	s_mov_b32 m0, s7
	s_nop 3
	v_max_f32_e32 v14, v128, v128
	v_max_f32_e32 v14, 0xff800000, v14
	v_max3_f32 v15, v130, s69, v131
	v_max3_f32 v14, v14, v129, v96
	v_max3_f32 v15, v15, v98, v99
	v_max3_f32 v14, v14, v97, v132
	v_max3_f32 v15, v15, v134, v135
	v_max3_f32 v14, v14, v133, v100
	v_max3_f32 v15, v15, v102, v103
	v_max3_f32 v14, v14, v101, v136
	v_max3_f32 v15, v15, v138, v139
	v_max3_f32 v14, v14, v137, v104
	v_max3_f32 v15, v15, v106, v107
	v_max3_f32 v14, v14, v105, v140
	v_max3_f32 v15, v15, v142, v143
	v_max3_f32 v14, v14, v141, v108
	v_max3_f32 v15, v15, v110, v111
	v_max3_f32 v14, v14, v109, v15
	v_mov_b32_e32 v15, v14
	s_nop 1
	v_permlane32_swap_b32_e32 v14, v15
	v_max3_f32 v14, v14, s69, v15
	v_cmp_lt_f32_e32 vcc, s72, v14
	s_cmp_lg_u64 vcc, 0
	s_cselect_b64 s[6:7], -1, 0
	s_cbranch_vccnz .LBB0_1362

.LBB0_1301:
	ds_read_b64_tr_b16 v[188:189], v247 offset:57344
	ds_read_b64_tr_b16 v[190:191], v247 offset:57856
	s_waitcnt lgkmcnt(13)
	v_mfma_f32_32x32x16_bf16 v[112:127], v[92:95], v[180:183], v[64:79]
	v_add_f32_e32 v250, v128, v129
	v_add_f32_e32 v251, v130, v131
	v_add_f32_e32 v252, v132, v133
	v_add_f32_e32 v253, v134, v135
	v_add_f32_e32 v250, v136, v250
	v_cvt_pk_bf16_f32 v184, v128, v129
	v_cvt_pk_bf16_f32 v185, v130, v131
	ds_read_b64_tr_b16 v[156:157], v247 offset:61440
	ds_read_b64_tr_b16 v[158:159], v247 offset:61952
	s_waitcnt lgkmcnt(14)
	v_mfma_f32_32x32x16_bf16 v[80:95], v[216:219], v[180:183], v[64:79]
	v_add_f32_e32 v251, v137, v251
	v_add_f32_e32 v252, v138, v252
	v_add_f32_e32 v253, v139, v253
	v_add_f32_e32 v250, v140, v250
	v_cvt_pk_bf16_f32 v186, v132, v133
	v_cvt_pk_bf16_f32 v187, v134, v135
	ds_read_b64_tr_b16 v[128:129], v247 offset:58368
	ds_read_b64_tr_b16 v[130:131], v247 offset:58880
	s_waitcnt lgkmcnt(14)
	v_mfma_f32_32x32x16_bf16 v[112:127], v[220:223], v[176:179], v[112:127]
	v_add_f32_e32 v251, v141, v251
	v_add_f32_e32 v252, v142, v252
	v_add_f32_e32 v253, v143, v253
	v_add_f32_e32 v250, v96, v250
	v_cvt_pk_bf16_f32 v10, v136, v137
	v_cvt_pk_bf16_f32 v11, v138, v139
	ds_read_b64_tr_b16 v[132:133], v247 offset:62464
	ds_read_b64_tr_b16 v[134:135], v247 offset:62976
	v_mfma_f32_32x32x16_bf16 v[80:95], v[212:215], v[176:179], v[80:95]
	v_add_f32_e32 v251, v97, v251
	v_add_f32_e32 v252, v98, v252
	v_add_f32_e32 v253, v99, v253
	v_add_f32_e32 v250, v100, v250
	v_cvt_pk_bf16_f32 v12, v140, v141
	v_cvt_pk_bf16_f32 v13, v142, v143
	ds_read_b64_tr_b16 v[136:137], v247 offset:59392
	ds_read_b64_tr_b16 v[138:139], v247 offset:59904
	s_waitcnt lgkmcnt(14)
	v_mfma_f32_32x32x16_bf16 v[112:127], v[208:211], v[172:175], v[112:127]
	v_add_f32_e32 v251, v101, v251
	v_add_f32_e32 v252, v102, v252
	v_add_f32_e32 v253, v103, v253
	v_add_f32_e32 v250, v104, v250
	v_cvt_pk_bf16_f32 v6, v96, v97
	v_cvt_pk_bf16_f32 v7, v98, v99
	ds_read_b64_tr_b16 v[96:97], v247 offset:63488
	ds_read_b64_tr_b16 v[98:99], v247 offset:64000
	v_mfma_f32_32x32x16_bf16 v[80:95], v[196:199], v[172:175], v[80:95]
	v_add_f32_e32 v251, v105, v251
	v_add_f32_e32 v252, v106, v252
	v_add_f32_e32 v253, v107, v253
	v_add_f32_e32 v250, v108, v250
	v_cvt_pk_bf16_f32 v8, v100, v101
	v_cvt_pk_bf16_f32 v9, v102, v103
	ds_read_b64_tr_b16 v[100:101], v247 offset:60416
	ds_read_b64_tr_b16 v[102:103], v247 offset:60928
	v_mfma_f32_32x32x16_bf16 v[112:127], v[192:195], v[168:171], v[112:127]
	v_add_f32_e32 v251, v109, v251
	v_add_f32_e32 v252, v110, v252
	v_add_f32_e32 v253, v111, v253
	v_add_f32_e32 v250, v251, v250
	v_cvt_pk_bf16_f32 v2, v104, v105
	v_cvt_pk_bf16_f32 v3, v106, v107
	ds_read_b64_tr_b16 v[104:105], v247 offset:64512
	ds_read_b64_tr_b16 v[106:107], v247 offset:65024
	v_mfma_f32_32x32x16_bf16 v[80:95], v[144:147], v[168:171], v[80:95]
	v_add_f32_e32 v252, v253, v252
	v_add_f32_e32 v14, v252, v250
	v_cvt_pk_bf16_f32 v4, v108, v109
	v_cvt_pk_bf16_f32 v5, v110, v111
	s_waitcnt lgkmcnt(14)
	v_mfma_f32_32x32x16_bf16 v[112:127], v[152:155], v[164:167], v[112:127]
	v_mfma_f32_32x32x16_bf16 v[80:95], v[148:151], v[164:167], v[80:95]
	v_mfma_f32_32x32x16_bf16 v[112:127], v[204:207], v[160:163], v[112:127]
	v_mfma_f32_32x32x16_bf16 v[80:95], v[200:203], v[160:163], v[80:95]
	v_add_f32_e32 v225, v0, v14
	s_nop 9
	v_max_f32_e32 v0, v112, v112
	v_max_f32_e32 v0, 0xff800000, v0
	v_max3_f32 v14, v114, s69, v115
	v_max3_f32 v0, v0, v113, v80
	v_max3_f32 v14, v14, v82, v83
	v_max3_f32 v0, v0, v81, v116
	v_max3_f32 v14, v14, v118, v119
	v_max3_f32 v0, v0, v117, v84
	v_max3_f32 v14, v14, v86, v87
	v_max3_f32 v0, v0, v85, v120
	v_max3_f32 v14, v14, v122, v123
	v_max3_f32 v0, v0, v121, v88
	v_max3_f32 v14, v14, v90, v91
	v_max3_f32 v0, v0, v89, v124
	v_max3_f32 v14, v14, v126, v127
	v_max3_f32 v0, v0, v125, v92
	v_max3_f32 v14, v14, v94, v95
	v_max3_f32 v0, v0, v93, v14
	v_mov_b32_e32 v14, v0
	s_nop 1
	v_permlane32_swap_b32_e32 v0, v14
	v_max3_f32 v0, v0, s69, v14
	v_cmp_lt_f32_e32 vcc, s72, v0
	s_cmp_lg_u64 vcc, 0
	s_cselect_b64 s[6:7], -1, 0
	s_cbranch_vccnz .LBB0_1365

.LBB0_1304:
	v_lshrrev_b32_e32 v224, 3, v246
	v_or_b32_e32 v2, s94, v224
	v_mov_b32_e32 v3, s96
	v_lshlrev_b64 v[14:15], 11, v[2:3]
	v_lshl_add_u64 v[2:3], s[48:49], 0, v[14:15]
	s_lshl_b32 s8, s8, 1
	v_and_b32_e32 v0, 56, v243
	v_lshl_add_u64 v[2:3], v[2:3], 0, s[8:9]
	v_lshlrev_b32_e32 v0, 1, v0
	v_lshl_add_u64 v[2:3], v[2:3], 0, v[0:1]
	v_add_co_u32_e32 v6, vcc, s67, v2
	s_nop 1
	v_addc_co_u32_e32 v7, vcc, 0, v3, vcc
	global_load_dwordx4 v[140:143], v[2:3], off offset:1024
	global_load_dwordx4 v[136:139], v[6:7], off offset:1024
	v_add_co_u32_e32 v6, vcc, s66, v2
	s_nop 1
	v_addc_co_u32_e32 v7, vcc, 0, v3, vcc
	v_add_co_u32_e32 v2, vcc, s63, v2
	s_nop 1
	v_addc_co_u32_e32 v3, vcc, 0, v3, vcc
	global_load_dwordx4 v[132:135], v[6:7], off offset:1024
	global_load_dwordx4 v[128:131], v[2:3], off offset:1024
	ds_read_b64_tr_b16 v[156:157], v248 offset:16384
	ds_read_b64_tr_b16 v[158:159], v248 offset:16896
	s_waitcnt lgkmcnt(13)
	v_mfma_f32_32x32x16_bf16 v[96:111], v[220:223], v[180:183], v[64:79]
	v_add_f32_e32 v250, v112, v113
	v_add_f32_e32 v251, v114, v115
	v_add_f32_e32 v252, v116, v117
	v_add_f32_e32 v253, v118, v119
	v_add_f32_e32 v250, v120, v250
	v_cvt_pk_bf16_f32 v184, v112, v113
	v_cvt_pk_bf16_f32 v185, v114, v115
	ds_read_b64_tr_b16 v[112:113], v248 offset:20480
	ds_read_b64_tr_b16 v[114:115], v248 offset:20992
	s_waitcnt lgkmcnt(14)
	v_mfma_f32_32x32x16_bf16 v[64:79], v[216:219], v[180:183], v[64:79]
	v_add_f32_e32 v251, v121, v251
	v_add_f32_e32 v252, v122, v252
	v_add_f32_e32 v253, v123, v253
	v_add_f32_e32 v250, v124, v250
	v_cvt_pk_bf16_f32 v186, v116, v117
	v_cvt_pk_bf16_f32 v187, v118, v119
	ds_read_b64_tr_b16 v[116:117], v248 offset:17408
	ds_read_b64_tr_b16 v[118:119], v248 offset:17920
	s_waitcnt lgkmcnt(14)
	v_mfma_f32_32x32x16_bf16 v[96:111], v[212:215], v[176:179], v[96:111]
	v_add_f32_e32 v251, v125, v251
	v_add_f32_e32 v252, v126, v252
	v_add_f32_e32 v253, v127, v253
	v_add_f32_e32 v250, v80, v250
	v_cvt_pk_bf16_f32 v10, v120, v121
	v_cvt_pk_bf16_f32 v11, v122, v123
	ds_read_b64_tr_b16 v[120:121], v248 offset:21504
	ds_read_b64_tr_b16 v[122:123], v248 offset:22016
	v_mfma_f32_32x32x16_bf16 v[64:79], v[208:211], v[176:179], v[64:79]
	v_add_f32_e32 v251, v81, v251
	v_add_f32_e32 v252, v82, v252
	v_add_f32_e32 v253, v83, v253
	v_add_f32_e32 v250, v84, v250
	v_cvt_pk_bf16_f32 v12, v124, v125
	v_cvt_pk_bf16_f32 v13, v126, v127
	ds_read_b64_tr_b16 v[124:125], v248 offset:18432
	ds_read_b64_tr_b16 v[126:127], v248 offset:18944
	s_waitcnt lgkmcnt(14)
	v_mfma_f32_32x32x16_bf16 v[96:111], v[204:207], v[172:175], v[96:111]
	v_add_f32_e32 v251, v85, v251
	v_add_f32_e32 v252, v86, v252
	v_add_f32_e32 v253, v87, v253
	v_add_f32_e32 v250, v88, v250
	v_cvt_pk_bf16_f32 v6, v80, v81
	v_cvt_pk_bf16_f32 v7, v82, v83
	ds_read_b64_tr_b16 v[176:177], v248 offset:22528
	ds_read_b64_tr_b16 v[178:179], v248 offset:23040
	v_mfma_f32_32x32x16_bf16 v[64:79], v[192:195], v[172:175], v[64:79]
	v_add_f32_e32 v251, v89, v251
	v_add_f32_e32 v252, v90, v252
	v_add_f32_e32 v253, v91, v253
	v_add_f32_e32 v250, v92, v250
	v_cvt_pk_bf16_f32 v8, v84, v85
	v_cvt_pk_bf16_f32 v9, v86, v87
	ds_read_b64_tr_b16 v[172:173], v248 offset:19456
	ds_read_b64_tr_b16 v[174:175], v248 offset:19968
	v_mfma_f32_32x32x16_bf16 v[96:111], v[188:191], v[168:171], v[96:111]
	v_add_f32_e32 v251, v93, v251
	v_add_f32_e32 v252, v94, v252
	v_add_f32_e32 v253, v95, v253
	v_add_f32_e32 v250, v251, v250
	v_cvt_pk_bf16_f32 v2, v88, v89
	v_cvt_pk_bf16_f32 v3, v90, v91
	ds_read_b64_tr_b16 v[180:181], v248 offset:23552
	ds_read_b64_tr_b16 v[182:183], v248 offset:24064
	v_mfma_f32_32x32x16_bf16 v[64:79], v[144:147], v[168:171], v[64:79]
	v_add_f32_e32 v252, v253, v252
	v_add_f32_e32 v80, v252, v250
	v_cvt_pk_bf16_f32 v4, v92, v93
	v_cvt_pk_bf16_f32 v5, v94, v95
	s_waitcnt lgkmcnt(14)
	v_mfma_f32_32x32x16_bf16 v[96:111], v[152:155], v[164:167], v[96:111]
	v_mfma_f32_32x32x16_bf16 v[64:79], v[148:151], v[164:167], v[64:79]
	v_mfma_f32_32x32x16_bf16 v[96:111], v[200:203], v[160:163], v[96:111]
	v_mfma_f32_32x32x16_bf16 v[64:79], v[196:199], v[160:163], v[64:79]
	s_nop 10
	v_max_f32_e32 v81, v96, v96
	v_max_f32_e32 v81, 0xff800000, v81
	v_max3_f32 v82, v98, s69, v99
	v_max3_f32 v81, v81, v97, v64
	v_max3_f32 v82, v82, v66, v67
	v_max3_f32 v81, v81, v65, v100
	v_max3_f32 v82, v82, v102, v103
	v_max3_f32 v81, v81, v101, v68
	v_max3_f32 v82, v82, v70, v71
	v_max3_f32 v81, v81, v69, v104
	v_max3_f32 v82, v82, v106, v107
	v_max3_f32 v81, v81, v105, v72
	v_max3_f32 v82, v82, v74, v75
	v_max3_f32 v81, v81, v73, v108
	v_max3_f32 v82, v82, v110, v111
	v_max3_f32 v81, v81, v109, v76
	v_max3_f32 v82, v82, v78, v79
	v_add_f32_e32 v144, v225, v80
	v_max3_f32 v80, v81, v77, v82
	v_mov_b32_e32 v81, v80
	s_nop 1
	v_permlane32_swap_b32_e32 v80, v81
	v_max3_f32 v80, v80, s69, v81
	v_cmp_lt_f32_e32 vcc, s72, v80
	s_cmp_lg_u64 vcc, 0
	s_cselect_b64 s[6:7], -1, 0
	s_cbranch_vccnz .LBB0_1368

.LBB0_1307:
	v_add_f32_e32 v250, v96, v97
	v_add_f32_e32 v251, v98, v99
	v_add_f32_e32 v252, v100, v101
	v_add_f32_e32 v253, v102, v103
	v_add_f32_e32 v250, v104, v250
	v_add_f32_e32 v251, v105, v251
	v_add_f32_e32 v252, v106, v252
	v_add_f32_e32 v253, v107, v253
	v_add_f32_e32 v250, v108, v250
	v_add_f32_e32 v251, v109, v251
	v_add_f32_e32 v252, v110, v252
	v_add_f32_e32 v253, v111, v253
	v_add_f32_e32 v250, v64, v250
	v_add_f32_e32 v251, v65, v251
	v_add_f32_e32 v252, v66, v252
	v_add_f32_e32 v253, v67, v253
	v_add_f32_e32 v250, v68, v250
	v_add_f32_e32 v251, v69, v251
	v_add_f32_e32 v252, v70, v252
	v_add_f32_e32 v253, v71, v253
	v_add_f32_e32 v250, v72, v250
	v_add_f32_e32 v251, v73, v251
	v_add_f32_e32 v252, v74, v252
	v_add_f32_e32 v253, v75, v253
	v_add_f32_e32 v250, v76, v250
	v_add_f32_e32 v251, v77, v251
	v_add_f32_e32 v252, v78, v252
	v_add_f32_e32 v253, v79, v253
	v_add_f32_e32 v250, v251, v250
	v_add_f32_e32 v252, v253, v252
	v_add_f32_e32 v2, v252, v250
	v_add_f32_e32 v2, v144, v2
	v_cvt_pk_bf16_f32 v4, v96, v97
	v_cvt_pk_bf16_f32 v5, v98, v99
	v_cvt_pk_bf16_f32 v6, v100, v101
	v_cvt_pk_bf16_f32 v7, v102, v103
	v_cvt_pk_bf16_f32 v8, v104, v105
	v_cvt_pk_bf16_f32 v9, v106, v107
	v_cvt_pk_bf16_f32 v10, v108, v109
	v_cvt_pk_bf16_f32 v11, v110, v111
	v_cvt_pk_bf16_f32 v64, v64, v65
	v_cvt_pk_bf16_f32 v65, v66, v67
	v_cvt_pk_bf16_f32 v66, v68, v69
	v_cvt_pk_bf16_f32 v67, v70, v71
	v_cvt_pk_bf16_f32 v68, v72, v73
	v_cvt_pk_bf16_f32 v69, v74, v75
	v_cvt_pk_bf16_f32 v70, v76, v77
	v_cvt_pk_bf16_f32 v71, v78, v79
	s_cmp_lg_u32 0, -1
	s_cselect_b32 s6, 0, 0
	s_add_i32 s6, s6, 0x12000
	v_add_u32_e32 v3, s6, v240
	v_add3_u32 v3, v3, v235, v241
	ds_read_b64_tr_b16 v[72:73],v3 offset:0
	ds_read_b64_tr_b16 v[74:75],v3 offset:512
	ds_read_b64_tr_b16 v[76:77],v3 offset:1024
	ds_read_b64_tr_b16 v[78:79],v3 offset:1536
	ds_read_b64_tr_b16 v[80:81],v3 offset:2048
	ds_read_b64_tr_b16 v[82:83],v3 offset:2560
	ds_read_b64_tr_b16 v[84:85],v3 offset:3072
	ds_read_b64_tr_b16 v[86:87],v3 offset:3584
	s_waitcnt lgkmcnt(0)
	s_nop 0
	v_mfma_f32_32x32x16_bf16 v[48:63], v[4:7], v[72:75], v[48:63]
	ds_read_b64_tr_b16 v[72:73],v3 offset:4096
	ds_read_b64_tr_b16 v[74:75],v3 offset:4608
	v_mfma_f32_32x32x16_bf16 v[48:63], v[8:11], v[76:79], v[48:63]
	ds_read_b64_tr_b16 v[76:77],v3 offset:5120
	ds_read_b64_tr_b16 v[78:79],v3 offset:5632
	v_mfma_f32_32x32x16_bf16 v[48:63], v[64:67], v[80:83], v[48:63]
	ds_read_b64_tr_b16 v[80:81],v3 offset:6144
	ds_read_b64_tr_b16 v[82:83],v3 offset:6656
	ds_read_b64_tr_b16 v[88:89],v3 offset:7168
	ds_read_b64_tr_b16 v[90:91],v3 offset:7680
	s_waitcnt lgkmcnt(0)
	v_mfma_f32_32x32x16_bf16 v[48:63], v[68:71], v[84:87], v[48:63]
	v_mfma_f32_32x32x16_bf16 v[32:47], v[4:7], v[72:75], v[32:47]
	v_mov_b32_e32 v3, v2
	s_nop 1
	v_permlane32_swap_b32_e32 v2, v3
	v_mfma_f32_32x32x16_bf16 v[32:47], v[8:11], v[76:79], v[32:47]
	v_mfma_f32_32x32x16_bf16 v[32:47], v[64:67], v[80:83], v[32:47]
	v_mfma_f32_32x32x16_bf16 v[32:47], v[68:71], v[88:91], v[32:47]
	s_and_saveexec_b64 s[6:7], s[4:5]
	v_add_f32_e32 v2, v2, v3
	ds_write_b32 v239, v2 offset:128
	s_or_b64 exec, exec, s[6:7]
	s_waitcnt lgkmcnt(0)
	ds_read_b128 v[2:5], v234 offset:128
	ds_read_b128 v[6:9], v234 offset:160
	s_lshl_b32 s4, s95, 12
	s_add_i32 s4, s4, 0
	s_add_i32 s4, s4, 0x14800
	s_waitcnt lgkmcnt(1)
	v_rcp_f32_e32 v10, v2
	v_rcp_f32_e32 v11, v3
	v_lshlrev_b32_e32 v68, 9, v238
	v_lshlrev_b32_e32 v69, 1, v237
	v_mul_f32_e32 v48, v48, v10
	v_mul_f32_e32 v10, v32, v10
	v_add3_u32 v68, s4, v68, v69
	v_cvt_pk_bf16_f32 v10, v10, s0
	v_rcp_f32_e32 v12, v4
	ds_write_b16 v68, v10 offset:64
	v_mul_f32_e32 v10, v49, v11
	v_cvt_pk_bf16_f32 v10, v10, s0
	ds_write_b16 v68, v10 offset:128
	v_mul_f32_e32 v10, v33, v11
	v_cvt_pk_bf16_f32 v10, v10, s0
	v_rcp_f32_e32 v13, v5
	ds_write_b16 v68, v10 offset:192
	v_mul_f32_e32 v10, v50, v12
	v_cvt_pk_bf16_f32 v10, v10, s0
	ds_write_b16 v68, v10 offset:256
	v_mul_f32_e32 v10, v34, v12
	v_cvt_pk_bf16_f32 v10, v10, s0
	s_waitcnt lgkmcnt(4)
	v_rcp_f32_e32 v64, v6
	ds_write_b16 v68, v10 offset:320
	v_mul_f32_e32 v10, v51, v13
	v_cvt_pk_bf16_f32 v10, v10, s0
	ds_write_b16 v68, v10 offset:384
	v_mul_f32_e32 v10, v35, v13
	v_cvt_pk_bf16_f32 v10, v10, s0
	v_rcp_f32_e32 v65, v7
	ds_write_b16 v68, v10 offset:448
	v_mul_f32_e32 v10, v52, v64
	v_cvt_pk_bf16_f32 v10, v10, s0
	ds_write_b16 v68, v10 offset:1024
	v_mul_f32_e32 v10, v36, v64
	v_cvt_pk_bf16_f32 v10, v10, s0
	v_rcp_f32_e32 v66, v8
	ds_write_b16 v68, v10 offset:1088
	v_mul_f32_e32 v10, v53, v65
	v_cvt_pk_bf16_f32 v10, v10, s0
	ds_write_b16 v68, v10 offset:1152
	v_mul_f32_e32 v10, v37, v65
	ds_read_b128 v[2:5], v234 offset:192
	v_cvt_pk_bf16_f32 v10, v10, s0
	v_rcp_f32_e32 v67, v9
	ds_write_b16 v68, v10 offset:1216
	v_mul_f32_e32 v10, v54, v66
	v_cvt_pk_bf16_f32 v10, v10, s0
	ds_write_b16 v68, v10 offset:1280
	v_mul_f32_e32 v10, v38, v66
	v_cvt_pk_bf16_f32 v10, v10, s0
	ds_read_b128 v[6:9], v234 offset:224
	s_waitcnt lgkmcnt(3)
	v_rcp_f32_e32 v2, v2
	ds_write_b16 v68, v10 offset:1344
	v_mul_f32_e32 v10, v55, v67
	v_cvt_pk_bf16_f32 v10, v10, s0
	v_rcp_f32_e32 v3, v3
	ds_write_b16 v68, v10 offset:1408
	v_mul_f32_e32 v10, v39, v67
	v_cvt_pk_bf16_f32 v10, v10, s0
	ds_write_b16 v68, v10 offset:1472
	v_mul_f32_e32 v10, v56, v2
	v_mul_f32_e32 v2, v40, v2
	v_cvt_pk_bf16_f32 v2, v2, s0
	v_rcp_f32_e32 v4, v4
	ds_write_b16 v68, v2 offset:2112
	v_mul_f32_e32 v2, v57, v3
	v_cvt_pk_bf16_f32 v2, v2, s0
	ds_write_b16 v68, v2 offset:2176
	v_mul_f32_e32 v2, v41, v3
	v_cvt_pk_bf16_f32 v2, v2, s0
	v_rcp_f32_e32 v5, v5
	ds_write_b16 v68, v2 offset:2240
	v_mul_f32_e32 v2, v58, v4
	v_cvt_pk_bf16_f32 v2, v2, s0
	ds_write_b16 v68, v2 offset:2304
	v_mul_f32_e32 v2, v42, v4
	v_cvt_pk_bf16_f32 v2, v2, s0
	s_waitcnt lgkmcnt(7)
	v_rcp_f32_e32 v6, v6
	ds_write_b16 v68, v2 offset:2368
	v_mul_f32_e32 v2, v59, v5
	v_cvt_pk_bf16_f32 v2, v2, s0
	ds_write_b16 v68, v2 offset:2432
	v_mul_f32_e32 v2, v43, v5
	v_cvt_pk_bf16_f32 v2, v2, s0
	v_rcp_f32_e32 v7, v7
	ds_write_b16 v68, v2 offset:2496
	v_mul_f32_e32 v2, v60, v6
	v_cvt_pk_bf16_f32 v2, v2, s0
	ds_write_b16 v68, v2 offset:3072
	v_mul_f32_e32 v2, v44, v6
	v_cvt_pk_bf16_f32 v2, v2, s0
	v_rcp_f32_e32 v8, v8
	ds_write_b16 v68, v2 offset:3136
	v_mul_f32_e32 v2, v61, v7
	v_cvt_pk_bf16_f32 v2, v2, s0
	ds_write_b16 v68, v2 offset:3200
	v_mul_f32_e32 v2, v45, v7
	v_cvt_pk_bf16_f32 v2, v2, s0
	v_rcp_f32_e32 v9, v9
	ds_write_b16 v68, v2 offset:3264
	v_mul_f32_e32 v2, v62, v8
	v_cvt_pk_bf16_f32 v2, v2, s0
	ds_write_b16 v68, v2 offset:3328
	v_mul_f32_e32 v2, v46, v8
	v_cvt_pk_bf16_f32 v2, v2, s0
	ds_write_b16 v68, v2 offset:3392
	v_mul_f32_e32 v2, v63, v9
	s_waitcnt vmcnt(3)
	v_lshlrev_b32_e32 v12, 16, v140
	v_cvt_pk_bf16_f32 v2, v2, s0
	v_and_b32_e32 v13, 0xffff0000, v140
	v_mul_f32_e32 v4, 0xbfb8aa3b, v12
	ds_write_b16 v68, v2 offset:3456
	v_mul_f32_e32 v2, v47, v9
	v_exp_f32_e32 v8, v4
	v_mul_f32_e32 v4, 0xbfb8aa3b, v13
	v_cvt_pk_bf16_f32 v48, v48, s0
	v_cvt_pk_bf16_f32 v10, v10, s0
	v_cvt_pk_bf16_f32 v2, v2, s0
	v_exp_f32_e32 v9, v4
	ds_write_b16 v68, v48
	ds_write_b16 v68, v10 offset:2048
	ds_write_b16 v68, v2 offset:3520
	v_add_u32_e32 v36, s4, v0
	s_waitcnt lgkmcnt(0)
	v_lshl_add_u64 v[2:3], s[50:51], 0, v[0:1]
	v_lshl_add_u32 v0, v224, 7, v36
	ds_read_b128 v[4:7], v0
	v_add_f32_e32 v0, 1.0, v8
	v_rcp_f32_e32 v32, v0
	v_add_f32_e32 v0, 1.0, v9
	v_rcp_f32_e32 v33, v0
	s_waitcnt lgkmcnt(0)
	v_lshlrev_b32_e32 v34, 16, v4
	v_and_b32_e32 v35, 0xffff0000, v4
	s_bitset1_b32 s8, 10
	v_pk_mul_f32 v[12:13], v[32:33], v[12:13]
	v_lshlrev_b32_e32 v32, 16, v141
	v_and_b32_e32 v33, 0xffff0000, v141
	v_mul_f32_e32 v4, 0xbfb8aa3b, v32
	v_exp_f32_e32 v4, v4
	v_mul_f32_e32 v37, 0xbfb8aa3b, v33
	v_exp_f32_e32 v37, v37
	v_pk_mul_f32 v[12:13], v[12:13], v[34:35]
	v_add_f32_e32 v4, 1.0, v4
	v_rcp_f32_e32 v34, v4
	v_add_f32_e32 v4, 1.0, v37
	v_rcp_f32_e32 v35, v4
	v_cvt_pk_bf16_f32 v4, v12, v13
	v_lshlrev_b32_e32 v12, 16, v5
	v_and_b32_e32 v13, 0xffff0000, v5
	v_pk_mul_f32 v[32:33], v[34:35], v[32:33]
	v_lshlrev_b32_e32 v34, 16, v142
	v_and_b32_e32 v35, 0xffff0000, v142
	v_mul_f32_e32 v5, 0xbfb8aa3b, v34
	v_exp_f32_e32 v5, v5
	v_mul_f32_e32 v37, 0xbfb8aa3b, v35
	v_exp_f32_e32 v37, v37
	v_pk_mul_f32 v[12:13], v[32:33], v[12:13]
	v_add_f32_e32 v5, 1.0, v5
	v_rcp_f32_e32 v32, v5
	v_add_f32_e32 v5, 1.0, v37
	v_rcp_f32_e32 v33, v5
	v_cvt_pk_bf16_f32 v5, v12, v13
	v_lshlrev_b32_e32 v12, 16, v6
	v_and_b32_e32 v13, 0xffff0000, v6
	v_pk_mul_f32 v[32:33], v[32:33], v[34:35]
	v_lshlrev_b32_e32 v34, 16, v143
	v_and_b32_e32 v35, 0xffff0000, v143
	v_mul_f32_e32 v6, 0xbfb8aa3b, v34
	v_exp_f32_e32 v6, v6
	v_mul_f32_e32 v37, 0xbfb8aa3b, v35
	v_exp_f32_e32 v37, v37
	v_pk_mul_f32 v[12:13], v[32:33], v[12:13]
	v_add_f32_e32 v6, 1.0, v6
	v_rcp_f32_e32 v32, v6
	v_add_f32_e32 v6, 1.0, v37
	v_rcp_f32_e32 v33, v6
	v_cvt_pk_bf16_f32 v6, v12, v13
	v_lshlrev_b32_e32 v12, 16, v7
	v_and_b32_e32 v13, 0xffff0000, v7
	v_pk_mul_f32 v[32:33], v[32:33], v[34:35]
	v_or_b32_e32 v0, 8, v224
	v_pk_mul_f32 v[12:13], v[32:33], v[12:13]
	v_lshl_add_u32 v8, v0, 7, v36
	v_cvt_pk_bf16_f32 v7, v12, v13
	v_lshl_add_u64 v[12:13], v[2:3], 0, v[14:15]
	v_lshl_add_u64 v[12:13], v[12:13], 0, s[8:9]
	global_store_dwordx4 v[12:13], v[4:7], off
	ds_read_b128 v[8:11], v8
	s_mov_b64 s[4:5], 0
	s_waitcnt vmcnt(3)
	v_lshlrev_b32_e32 v6, 16, v136
	v_and_b32_e32 v7, 0xffff0000, v136
	v_mul_f32_e32 v4, 0xbfb8aa3b, v6
	v_exp_f32_e32 v5, v4
	v_mul_f32_e32 v4, 0xbfb8aa3b, v7
	v_exp_f32_e32 v13, v4
	v_or_b32_e32 v4, s94, v0
	v_add_f32_e32 v0, 1.0, v5
	v_rcp_f32_e32 v12, v0
	v_add_f32_e32 v0, 1.0, v13
	v_rcp_f32_e32 v13, v0
	s_waitcnt lgkmcnt(0)
	v_lshlrev_b32_e32 v14, 16, v8
	v_and_b32_e32 v15, 0xffff0000, v8
	v_mov_b32_e32 v5, s96
	v_pk_mul_f32 v[6:7], v[12:13], v[6:7]
	v_lshlrev_b32_e32 v12, 16, v137
	v_and_b32_e32 v13, 0xffff0000, v137
	v_mul_f32_e32 v0, 0xbfb8aa3b, v12
	v_exp_f32_e32 v0, v0
	v_mul_f32_e32 v8, 0xbfb8aa3b, v13
	v_exp_f32_e32 v8, v8
	v_pk_mul_f32 v[6:7], v[6:7], v[14:15]
	v_add_f32_e32 v0, 1.0, v0
	v_rcp_f32_e32 v14, v0
	v_add_f32_e32 v0, 1.0, v8
	v_rcp_f32_e32 v15, v0
	v_cvt_pk_bf16_f32 v6, v6, v7
	v_lshlrev_b32_e32 v8, 16, v9
	v_and_b32_e32 v9, 0xffff0000, v9
	v_pk_mul_f32 v[12:13], v[14:15], v[12:13]
	v_lshlrev_b32_e32 v14, 16, v138
	v_and_b32_e32 v15, 0xffff0000, v138
	v_mul_f32_e32 v0, 0xbfb8aa3b, v14
	v_exp_f32_e32 v0, v0
	v_mul_f32_e32 v7, 0xbfb8aa3b, v15
	v_exp_f32_e32 v7, v7
	v_pk_mul_f32 v[8:9], v[12:13], v[8:9]
	v_add_f32_e32 v0, 1.0, v0
	v_rcp_f32_e32 v12, v0
	v_add_f32_e32 v0, 1.0, v7
	v_rcp_f32_e32 v13, v0
	v_cvt_pk_bf16_f32 v7, v8, v9
	v_lshlrev_b32_e32 v8, 16, v10
	v_and_b32_e32 v9, 0xffff0000, v10
	v_pk_mul_f32 v[12:13], v[12:13], v[14:15]
	v_lshlrev_b32_e32 v14, 16, v139
	v_and_b32_e32 v15, 0xffff0000, v139
	v_mul_f32_e32 v0, 0xbfb8aa3b, v14
	v_exp_f32_e32 v0, v0
	v_mul_f32_e32 v10, 0xbfb8aa3b, v15
	v_exp_f32_e32 v10, v10
	v_pk_mul_f32 v[8:9], v[12:13], v[8:9]
	v_add_f32_e32 v0, 1.0, v0
	v_rcp_f32_e32 v12, v0
	v_add_f32_e32 v0, 1.0, v10
	v_rcp_f32_e32 v13, v0
	v_lshlrev_b32_e32 v10, 16, v11
	v_and_b32_e32 v11, 0xffff0000, v11
	v_cvt_pk_bf16_f32 v8, v8, v9
	v_pk_mul_f32 v[12:13], v[12:13], v[14:15]
	v_or_b32_e32 v0, 16, v224
	v_pk_mul_f32 v[10:11], v[12:13], v[10:11]
	s_waitcnt vmcnt(2)
	v_lshlrev_b32_e32 v14, 16, v132
	v_cvt_pk_bf16_f32 v9, v10, v11
	v_lshlrev_b64 v[10:11], 11, v[4:5]
	v_lshl_add_u64 v[10:11], v[2:3], 0, v[10:11]
	v_lshl_add_u64 v[10:11], v[10:11], 0, s[8:9]
	v_lshl_add_u32 v4, v0, 7, v36
	global_store_dwordx4 v[10:11], v[6:9], off
	ds_read_b128 v[6:9], v4
	v_and_b32_e32 v15, 0xffff0000, v132
	v_mul_f32_e32 v4, 0xbfb8aa3b, v14
	v_exp_f32_e32 v10, v4
	v_mul_f32_e32 v4, 0xbfb8aa3b, v15
	v_exp_f32_e32 v11, v4
	v_or_b32_e32 v4, s94, v0
	v_add_f32_e32 v0, 1.0, v10
	v_rcp_f32_e32 v32, v0
	v_add_f32_e32 v0, 1.0, v11
	v_rcp_f32_e32 v33, v0
	v_or_b32_e32 v0, 24, v224
	s_waitcnt lgkmcnt(0)
	v_lshlrev_b32_e32 v34, 16, v6
	v_and_b32_e32 v35, 0xffff0000, v6
	v_pk_mul_f32 v[14:15], v[32:33], v[14:15]
	v_lshlrev_b32_e32 v32, 16, v133
	v_and_b32_e32 v33, 0xffff0000, v133
	v_mul_f32_e32 v6, 0xbfb8aa3b, v32
	v_lshl_add_u32 v10, v0, 7, v36
	v_exp_f32_e32 v6, v6
	v_mul_f32_e32 v36, 0xbfb8aa3b, v33
	v_exp_f32_e32 v36, v36
	v_pk_mul_f32 v[14:15], v[14:15], v[34:35]
	v_add_f32_e32 v6, 1.0, v6
	v_rcp_f32_e32 v34, v6
	v_add_f32_e32 v6, 1.0, v36
	v_rcp_f32_e32 v35, v6
	v_cvt_pk_bf16_f32 v6, v14, v15
	v_lshlrev_b32_e32 v14, 16, v7
	v_and_b32_e32 v15, 0xffff0000, v7
	v_pk_mul_f32 v[32:33], v[34:35], v[32:33]
	v_lshlrev_b32_e32 v34, 16, v134
	v_and_b32_e32 v35, 0xffff0000, v134
	v_mul_f32_e32 v7, 0xbfb8aa3b, v34
	v_exp_f32_e32 v7, v7
	v_mul_f32_e32 v36, 0xbfb8aa3b, v35
	v_exp_f32_e32 v36, v36
	v_pk_mul_f32 v[14:15], v[32:33], v[14:15]
	v_add_f32_e32 v7, 1.0, v7
	v_rcp_f32_e32 v32, v7
	v_add_f32_e32 v7, 1.0, v36
	v_rcp_f32_e32 v33, v7
	v_cvt_pk_bf16_f32 v7, v14, v15
	v_lshlrev_b32_e32 v14, 16, v8
	v_and_b32_e32 v15, 0xffff0000, v8
	v_pk_mul_f32 v[32:33], v[32:33], v[34:35]
	v_lshlrev_b32_e32 v34, 16, v135
	v_and_b32_e32 v35, 0xffff0000, v135
	v_mul_f32_e32 v8, 0xbfb8aa3b, v34
	v_exp_f32_e32 v8, v8
	v_mul_f32_e32 v36, 0xbfb8aa3b, v35
	v_exp_f32_e32 v36, v36
	v_pk_mul_f32 v[14:15], v[32:33], v[14:15]
	v_add_f32_e32 v8, 1.0, v8
	v_rcp_f32_e32 v32, v8
	v_add_f32_e32 v8, 1.0, v36
	v_rcp_f32_e32 v33, v8
	v_cvt_pk_bf16_f32 v8, v14, v15
	v_lshlrev_b32_e32 v14, 16, v9
	v_and_b32_e32 v15, 0xffff0000, v9
	v_pk_mul_f32 v[32:33], v[32:33], v[34:35]
	ds_read_b128 v[10:13], v10
	v_pk_mul_f32 v[14:15], v[32:33], v[14:15]
	s_waitcnt vmcnt(2)
	v_lshlrev_b32_e32 v32, 16, v128
	v_cvt_pk_bf16_f32 v9, v14, v15
	v_lshlrev_b64 v[14:15], 11, v[4:5]
	v_and_b32_e32 v33, 0xffff0000, v128
	v_mul_f32_e32 v4, 0xbfb8aa3b, v32
	v_exp_f32_e32 v4, v4
	v_mul_f32_e32 v34, 0xbfb8aa3b, v33
	v_exp_f32_e32 v34, v34
	v_lshl_add_u64 v[14:15], v[2:3], 0, v[14:15]
	v_lshl_add_u64 v[14:15], v[14:15], 0, s[8:9]
	v_add_f32_e32 v4, 1.0, v4
	global_store_dwordx4 v[14:15], v[6:9], off
	v_lshlrev_b32_e32 v14, 16, v129
	v_and_b32_e32 v15, 0xffff0000, v129
	v_rcp_f32_e32 v6, v4
	v_add_f32_e32 v4, 1.0, v34
	v_rcp_f32_e32 v7, v4
	v_or_b32_e32 v4, s94, v0
	v_mul_f32_e32 v0, 0xbfb8aa3b, v14
	s_waitcnt lgkmcnt(0)
	v_lshlrev_b32_e32 v8, 16, v10
	v_and_b32_e32 v9, 0xffff0000, v10
	v_exp_f32_e32 v0, v0
	v_mul_f32_e32 v10, 0xbfb8aa3b, v15
	v_exp_f32_e32 v10, v10
	v_pk_mul_f32 v[6:7], v[6:7], v[32:33]
	v_add_f32_e32 v0, 1.0, v0
	v_pk_mul_f32 v[6:7], v[6:7], v[8:9]
	v_rcp_f32_e32 v8, v0
	v_add_f32_e32 v0, 1.0, v10
	v_rcp_f32_e32 v9, v0
	v_cvt_pk_bf16_f32 v6, v6, v7
	v_lshlrev_b32_e32 v10, 16, v11
	v_and_b32_e32 v11, 0xffff0000, v11
	v_pk_mul_f32 v[8:9], v[8:9], v[14:15]
	v_lshlrev_b32_e32 v14, 16, v130
	v_and_b32_e32 v15, 0xffff0000, v130
	v_mul_f32_e32 v0, 0xbfb8aa3b, v14
	v_exp_f32_e32 v0, v0
	v_mul_f32_e32 v7, 0xbfb8aa3b, v15
	v_exp_f32_e32 v7, v7
	v_pk_mul_f32 v[8:9], v[8:9], v[10:11]
	v_add_f32_e32 v0, 1.0, v0
	v_rcp_f32_e32 v10, v0
	v_add_f32_e32 v0, 1.0, v7
	v_rcp_f32_e32 v11, v0
	v_cvt_pk_bf16_f32 v7, v8, v9
	v_lshlrev_b32_e32 v8, 16, v12
	v_and_b32_e32 v9, 0xffff0000, v12
	v_pk_mul_f32 v[10:11], v[10:11], v[14:15]
	v_lshlrev_b32_e32 v14, 16, v131
	v_and_b32_e32 v15, 0xffff0000, v131
	v_mul_f32_e32 v0, 0xbfb8aa3b, v14
	v_exp_f32_e32 v0, v0
	v_mul_f32_e32 v12, 0xbfb8aa3b, v15
	v_exp_f32_e32 v12, v12
	v_pk_mul_f32 v[8:9], v[10:11], v[8:9]
	v_add_f32_e32 v0, 1.0, v0
	v_rcp_f32_e32 v10, v0
	v_add_f32_e32 v0, 1.0, v12
	v_rcp_f32_e32 v11, v0
	v_lshlrev_b32_e32 v12, 16, v13
	v_and_b32_e32 v13, 0xffff0000, v13
	v_lshlrev_b64 v[4:5], 11, v[4:5]
	v_pk_mul_f32 v[10:11], v[10:11], v[14:15]
	v_lshl_add_u64 v[2:3], v[2:3], 0, v[4:5]
	v_pk_mul_f32 v[10:11], v[10:11], v[12:13]
	v_cvt_pk_bf16_f32 v8, v8, v9
	v_cvt_pk_bf16_f32 v9, v10, v11
	v_lshl_add_u64 v[2:3], v[2:3], 0, s[8:9]
	global_store_dwordx4 v[2:3], v[6:9], off
	s_waitcnt vmcnt(0) lgkmcnt(0)
	s_barrier

.LBB0_1313:
	s_mov_b32 s6, s47
	s_mov_b32 s7, s46
	v_add_u32_e32 v214, s7, v206
	ds_read_b64_tr_b16 v[210:211], v214 offset:32768
	ds_read_b64_tr_b16 v[212:213], v214 offset:33280
	v_add_f32_e32 v250, v96, v97
	v_add_f32_e32 v251, v98, v99
	v_add_f32_e32 v252, v100, v101
	v_add_f32_e32 v253, v102, v103
	v_add_f32_e32 v250, v104, v250
	v_cvt_pk_bf16_f32 v160, v96, v97
	v_cvt_pk_bf16_f32 v161, v98, v99
	s_waitcnt lgkmcnt(9)
	v_mfma_f32_32x32x16_bf16 v[128:143], v[112:115], v[172:175], v[32:47]
	ds_read_b64_tr_b16 v[96:97], v214 offset:36864
	ds_read_b64_tr_b16 v[98:99], v214 offset:37376
	s_waitcnt lgkmcnt(10)
	v_mfma_f32_32x32x16_bf16 v[112:127], v[188:191], v[172:175], v[32:47]
	v_add_f32_e32 v251, v105, v251
	v_add_f32_e32 v252, v106, v252
	v_add_f32_e32 v253, v107, v253
	v_add_f32_e32 v250, v108, v250
	v_cvt_pk_bf16_f32 v162, v100, v101
	v_cvt_pk_bf16_f32 v163, v102, v103
	ds_read_b64_tr_b16 v[100:101], v214 offset:33792
	ds_read_b64_tr_b16 v[102:103], v214 offset:34304
	v_add_f32_e32 v251, v109, v251
	v_add_f32_e32 v252, v110, v252
	v_add_f32_e32 v253, v111, v253
	v_add_f32_e32 v250, v80, v250
	v_cvt_pk_bf16_f32 v10, v104, v105
	v_cvt_pk_bf16_f32 v11, v106, v107
	s_waitcnt lgkmcnt(11)
	v_mfma_f32_32x32x16_bf16 v[128:143], v[184:187], v[176:179], v[128:143]
	ds_read_b64_tr_b16 v[104:105], v214 offset:37888
	ds_read_b64_tr_b16 v[106:107], v214 offset:38400
	s_waitcnt lgkmcnt(12)
	v_mfma_f32_32x32x16_bf16 v[112:127], v[180:183], v[176:179], v[112:127]
	v_add_f32_e32 v251, v81, v251
	v_add_f32_e32 v252, v82, v252
	v_add_f32_e32 v253, v83, v253
	v_add_f32_e32 v250, v84, v250
	v_cvt_pk_bf16_f32 v12, v108, v109
	v_cvt_pk_bf16_f32 v13, v110, v111
	ds_read_b64_tr_b16 v[108:109], v214 offset:34816
	ds_read_b64_tr_b16 v[110:111], v214 offset:35328
	v_add_f32_e32 v251, v85, v251
	v_add_f32_e32 v252, v86, v252
	v_add_f32_e32 v253, v87, v253
	v_add_f32_e32 v250, v88, v250
	v_cvt_pk_bf16_f32 v6, v80, v81
	v_cvt_pk_bf16_f32 v7, v82, v83
	s_waitcnt lgkmcnt(13)
	v_mfma_f32_32x32x16_bf16 v[128:143], v[156:159], v[168:171], v[128:143]
	ds_read_b64_tr_b16 v[80:81], v214 offset:38912
	ds_read_b64_tr_b16 v[82:83], v214 offset:39424
	s_waitcnt lgkmcnt(14)
	v_mfma_f32_32x32x16_bf16 v[112:127], v[152:155], v[168:171], v[112:127]
	v_add_f32_e32 v251, v89, v251
	v_add_f32_e32 v252, v90, v252
	v_add_f32_e32 v253, v91, v253
	v_add_f32_e32 v250, v92, v250
	v_cvt_pk_bf16_f32 v8, v84, v85
	v_cvt_pk_bf16_f32 v9, v86, v87
	ds_read_b64_tr_b16 v[84:85], v214 offset:35840
	ds_read_b64_tr_b16 v[86:87], v214 offset:36352
	v_add_f32_e32 v251, v93, v251
	v_add_f32_e32 v252, v94, v252
	v_add_f32_e32 v253, v95, v253
	s_waitcnt lgkmcnt(14)
	v_mfma_f32_32x32x16_bf16 v[128:143], v[148:151], v[164:167], v[128:143]
	v_add_f32_e32 v250, v251, v250
	v_cvt_pk_bf16_f32 v2, v88, v89
	v_cvt_pk_bf16_f32 v3, v90, v91
	ds_read_b64_tr_b16 v[88:89], v214 offset:39936
	ds_read_b64_tr_b16 v[90:91], v214 offset:40448
	v_mfma_f32_32x32x16_bf16 v[112:127], v[144:147], v[164:167], v[112:127]
	v_add_f32_e32 v252, v253, v252
	v_add_f32_e32 v144, v252, v250
	v_cvt_pk_bf16_f32 v4, v92, v93
	v_cvt_pk_bf16_f32 v5, v94, v95
	v_lshl_add_u64 v[92:93], v[196:197], 0, s[14:15]
	s_add_i32 s46, s47, s31
	s_mov_b32 s47, m0
	s_mov_b32 m0, s46
	s_nop 0
	global_load_lds_dwordx4 v[92:93], off
	s_mov_b32 m0, s47
	s_add_i32 s46, s45, s42
	s_mov_b32 s47, m0
	s_mov_b32 m0, s46
	s_nop 0
	global_load_lds_dwordx4 v[194:195], off
	s_mov_b32 m0, s47
	v_add_f32_e32 v0, v0, v144
	s_waitcnt lgkmcnt(14)
	v_mfma_f32_32x32x16_bf16 v[48:63], v[160:163], v[210:213], v[48:63]
	v_exp_f32_e32 v128, v128
	v_exp_f32_e32 v129, v129
	v_exp_f32_e32 v130, v130
	v_exp_f32_e32 v131, v131
	s_waitcnt lgkmcnt(12)
	v_mfma_f32_32x32x16_bf16 v[64:79], v[160:163], v[96:99], v[64:79]
	v_exp_f32_e32 v132, v132
	v_exp_f32_e32 v133, v133
	v_exp_f32_e32 v134, v134
	v_exp_f32_e32 v135, v135
	v_add_u32_e32 v96, s44, v208
	ds_read_b128 v[92:95], v96
	ds_read_b128 v[148:151], v96 offset:2048
	v_add_u32_e32 v97, s44, v209
	s_waitcnt lgkmcnt(12)
	v_mfma_f32_32x32x16_bf16 v[48:63], v[10:13], v[100:103], v[48:63]
	v_exp_f32_e32 v136, v136
	v_exp_f32_e32 v137, v137
	v_exp_f32_e32 v138, v138
	v_exp_f32_e32 v139, v139
	ds_read_b128 v[152:155], v97
	ds_read_b128 v[156:159], v97 offset:2048
	s_waitcnt lgkmcnt(12)
	v_mfma_f32_32x32x16_bf16 v[64:79], v[10:13], v[104:107], v[64:79]
	v_exp_f32_e32 v140, v140
	v_exp_f32_e32 v141, v141
	v_exp_f32_e32 v142, v142
	v_exp_f32_e32 v143, v143
	ds_read_b128 v[180:183], v96 offset:4096
	ds_read_b128 v[184:187], v96 offset:6144
	s_waitcnt lgkmcnt(12)
	v_mfma_f32_32x32x16_bf16 v[48:63], v[6:9], v[108:111], v[48:63]
	v_exp_f32_e32 v112, v112
	v_exp_f32_e32 v113, v113
	v_exp_f32_e32 v114, v114
	v_exp_f32_e32 v115, v115
	ds_read_b128 v[188:191], v97 offset:4096
	ds_read_b128 v[144:147], v97 offset:6144
	s_waitcnt lgkmcnt(12)
	v_mfma_f32_32x32x16_bf16 v[64:79], v[6:9], v[80:83], v[64:79]
	v_exp_f32_e32 v116, v116
	v_exp_f32_e32 v117, v117
	v_exp_f32_e32 v118, v118
	v_exp_f32_e32 v119, v119
	s_waitcnt lgkmcnt(10)
	v_mfma_f32_32x32x16_bf16 v[48:63], v[2:5], v[84:87], v[48:63]
	v_exp_f32_e32 v120, v120
	v_exp_f32_e32 v121, v121
	v_exp_f32_e32 v122, v122
	v_exp_f32_e32 v123, v123
	s_waitcnt lgkmcnt(8)
	v_mfma_f32_32x32x16_bf16 v[64:79], v[2:5], v[88:91], v[64:79]
	v_exp_f32_e32 v124, v124
	v_exp_f32_e32 v125, v125
	v_exp_f32_e32 v126, v126
	v_exp_f32_e32 v127, v127
	s_waitcnt vmcnt(4) lgkmcnt(0)
	s_barrier
	v_add_u32_e32 v218, s6, v206
	ds_read_b64_tr_b16 v[210:211], v218 offset:32768
	ds_read_b64_tr_b16 v[212:213], v218 offset:33280
	s_waitcnt lgkmcnt(9)
	v_mfma_f32_32x32x16_bf16 v[96:111], v[92:95], v[172:175], v[32:47]
	v_add_f32_e32 v250, v128, v129
	v_add_f32_e32 v251, v130, v131
	v_add_f32_e32 v252, v132, v133
	v_add_f32_e32 v253, v134, v135
	v_add_f32_e32 v250, v136, v250
	v_cvt_pk_bf16_f32 v160, v128, v129
	v_cvt_pk_bf16_f32 v161, v130, v131
	ds_read_b64_tr_b16 v[128:129], v218 offset:36864
	ds_read_b64_tr_b16 v[130:131], v218 offset:37376
	s_waitcnt lgkmcnt(10)
	v_mfma_f32_32x32x16_bf16 v[80:95], v[148:151], v[172:175], v[32:47]
	v_add_f32_e32 v251, v137, v251
	v_add_f32_e32 v252, v138, v252
	v_add_f32_e32 v253, v139, v253
	v_add_f32_e32 v250, v140, v250
	v_cvt_pk_bf16_f32 v162, v132, v133
	v_cvt_pk_bf16_f32 v163, v134, v135
	ds_read_b64_tr_b16 v[132:133], v218 offset:33792
	ds_read_b64_tr_b16 v[134:135], v218 offset:34304
	s_waitcnt lgkmcnt(11)
	v_mfma_f32_32x32x16_bf16 v[96:111], v[152:155], v[176:179], v[96:111]
	v_add_f32_e32 v251, v141, v251
	v_add_f32_e32 v252, v142, v252
	v_add_f32_e32 v253, v143, v253
	v_add_f32_e32 v250, v112, v250
	v_cvt_pk_bf16_f32 v10, v136, v137
	v_cvt_pk_bf16_f32 v11, v138, v139
	ds_read_b64_tr_b16 v[136:137], v218 offset:37888
	ds_read_b64_tr_b16 v[138:139], v218 offset:38400
	s_waitcnt lgkmcnt(12)
	v_mfma_f32_32x32x16_bf16 v[80:95], v[156:159], v[176:179], v[80:95]
	v_add_f32_e32 v251, v113, v251
	v_add_f32_e32 v252, v114, v252
	v_add_f32_e32 v253, v115, v253
	v_add_f32_e32 v250, v116, v250
	v_cvt_pk_bf16_f32 v12, v140, v141
	v_cvt_pk_bf16_f32 v13, v142, v143
	ds_read_b64_tr_b16 v[140:141], v218 offset:34816
	ds_read_b64_tr_b16 v[142:143], v218 offset:35328
	s_waitcnt lgkmcnt(13)
	v_mfma_f32_32x32x16_bf16 v[96:111], v[180:183], v[168:171], v[96:111]
	v_add_f32_e32 v251, v117, v251
	v_add_f32_e32 v252, v118, v252
	v_add_f32_e32 v253, v119, v253
	v_add_f32_e32 v250, v120, v250
	v_cvt_pk_bf16_f32 v6, v112, v113
	v_cvt_pk_bf16_f32 v7, v114, v115
	ds_read_b64_tr_b16 v[214:215], v218 offset:38912
	ds_read_b64_tr_b16 v[216:217], v218 offset:39424
	s_waitcnt lgkmcnt(14)
	v_mfma_f32_32x32x16_bf16 v[80:95], v[184:187], v[168:171], v[80:95]
	v_add_f32_e32 v251, v121, v251
	v_add_f32_e32 v252, v122, v252
	v_add_f32_e32 v253, v123, v253
	v_add_f32_e32 v250, v124, v250
	v_cvt_pk_bf16_f32 v8, v116, v117
	v_cvt_pk_bf16_f32 v9, v118, v119
	ds_read_b64_tr_b16 v[116:117], v218 offset:35840
	ds_read_b64_tr_b16 v[118:119], v218 offset:36352
	s_waitcnt lgkmcnt(14)
	v_mfma_f32_32x32x16_bf16 v[96:111], v[188:191], v[164:167], v[96:111]
	v_add_f32_e32 v251, v125, v251
	v_add_f32_e32 v252, v126, v252
	v_add_f32_e32 v253, v127, v253
	v_add_f32_e32 v250, v251, v250
	v_cvt_pk_bf16_f32 v2, v120, v121
	v_cvt_pk_bf16_f32 v3, v122, v123
	ds_read_b64_tr_b16 v[120:121], v218 offset:39936
	ds_read_b64_tr_b16 v[122:123], v218 offset:40448
	v_mfma_f32_32x32x16_bf16 v[80:95], v[144:147], v[164:167], v[80:95]
	v_add_f32_e32 v252, v253, v252
	v_add_f32_e32 v112, v252, v250
	v_cvt_pk_bf16_f32 v4, v124, v125
	v_cvt_pk_bf16_f32 v5, v126, v127
	s_nop 0
	v_add_f32_e32 v0, v0, v112
	v_lshl_add_u64 v[112:113], v[196:197], 0, s[40:41]
	s_add_i32 s46, s44, s31
	s_mov_b32 s47, m0
	s_mov_b32 m0, s46
	s_nop 0
	global_load_lds_dwordx4 v[112:113], off
	s_mov_b32 m0, s47
	v_lshl_add_u64 v[112:113], v[198:199], 0, s[24:25]
	s_add_i32 s46, s7, s42
	s_mov_b32 s47, m0
	s_mov_b32 m0, s46
	s_nop 0
	global_load_lds_dwordx4 v[112:113], off
	s_mov_b32 m0, s47
	s_waitcnt lgkmcnt(14)
	v_mfma_f32_32x32x16_bf16 v[48:63], v[160:163], v[210:213], v[48:63]
	v_exp_f32_e32 v96, v96
	v_exp_f32_e32 v97, v97
	v_exp_f32_e32 v98, v98
	v_exp_f32_e32 v99, v99
	s_waitcnt lgkmcnt(12)
	v_mfma_f32_32x32x16_bf16 v[64:79], v[160:163], v[128:131], v[64:79]
	v_exp_f32_e32 v100, v100
	v_exp_f32_e32 v101, v101
	v_exp_f32_e32 v102, v102
	v_exp_f32_e32 v103, v103
	v_add_u32_e32 v124, s45, v208
	ds_read_b128 v[112:115], v124
	ds_read_b128 v[188:191], v124 offset:2048
	v_add_u32_e32 v125, s45, v209
	s_waitcnt lgkmcnt(12)
	v_mfma_f32_32x32x16_bf16 v[48:63], v[10:13], v[132:135], v[48:63]
	v_exp_f32_e32 v104, v104
	v_exp_f32_e32 v105, v105
	v_exp_f32_e32 v106, v106
	v_exp_f32_e32 v107, v107
	ds_read_b128 v[184:187], v125
	ds_read_b128 v[180:183], v125 offset:2048
	s_waitcnt lgkmcnt(12)
	v_mfma_f32_32x32x16_bf16 v[64:79], v[10:13], v[136:139], v[64:79]
	v_exp_f32_e32 v108, v108
	v_exp_f32_e32 v109, v109
	v_exp_f32_e32 v110, v110
	v_exp_f32_e32 v111, v111
	ds_read_b128 v[156:159], v124 offset:4096
	ds_read_b128 v[152:155], v124 offset:6144
	s_waitcnt lgkmcnt(12)
	v_mfma_f32_32x32x16_bf16 v[48:63], v[6:9], v[140:143], v[48:63]
	v_exp_f32_e32 v80, v80
	v_exp_f32_e32 v81, v81
	v_exp_f32_e32 v82, v82
	v_exp_f32_e32 v83, v83
	ds_read_b128 v[148:151], v125 offset:4096
	ds_read_b128 v[144:147], v125 offset:6144
	s_waitcnt lgkmcnt(12)
	v_mfma_f32_32x32x16_bf16 v[64:79], v[6:9], v[214:217], v[64:79]
	v_exp_f32_e32 v84, v84
	v_exp_f32_e32 v85, v85
	v_exp_f32_e32 v86, v86
	v_exp_f32_e32 v87, v87
	s_waitcnt lgkmcnt(10)
	v_mfma_f32_32x32x16_bf16 v[48:63], v[2:5], v[116:119], v[48:63]
	v_exp_f32_e32 v88, v88
	v_exp_f32_e32 v89, v89
	v_exp_f32_e32 v90, v90
	v_exp_f32_e32 v91, v91
	s_waitcnt lgkmcnt(8)
	v_mfma_f32_32x32x16_bf16 v[64:79], v[2:5], v[120:123], v[64:79]
	v_exp_f32_e32 v92, v92
	v_exp_f32_e32 v93, v93
	v_exp_f32_e32 v94, v94
	v_exp_f32_e32 v95, v95
	s_waitcnt vmcnt(4) lgkmcnt(0)
	s_barrier
	s_add_i32 s43, s43, 2
	v_lshl_add_u64 v[194:195], v[194:195], 0, s[22:23]
	v_lshl_add_u64 v[196:197], v[196:197], 0, s[22:23]
	v_lshl_add_u64 v[198:199], v[198:199], 0, s[22:23]
	s_mov_b32 s46, s44
	s_mov_b32 s47, s45
	s_mov_b32 s44, s7
	s_cmp_gt_u32 s43, 60
	s_mov_b32 s45, s6
	s_cbranch_scc0 .LBB0_1313
	s_and_b32 s6, s21, 0x3fffffc0
	s_lshl_b32 s6, s6, 2
	s_add_i32 s31, s6, 0
	s_add_i32 s31, s31, 0x10000
	ds_read_b64_tr_b16 v[194:195], v206 offset:49152
	ds_read_b64_tr_b16 v[196:197], v206 offset:49664
	s_waitcnt lgkmcnt(9)
	v_mfma_f32_32x32x16_bf16 v[128:143], v[112:115], v[172:175], v[32:47]
	v_add_f32_e32 v250, v96, v97
	v_add_f32_e32 v251, v98, v99
	v_add_f32_e32 v252, v100, v101
	v_add_f32_e32 v253, v102, v103
	v_add_f32_e32 v250, v104, v250
	v_cvt_pk_bf16_f32 v160, v96, v97
	v_cvt_pk_bf16_f32 v161, v98, v99
	ds_read_b64_tr_b16 v[96:97], v206 offset:53248
	ds_read_b64_tr_b16 v[98:99], v206 offset:53760
	v_add_f32_e32 v251, v105, v251
	v_add_f32_e32 v252, v106, v252
	v_add_f32_e32 v253, v107, v253
	v_add_f32_e32 v250, v108, v250
	v_cvt_pk_bf16_f32 v162, v100, v101
	v_cvt_pk_bf16_f32 v163, v102, v103
	s_waitcnt lgkmcnt(10)
	v_mfma_f32_32x32x16_bf16 v[112:127], v[188:191], v[172:175], v[32:47]
	ds_read_b64_tr_b16 v[100:101], v206 offset:50176
	ds_read_b64_tr_b16 v[102:103], v206 offset:50688
	s_waitcnt lgkmcnt(11)
	v_mfma_f32_32x32x16_bf16 v[128:143], v[184:187], v[176:179], v[128:143]
	v_add_f32_e32 v251, v109, v251
	v_add_f32_e32 v252, v110, v252
	v_add_f32_e32 v253, v111, v253
	v_add_f32_e32 v250, v80, v250
	v_cvt_pk_bf16_f32 v10, v104, v105
	v_cvt_pk_bf16_f32 v11, v106, v107
	ds_read_b64_tr_b16 v[104:105], v206 offset:54272
	ds_read_b64_tr_b16 v[106:107], v206 offset:54784
	v_add_f32_e32 v251, v81, v251
	v_add_f32_e32 v252, v82, v252
	v_add_f32_e32 v253, v83, v253
	v_add_f32_e32 v250, v84, v250
	v_cvt_pk_bf16_f32 v12, v108, v109
	v_cvt_pk_bf16_f32 v13, v110, v111
	s_waitcnt lgkmcnt(12)
	v_mfma_f32_32x32x16_bf16 v[112:127], v[180:183], v[176:179], v[112:127]
	ds_read_b64_tr_b16 v[108:109], v206 offset:51200
	ds_read_b64_tr_b16 v[110:111], v206 offset:51712
	s_waitcnt lgkmcnt(13)
	v_mfma_f32_32x32x16_bf16 v[128:143], v[156:159], v[168:171], v[128:143]
	v_add_f32_e32 v251, v85, v251
	v_add_f32_e32 v252, v86, v252
	v_add_f32_e32 v253, v87, v253
	v_add_f32_e32 v250, v88, v250
	v_cvt_pk_bf16_f32 v6, v80, v81
	v_cvt_pk_bf16_f32 v7, v82, v83
	ds_read_b64_tr_b16 v[80:81], v206 offset:55296
	ds_read_b64_tr_b16 v[82:83], v206 offset:55808
	v_add_f32_e32 v251, v89, v251
	v_add_f32_e32 v252, v90, v252
	v_add_f32_e32 v253, v91, v253
	v_add_f32_e32 v250, v92, v250
	v_cvt_pk_bf16_f32 v8, v84, v85
	v_cvt_pk_bf16_f32 v9, v86, v87
	s_waitcnt lgkmcnt(14)
	v_mfma_f32_32x32x16_bf16 v[112:127], v[152:155], v[168:171], v[112:127]
	ds_read_b64_tr_b16 v[84:85], v206 offset:52224
	ds_read_b64_tr_b16 v[86:87], v206 offset:52736
	s_waitcnt lgkmcnt(14)
	v_mfma_f32_32x32x16_bf16 v[128:143], v[148:151], v[164:167], v[128:143]
	v_add_f32_e32 v251, v93, v251
	v_add_f32_e32 v252, v94, v252
	v_add_f32_e32 v253, v95, v253
	v_add_f32_e32 v250, v251, v250
	v_cvt_pk_bf16_f32 v2, v88, v89
	v_cvt_pk_bf16_f32 v3, v90, v91
	ds_read_b64_tr_b16 v[88:89], v206 offset:56320
	ds_read_b64_tr_b16 v[90:91], v206 offset:56832
	v_add_f32_e32 v252, v253, v252
	v_add_f32_e32 v148, v252, v250
	v_cvt_pk_bf16_f32 v4, v92, v93
	v_cvt_pk_bf16_f32 v5, v94, v95
	v_mfma_f32_32x32x16_bf16 v[112:127], v[144:147], v[164:167], v[112:127]
	s_mov_b64 s[42:43], 0x10c000
	v_lshl_add_u64 v[92:93], v[192:193], 0, s[42:43]
	s_mov_b32 s6, m0
	s_mov_b32 m0, s20
	s_nop 0
	global_load_lds_dwordx4 v[92:93], off
	s_mov_b32 m0, s6
	s_mov_b64 s[6:7], 0x104000
	s_cmp_lg_u32 0, -1
	v_lshl_add_u64 v[92:93], v[14:15], 0, s[6:7]
	s_cselect_b32 s6, 0, 0
	s_add_i32 s7, s6, s8
	s_add_i32 s20, s7, 0xa000
	s_mov_b32 s21, m0
	s_mov_b32 m0, s20
	s_nop 0
	global_load_lds_dwordx4 v[92:93], off
	s_mov_b32 m0, s21
	v_add_f32_e32 v0, v0, v148
	s_waitcnt lgkmcnt(14)
	v_mfma_f32_32x32x16_bf16 v[48:63], v[160:163], v[194:197], v[48:63]
	v_exp_f32_e32 v128, v128
	v_exp_f32_e32 v129, v129
	v_exp_f32_e32 v130, v130
	v_exp_f32_e32 v131, v131
	s_waitcnt lgkmcnt(12)
	v_mfma_f32_32x32x16_bf16 v[64:79], v[160:163], v[96:99], v[64:79]
	v_exp_f32_e32 v132, v132
	v_exp_f32_e32 v133, v133
	v_exp_f32_e32 v134, v134
	v_exp_f32_e32 v135, v135
	ds_read_b128 v[92:95], v208
	ds_read_b128 v[180:183], v208 offset:2048
	s_waitcnt lgkmcnt(12)
	v_mfma_f32_32x32x16_bf16 v[48:63], v[10:13], v[100:103], v[48:63]
	v_exp_f32_e32 v136, v136
	v_exp_f32_e32 v137, v137
	v_exp_f32_e32 v138, v138
	v_exp_f32_e32 v139, v139
	ds_read_b128 v[100:103], v209
	ds_read_b128 v[184:187], v209 offset:2048
	s_waitcnt lgkmcnt(12)
	v_mfma_f32_32x32x16_bf16 v[64:79], v[10:13], v[104:107], v[64:79]
	v_exp_f32_e32 v140, v140
	v_exp_f32_e32 v141, v141
	v_exp_f32_e32 v142, v142
	v_exp_f32_e32 v143, v143
	ds_read_b128 v[104:107], v208 offset:4096
	ds_read_b128 v[188:191], v208 offset:6144
	s_waitcnt lgkmcnt(12)
	v_mfma_f32_32x32x16_bf16 v[48:63], v[6:9], v[108:111], v[48:63]
	v_exp_f32_e32 v112, v112
	v_exp_f32_e32 v113, v113
	v_exp_f32_e32 v114, v114
	v_exp_f32_e32 v115, v115
	ds_read_b128 v[108:111], v209 offset:4096
	ds_read_b128 v[96:99], v209 offset:6144
	s_waitcnt lgkmcnt(12)
	v_mfma_f32_32x32x16_bf16 v[64:79], v[6:9], v[80:83], v[64:79]
	v_exp_f32_e32 v116, v116
	v_exp_f32_e32 v117, v117
	v_exp_f32_e32 v118, v118
	v_exp_f32_e32 v119, v119
	s_waitcnt lgkmcnt(10)
	v_mfma_f32_32x32x16_bf16 v[48:63], v[2:5], v[84:87], v[48:63]
	v_exp_f32_e32 v120, v120
	v_exp_f32_e32 v121, v121
	v_exp_f32_e32 v122, v122
	v_exp_f32_e32 v123, v123
	s_waitcnt lgkmcnt(8)
	v_mfma_f32_32x32x16_bf16 v[64:79], v[2:5], v[88:91], v[64:79]
	v_exp_f32_e32 v124, v124
	v_exp_f32_e32 v125, v125
	v_exp_f32_e32 v126, v126
	v_exp_f32_e32 v127, v127
	s_waitcnt vmcnt(4) lgkmcnt(0)
	s_barrier
	ds_read_b64_tr_b16 v[192:193], v206 offset:57344
	ds_read_b64_tr_b16 v[194:195], v206 offset:57856
	v_add_f32_e32 v250, v128, v129
	v_add_f32_e32 v251, v130, v131
	v_add_f32_e32 v252, v132, v133
	v_add_f32_e32 v253, v134, v135
	v_add_f32_e32 v250, v136, v250
	v_cvt_pk_bf16_f32 v160, v128, v129
	v_cvt_pk_bf16_f32 v161, v130, v131
	s_waitcnt lgkmcnt(9)
	v_mfma_f32_32x32x16_bf16 v[144:159], v[92:95], v[172:175], v[32:47]
	ds_read_b64_tr_b16 v[128:129], v206 offset:61440
	ds_read_b64_tr_b16 v[130:131], v206 offset:61952
	s_waitcnt lgkmcnt(10)
	v_mfma_f32_32x32x16_bf16 v[80:95], v[180:183], v[172:175], v[32:47]
	v_add_f32_e32 v251, v137, v251
	v_add_f32_e32 v252, v138, v252
	v_add_f32_e32 v253, v139, v253
	v_add_f32_e32 v250, v140, v250
	v_cvt_pk_bf16_f32 v162, v132, v133
	v_cvt_pk_bf16_f32 v163, v134, v135
	ds_read_b64_tr_b16 v[132:133], v206 offset:58368
	ds_read_b64_tr_b16 v[134:135], v206 offset:58880
	v_add_f32_e32 v251, v141, v251
	v_add_f32_e32 v252, v142, v252
	v_add_f32_e32 v253, v143, v253
	v_add_f32_e32 v250, v112, v250
	v_cvt_pk_bf16_f32 v10, v136, v137
	v_cvt_pk_bf16_f32 v11, v138, v139
	s_waitcnt lgkmcnt(11)
	v_mfma_f32_32x32x16_bf16 v[144:159], v[100:103], v[176:179], v[144:159]
	ds_read_b64_tr_b16 v[100:101], v206 offset:62464
	ds_read_b64_tr_b16 v[102:103], v206 offset:62976
	s_waitcnt lgkmcnt(12)
	v_mfma_f32_32x32x16_bf16 v[80:95], v[184:187], v[176:179], v[80:95]
	v_add_f32_e32 v251, v113, v251
	v_add_f32_e32 v252, v114, v252
	v_add_f32_e32 v253, v115, v253
	v_add_f32_e32 v250, v116, v250
	v_cvt_pk_bf16_f32 v12, v140, v141
	v_cvt_pk_bf16_f32 v13, v142, v143
	ds_read_b64_tr_b16 v[136:137], v206 offset:59392
	ds_read_b64_tr_b16 v[138:139], v206 offset:59904
	v_add_f32_e32 v251, v117, v251
	v_add_f32_e32 v252, v118, v252
	v_add_f32_e32 v253, v119, v253
	v_add_f32_e32 v250, v120, v250
	v_cvt_pk_bf16_f32 v6, v112, v113
	v_cvt_pk_bf16_f32 v7, v114, v115
	s_waitcnt lgkmcnt(13)
	v_mfma_f32_32x32x16_bf16 v[144:159], v[104:107], v[168:171], v[144:159]
	ds_read_b64_tr_b16 v[104:105], v206 offset:63488
	ds_read_b64_tr_b16 v[106:107], v206 offset:64000
	s_waitcnt lgkmcnt(14)
	v_mfma_f32_32x32x16_bf16 v[80:95], v[188:191], v[168:171], v[80:95]
	v_add_f32_e32 v251, v121, v251
	v_add_f32_e32 v252, v122, v252
	v_add_f32_e32 v253, v123, v253
	v_add_f32_e32 v250, v124, v250
	v_cvt_pk_bf16_f32 v8, v116, v117
	v_cvt_pk_bf16_f32 v9, v118, v119
	ds_read_b64_tr_b16 v[116:117], v206 offset:60416
	ds_read_b64_tr_b16 v[118:119], v206 offset:60928
	v_add_f32_e32 v251, v125, v251
	v_add_f32_e32 v252, v126, v252
	v_add_f32_e32 v253, v127, v253
	v_add_f32_e32 v250, v251, v250
	v_cvt_pk_bf16_f32 v2, v120, v121
	v_cvt_pk_bf16_f32 v3, v122, v123
	s_waitcnt lgkmcnt(14)
	v_mfma_f32_32x32x16_bf16 v[144:159], v[108:111], v[164:167], v[144:159]
	ds_read_b64_tr_b16 v[108:109], v206 offset:64512
	ds_read_b64_tr_b16 v[110:111], v206 offset:65024
	v_mfma_f32_32x32x16_bf16 v[80:95], v[96:99], v[164:167], v[80:95]
	v_add_f32_e32 v252, v253, v252
	v_add_f32_e32 v96, v252, v250
	v_cvt_pk_bf16_f32 v4, v124, v125
	v_cvt_pk_bf16_f32 v5, v126, v127
	s_mov_b64 s[20:21], 0x108000
	v_add_f32_e32 v0, v0, v96
	v_lshl_add_u64 v[96:97], v[14:15], 0, s[20:21]
	s_add_i32 s7, s7, 0xc000
	s_mov_b32 s20, m0
	s_mov_b32 m0, s7
	s_nop 0
	global_load_lds_dwordx4 v[96:97], off
	s_mov_b32 m0, s20
	s_waitcnt lgkmcnt(14)
	v_mfma_f32_32x32x16_bf16 v[48:63], v[160:163], v[192:195], v[48:63]
	v_exp_f32_e32 v144, v144
	v_exp_f32_e32 v145, v145
	v_exp_f32_e32 v146, v146
	v_exp_f32_e32 v147, v147
	s_waitcnt lgkmcnt(12)
	v_mfma_f32_32x32x16_bf16 v[64:79], v[160:163], v[128:131], v[64:79]
	v_exp_f32_e32 v148, v148
	v_exp_f32_e32 v149, v149
	v_exp_f32_e32 v150, v150
	v_exp_f32_e32 v151, v151
	ds_read_b128 v[96:99], v208 offset:8192
	ds_read_b128 v[120:123], v208 offset:10240
	s_waitcnt lgkmcnt(12)
	v_mfma_f32_32x32x16_bf16 v[48:63], v[10:13], v[132:135], v[48:63]
	v_exp_f32_e32 v152, v152
	v_exp_f32_e32 v153, v153
	v_exp_f32_e32 v154, v154
	v_exp_f32_e32 v155, v155
	ds_read_b128 v[124:127], v209 offset:8192
	ds_read_b128 v[180:183], v209 offset:10240
	s_waitcnt lgkmcnt(12)
	v_mfma_f32_32x32x16_bf16 v[64:79], v[10:13], v[100:103], v[64:79]
	v_exp_f32_e32 v156, v156
	v_exp_f32_e32 v157, v157
	v_exp_f32_e32 v158, v158
	v_exp_f32_e32 v159, v159
	ds_read_b128 v[184:187], v208 offset:12288
	ds_read_b128 v[188:191], v208 offset:14336
	s_waitcnt lgkmcnt(12)
	v_mfma_f32_32x32x16_bf16 v[48:63], v[6:9], v[136:139], v[48:63]
	v_exp_f32_e32 v80, v80
	v_exp_f32_e32 v81, v81
	v_exp_f32_e32 v82, v82
	v_exp_f32_e32 v83, v83
	ds_read_b128 v[192:195], v209 offset:12288
	ds_read_b128 v[112:115], v209 offset:14336
	s_waitcnt lgkmcnt(12)
	v_mfma_f32_32x32x16_bf16 v[64:79], v[6:9], v[104:107], v[64:79]
	v_exp_f32_e32 v84, v84
	v_exp_f32_e32 v85, v85
	v_exp_f32_e32 v86, v86
	v_exp_f32_e32 v87, v87
	s_waitcnt lgkmcnt(10)
	v_mfma_f32_32x32x16_bf16 v[48:63], v[2:5], v[116:119], v[48:63]
	v_exp_f32_e32 v88, v88
	v_exp_f32_e32 v89, v89
	v_exp_f32_e32 v90, v90
	v_exp_f32_e32 v91, v91
	s_waitcnt lgkmcnt(8)
	v_mfma_f32_32x32x16_bf16 v[64:79], v[2:5], v[108:111], v[64:79]
	v_exp_f32_e32 v92, v92
	v_exp_f32_e32 v93, v93
	v_exp_f32_e32 v94, v94
	v_exp_f32_e32 v95, v95
	s_waitcnt vmcnt(3) lgkmcnt(0)
	s_barrier
	ds_read_b64_tr_b16 v[116:117], v206 offset:32768
	ds_read_b64_tr_b16 v[118:119], v206 offset:33280
	s_waitcnt lgkmcnt(9)
	v_mfma_f32_32x32x16_bf16 v[128:143], v[96:99], v[172:175], v[32:47]
	v_add_f32_e32 v250, v144, v145
	v_add_f32_e32 v251, v146, v147
	v_add_f32_e32 v252, v148, v149
	v_add_f32_e32 v253, v150, v151
	v_add_f32_e32 v250, v152, v250
	v_cvt_pk_bf16_f32 v160, v144, v145
	v_cvt_pk_bf16_f32 v161, v146, v147
	ds_read_b64_tr_b16 v[144:145], v206 offset:36864
	ds_read_b64_tr_b16 v[146:147], v206 offset:37376
	v_add_f32_e32 v251, v153, v251
	v_add_f32_e32 v252, v154, v252
	v_add_f32_e32 v253, v155, v253
	v_add_f32_e32 v250, v156, v250
	v_cvt_pk_bf16_f32 v162, v148, v149
	v_cvt_pk_bf16_f32 v163, v150, v151
	s_waitcnt lgkmcnt(10)
	v_mfma_f32_32x32x16_bf16 v[96:111], v[120:123], v[172:175], v[32:47]
	ds_read_b64_tr_b16 v[120:121], v206 offset:33792
	ds_read_b64_tr_b16 v[122:123], v206 offset:34304
	s_waitcnt lgkmcnt(11)
	v_mfma_f32_32x32x16_bf16 v[128:143], v[124:127], v[176:179], v[128:143]
	v_add_f32_e32 v251, v157, v251
	v_add_f32_e32 v252, v158, v252
	v_add_f32_e32 v253, v159, v253
	v_add_f32_e32 v250, v80, v250
	v_cvt_pk_bf16_f32 v10, v152, v153
	v_cvt_pk_bf16_f32 v11, v154, v155
	ds_read_b64_tr_b16 v[124:125], v206 offset:37888
	ds_read_b64_tr_b16 v[126:127], v206 offset:38400
	v_add_f32_e32 v251, v81, v251
	v_add_f32_e32 v252, v82, v252
	v_add_f32_e32 v253, v83, v253
	v_add_f32_e32 v250, v84, v250
	v_cvt_pk_bf16_f32 v12, v156, v157
	v_cvt_pk_bf16_f32 v13, v158, v159
	s_waitcnt lgkmcnt(12)
	v_mfma_f32_32x32x16_bf16 v[96:111], v[180:183], v[176:179], v[96:111]
	ds_read_b64_tr_b16 v[148:149], v206 offset:34816
	ds_read_b64_tr_b16 v[150:151], v206 offset:35328
	s_waitcnt lgkmcnt(13)
	v_mfma_f32_32x32x16_bf16 v[128:143], v[184:187], v[168:171], v[128:143]
	v_add_f32_e32 v251, v85, v251
	v_add_f32_e32 v252, v86, v252
	v_add_f32_e32 v253, v87, v253
	v_add_f32_e32 v250, v88, v250
	v_cvt_pk_bf16_f32 v6, v80, v81
	v_cvt_pk_bf16_f32 v7, v82, v83
	ds_read_b64_tr_b16 v[80:81], v206 offset:38912
	ds_read_b64_tr_b16 v[82:83], v206 offset:39424
	v_add_f32_e32 v251, v89, v251
	v_add_f32_e32 v252, v90, v252
	v_add_f32_e32 v253, v91, v253
	v_add_f32_e32 v250, v92, v250
	v_cvt_pk_bf16_f32 v8, v84, v85
	v_cvt_pk_bf16_f32 v9, v86, v87
	s_waitcnt lgkmcnt(14)
	v_mfma_f32_32x32x16_bf16 v[96:111], v[188:191], v[168:171], v[96:111]
	ds_read_b64_tr_b16 v[84:85], v206 offset:35840
	ds_read_b64_tr_b16 v[86:87], v206 offset:36352
	s_waitcnt lgkmcnt(14)
	v_mfma_f32_32x32x16_bf16 v[128:143], v[192:195], v[164:167], v[128:143]
	v_add_f32_e32 v251, v93, v251
	v_add_f32_e32 v252, v94, v252
	v_add_f32_e32 v253, v95, v253
	v_add_f32_e32 v250, v251, v250
	v_cvt_pk_bf16_f32 v2, v88, v89
	v_cvt_pk_bf16_f32 v3, v90, v91
	ds_read_b64_tr_b16 v[88:89], v206 offset:39936
	ds_read_b64_tr_b16 v[90:91], v206 offset:40448
	v_add_f32_e32 v252, v253, v252
	v_add_f32_e32 v152, v252, v250
	v_cvt_pk_bf16_f32 v4, v92, v93
	v_cvt_pk_bf16_f32 v5, v94, v95
	v_mfma_f32_32x32x16_bf16 v[96:111], v[112:115], v[164:167], v[96:111]
	s_add_i32 s6, s6, 0xe000
	v_lshl_add_u64 v[14:15], v[14:15], 0, s[42:43]
	s_add_i32 s8, s8, s6
	s_mov_b32 s7, m0
	s_mov_b32 m0, s8
	s_nop 0
	global_load_lds_dwordx4 v[14:15], off
	s_mov_b32 m0, s7
	v_add_f32_e32 v0, v0, v152
	s_mov_b64 s[80:81], 0x10c000
	s_waitcnt lgkmcnt(14)
	v_mfma_f32_32x32x16_bf16 v[48:63], v[160:163], v[116:119], v[48:63]
	v_exp_f32_e32 v128, v128
	v_exp_f32_e32 v129, v129
	v_exp_f32_e32 v130, v130
	v_exp_f32_e32 v131, v131
	s_waitcnt lgkmcnt(12)
	v_mfma_f32_32x32x16_bf16 v[64:79], v[160:163], v[144:147], v[64:79]
	v_exp_f32_e32 v132, v132
	v_exp_f32_e32 v133, v133
	v_exp_f32_e32 v134, v134
	v_exp_f32_e32 v135, v135
	ds_read_b128 v[92:95], v208 offset:16384
	ds_read_b128 v[152:155], v208 offset:18432
	s_waitcnt lgkmcnt(12)
	v_mfma_f32_32x32x16_bf16 v[48:63], v[10:13], v[120:123], v[48:63]
	v_exp_f32_e32 v136, v136
	v_exp_f32_e32 v137, v137
	v_exp_f32_e32 v138, v138
	v_exp_f32_e32 v139, v139
	ds_read_b128 v[156:159], v209 offset:16384
	ds_read_b128 v[180:183], v209 offset:18432
	s_waitcnt lgkmcnt(12)
	v_mfma_f32_32x32x16_bf16 v[64:79], v[10:13], v[124:127], v[64:79]
	v_exp_f32_e32 v140, v140
	v_exp_f32_e32 v141, v141
	v_exp_f32_e32 v142, v142
	v_exp_f32_e32 v143, v143
	ds_read_b128 v[184:187], v208 offset:20480
	ds_read_b128 v[188:191], v208 offset:22528
	s_waitcnt lgkmcnt(12)
	v_mfma_f32_32x32x16_bf16 v[48:63], v[6:9], v[148:151], v[48:63]
	v_exp_f32_e32 v96, v96
	v_exp_f32_e32 v97, v97
	v_exp_f32_e32 v98, v98
	v_exp_f32_e32 v99, v99
	ds_read_b128 v[148:151], v209 offset:20480
	ds_read_b128 v[144:147], v209 offset:22528
	s_waitcnt lgkmcnt(12)
	v_mfma_f32_32x32x16_bf16 v[64:79], v[6:9], v[80:83], v[64:79]
	v_exp_f32_e32 v100, v100
	v_exp_f32_e32 v101, v101
	v_exp_f32_e32 v102, v102
	v_exp_f32_e32 v103, v103
	s_waitcnt lgkmcnt(10)
	v_mfma_f32_32x32x16_bf16 v[48:63], v[2:5], v[84:87], v[48:63]
	v_exp_f32_e32 v104, v104
	v_exp_f32_e32 v105, v105
	v_exp_f32_e32 v106, v106
	v_exp_f32_e32 v107, v107
	s_waitcnt lgkmcnt(8)
	v_mfma_f32_32x32x16_bf16 v[64:79], v[2:5], v[88:91], v[64:79]
	v_exp_f32_e32 v108, v108
	v_exp_f32_e32 v109, v109
	v_exp_f32_e32 v110, v110
	v_exp_f32_e32 v111, v111
	s_waitcnt vmcnt(2) lgkmcnt(0)
	s_barrier
	ds_read_b64_tr_b16 v[192:193], v206 offset:40960
	ds_read_b64_tr_b16 v[194:195], v206 offset:41472
	v_add_f32_e32 v250, v128, v129
	v_add_f32_e32 v251, v130, v131
	v_add_f32_e32 v252, v132, v133
	v_add_f32_e32 v253, v134, v135
	v_add_f32_e32 v250, v136, v250
	v_cvt_pk_bf16_f32 v160, v128, v129
	v_cvt_pk_bf16_f32 v161, v130, v131
	s_waitcnt lgkmcnt(9)
	v_mfma_f32_32x32x16_bf16 v[112:127], v[92:95], v[172:175], v[32:47]
	ds_read_b64_tr_b16 v[128:129], v206 offset:45056
	ds_read_b64_tr_b16 v[130:131], v206 offset:45568
	s_waitcnt lgkmcnt(10)
	v_mfma_f32_32x32x16_bf16 v[80:95], v[152:155], v[172:175], v[32:47]
	v_add_f32_e32 v251, v137, v251
	v_add_f32_e32 v252, v138, v252
	v_add_f32_e32 v253, v139, v253
	v_add_f32_e32 v250, v140, v250
	v_cvt_pk_bf16_f32 v162, v132, v133
	v_cvt_pk_bf16_f32 v163, v134, v135
	ds_read_b64_tr_b16 v[132:133], v206 offset:41984
	ds_read_b64_tr_b16 v[134:135], v206 offset:42496
	v_add_f32_e32 v251, v141, v251
	v_add_f32_e32 v252, v142, v252
	v_add_f32_e32 v253, v143, v253
	v_add_f32_e32 v250, v96, v250
	v_cvt_pk_bf16_f32 v10, v136, v137
	v_cvt_pk_bf16_f32 v11, v138, v139
	s_waitcnt lgkmcnt(11)
	v_mfma_f32_32x32x16_bf16 v[112:127], v[156:159], v[176:179], v[112:127]
	ds_read_b64_tr_b16 v[136:137], v206 offset:46080
	ds_read_b64_tr_b16 v[138:139], v206 offset:46592
	s_waitcnt lgkmcnt(12)
	v_mfma_f32_32x32x16_bf16 v[80:95], v[180:183], v[176:179], v[80:95]
	v_add_f32_e32 v251, v97, v251
	v_add_f32_e32 v252, v98, v252
	v_add_f32_e32 v253, v99, v253
	v_add_f32_e32 v250, v100, v250
	v_cvt_pk_bf16_f32 v12, v140, v141
	v_cvt_pk_bf16_f32 v13, v142, v143
	ds_read_b64_tr_b16 v[140:141], v206 offset:43008
	ds_read_b64_tr_b16 v[142:143], v206 offset:43520
	v_add_f32_e32 v251, v101, v251
	v_add_f32_e32 v252, v102, v252
	v_add_f32_e32 v253, v103, v253
	v_add_f32_e32 v250, v104, v250
	v_cvt_pk_bf16_f32 v6, v96, v97
	v_cvt_pk_bf16_f32 v7, v98, v99
	s_waitcnt lgkmcnt(13)
	v_mfma_f32_32x32x16_bf16 v[112:127], v[184:187], v[168:171], v[112:127]
	ds_read_b64_tr_b16 v[96:97], v206 offset:47104
	ds_read_b64_tr_b16 v[98:99], v206 offset:47616
	s_waitcnt lgkmcnt(14)
	v_mfma_f32_32x32x16_bf16 v[80:95], v[188:191], v[168:171], v[80:95]
	v_add_f32_e32 v251, v105, v251
	v_add_f32_e32 v252, v106, v252
	v_add_f32_e32 v253, v107, v253
	v_add_f32_e32 v250, v108, v250
	v_cvt_pk_bf16_f32 v8, v100, v101
	v_cvt_pk_bf16_f32 v9, v102, v103
	ds_read_b64_tr_b16 v[100:101], v206 offset:44032
	ds_read_b64_tr_b16 v[102:103], v206 offset:44544
	v_add_f32_e32 v251, v109, v251
	v_add_f32_e32 v252, v110, v252
	v_add_f32_e32 v253, v111, v253
	v_add_f32_e32 v250, v251, v250
	v_cvt_pk_bf16_f32 v2, v104, v105
	v_cvt_pk_bf16_f32 v3, v106, v107
	s_waitcnt lgkmcnt(14)
	v_mfma_f32_32x32x16_bf16 v[112:127], v[148:151], v[164:167], v[112:127]
	ds_read_b64_tr_b16 v[104:105], v206 offset:48128
	ds_read_b64_tr_b16 v[106:107], v206 offset:48640
	v_mfma_f32_32x32x16_bf16 v[80:95], v[144:147], v[164:167], v[80:95]
	v_add_f32_e32 v252, v253, v252
	v_add_f32_e32 v14, v252, v250
	v_cvt_pk_bf16_f32 v4, v108, v109
	v_cvt_pk_bf16_f32 v5, v110, v111
	s_nop 0
	v_add_f32_e32 v185, v0, v14
	s_waitcnt lgkmcnt(14)
	v_mfma_f32_32x32x16_bf16 v[48:63], v[160:163], v[192:195], v[48:63]
	s_nop 0
	v_exp_f32_e32 v112, v112
	v_exp_f32_e32 v113, v113
	v_exp_f32_e32 v114, v114
	v_exp_f32_e32 v115, v115
	s_waitcnt lgkmcnt(12)
	v_mfma_f32_32x32x16_bf16 v[64:79], v[160:163], v[128:131], v[64:79]
	v_exp_f32_e32 v116, v116
	v_exp_f32_e32 v117, v117
	v_exp_f32_e32 v118, v118
	v_exp_f32_e32 v119, v119
	ds_read_b128 v[148:151], v208 offset:24576
	ds_read_b128 v[186:189], v208 offset:26624
	s_waitcnt lgkmcnt(12)
	v_mfma_f32_32x32x16_bf16 v[48:63], v[10:13], v[132:135], v[48:63]
	v_exp_f32_e32 v120, v120
	v_exp_f32_e32 v121, v121
	v_exp_f32_e32 v122, v122
	v_exp_f32_e32 v123, v123
	ds_read_b128 v[190:193], v209 offset:24576
	ds_read_b128 v[194:197], v209 offset:26624
	s_waitcnt lgkmcnt(12)
	v_mfma_f32_32x32x16_bf16 v[64:79], v[10:13], v[136:139], v[64:79]
	v_exp_f32_e32 v124, v124
	v_exp_f32_e32 v125, v125
	v_exp_f32_e32 v126, v126
	v_exp_f32_e32 v127, v127
	ds_read_b128 v[210:213], v208 offset:28672
	ds_read_b128 v[180:183], v208 offset:30720
	s_waitcnt lgkmcnt(12)
	v_mfma_f32_32x32x16_bf16 v[48:63], v[6:9], v[140:143], v[48:63]
	v_exp_f32_e32 v80, v80
	v_exp_f32_e32 v81, v81
	v_exp_f32_e32 v82, v82
	v_exp_f32_e32 v83, v83
	ds_read_b128 v[156:159], v209 offset:28672
	ds_read_b128 v[152:155], v209 offset:30720
	s_waitcnt lgkmcnt(12)
	v_mfma_f32_32x32x16_bf16 v[64:79], v[6:9], v[96:99], v[64:79]
	v_exp_f32_e32 v84, v84
	v_exp_f32_e32 v85, v85
	v_exp_f32_e32 v86, v86
	v_exp_f32_e32 v87, v87
	s_waitcnt lgkmcnt(10)
	v_mfma_f32_32x32x16_bf16 v[48:63], v[2:5], v[100:103], v[48:63]
	v_exp_f32_e32 v88, v88
	v_exp_f32_e32 v89, v89
	v_exp_f32_e32 v90, v90
	v_exp_f32_e32 v91, v91
	s_waitcnt lgkmcnt(8)
	v_mfma_f32_32x32x16_bf16 v[64:79], v[2:5], v[104:107], v[64:79]
	v_exp_f32_e32 v92, v92
	v_exp_f32_e32 v93, v93
	v_exp_f32_e32 v94, v94
	v_exp_f32_e32 v95, v95
	v_lshrrev_b32_e32 v184, 3, v203
	v_or_b32_e32 v2, s4, v184
	v_mov_b32_e32 v3, s5
	v_lshlrev_b64 v[14:15], 11, v[2:3]
	v_lshl_add_u64 v[2:3], s[48:49], 0, v[14:15]
	s_lshl_b32 s8, s26, 1
	v_and_b32_e32 v0, 56, v207
	v_lshl_add_u64 v[2:3], v[2:3], 0, s[8:9]
	v_lshlrev_b32_e32 v0, 1, v0
	v_lshl_add_u64 v[2:3], v[2:3], 0, v[0:1]
	v_add_co_u32_e32 v6, vcc, s67, v2
	s_waitcnt vmcnt(0) lgkmcnt(0)
	s_barrier
	s_nop 1
	v_addc_co_u32_e32 v7, vcc, 0, v3, vcc
	global_load_dwordx4 v[140:143], v[2:3], off
	global_load_dwordx4 v[136:139], v[6:7], off
	v_add_co_u32_e32 v6, vcc, s66, v2
	s_nop 1
	v_addc_co_u32_e32 v7, vcc, 0, v3, vcc
	v_add_co_u32_e32 v2, vcc, s63, v2
	s_nop 1
	v_addc_co_u32_e32 v3, vcc, 0, v3, vcc
	global_load_dwordx4 v[132:135], v[6:7], off
	global_load_dwordx4 v[128:131], v[2:3], off
	ds_read_b64_tr_b16 v[144:145], v206 offset:49152
	ds_read_b64_tr_b16 v[146:147], v206 offset:49664
	v_add_f32_e32 v250, v112, v113
	v_add_f32_e32 v251, v114, v115
	v_add_f32_e32 v252, v116, v117
	v_add_f32_e32 v253, v118, v119
	v_add_f32_e32 v250, v120, v250
	v_cvt_pk_bf16_f32 v160, v112, v113
	v_cvt_pk_bf16_f32 v161, v114, v115
	s_waitcnt lgkmcnt(9)
	v_mfma_f32_32x32x16_bf16 v[96:111], v[148:151], v[172:175], v[32:47]
	ds_read_b64_tr_b16 v[112:113], v206 offset:53248
	ds_read_b64_tr_b16 v[114:115], v206 offset:53760
	v_add_f32_e32 v251, v121, v251
	v_add_f32_e32 v252, v122, v252
	v_add_f32_e32 v253, v123, v253
	v_add_f32_e32 v250, v124, v250
	v_cvt_pk_bf16_f32 v162, v116, v117
	v_cvt_pk_bf16_f32 v163, v118, v119
	s_waitcnt lgkmcnt(10)
	v_mfma_f32_32x32x16_bf16 v[32:47], v[186:189], v[172:175], v[32:47]
	ds_read_b64_tr_b16 v[148:149], v206 offset:50176
	ds_read_b64_tr_b16 v[150:151], v206 offset:50688
	v_add_f32_e32 v251, v125, v251
	v_add_f32_e32 v252, v126, v252
	v_add_f32_e32 v253, v127, v253
	v_add_f32_e32 v250, v80, v250
	v_cvt_pk_bf16_f32 v10, v120, v121
	v_cvt_pk_bf16_f32 v11, v122, v123
	s_waitcnt lgkmcnt(11)
	v_mfma_f32_32x32x16_bf16 v[96:111], v[190:193], v[176:179], v[96:111]
	ds_read_b64_tr_b16 v[116:117], v206 offset:54272
	ds_read_b64_tr_b16 v[118:119], v206 offset:54784
	v_add_f32_e32 v251, v81, v251
	v_add_f32_e32 v252, v82, v252
	v_add_f32_e32 v253, v83, v253
	v_add_f32_e32 v250, v84, v250
	v_cvt_pk_bf16_f32 v12, v124, v125
	v_cvt_pk_bf16_f32 v13, v126, v127
	s_waitcnt lgkmcnt(12)
	v_mfma_f32_32x32x16_bf16 v[32:47], v[194:197], v[176:179], v[32:47]
	ds_read_b64_tr_b16 v[120:121], v206 offset:51200
	ds_read_b64_tr_b16 v[122:123], v206 offset:51712
	v_add_f32_e32 v251, v85, v251
	v_add_f32_e32 v252, v86, v252
	v_add_f32_e32 v253, v87, v253
	v_add_f32_e32 v250, v88, v250
	v_cvt_pk_bf16_f32 v6, v80, v81
	v_cvt_pk_bf16_f32 v7, v82, v83
	s_waitcnt lgkmcnt(13)
	v_mfma_f32_32x32x16_bf16 v[96:111], v[210:213], v[168:171], v[96:111]
	ds_read_b64_tr_b16 v[80:81], v206 offset:55296
	ds_read_b64_tr_b16 v[82:83], v206 offset:55808
	v_add_f32_e32 v251, v89, v251
	v_add_f32_e32 v252, v90, v252
	v_add_f32_e32 v253, v91, v253
	v_add_f32_e32 v250, v92, v250
	v_cvt_pk_bf16_f32 v8, v84, v85
	v_cvt_pk_bf16_f32 v9, v86, v87
	s_waitcnt lgkmcnt(14)
	v_mfma_f32_32x32x16_bf16 v[32:47], v[180:183], v[168:171], v[32:47]
	ds_read_b64_tr_b16 v[124:125], v206 offset:52224
	ds_read_b64_tr_b16 v[126:127], v206 offset:52736
	v_add_f32_e32 v251, v93, v251
	v_add_f32_e32 v252, v94, v252
	v_add_f32_e32 v253, v95, v253
	v_add_f32_e32 v250, v251, v250
	v_cvt_pk_bf16_f32 v2, v88, v89
	v_cvt_pk_bf16_f32 v3, v90, v91
	s_waitcnt lgkmcnt(14)
	v_mfma_f32_32x32x16_bf16 v[96:111], v[156:159], v[164:167], v[96:111]
	ds_read_b64_tr_b16 v[84:85], v206 offset:56320
	ds_read_b64_tr_b16 v[86:87], v206 offset:56832
	v_add_f32_e32 v252, v253, v252
	v_add_f32_e32 v88, v252, v250
	v_cvt_pk_bf16_f32 v4, v92, v93
	v_cvt_pk_bf16_f32 v5, v94, v95
	v_mfma_f32_32x32x16_bf16 v[32:47], v[152:155], v[164:167], v[32:47]
	s_nop 4
	v_exp_f32_e32 v96, v96
	v_exp_f32_e32 v97, v97
	v_exp_f32_e32 v98, v98
	v_exp_f32_e32 v99, v99
	s_nop 0
	v_exp_f32_e32 v100, v100
	v_exp_f32_e32 v101, v101
	v_exp_f32_e32 v102, v102
	v_exp_f32_e32 v103, v103
	s_nop 0
	v_exp_f32_e32 v104, v104
	v_exp_f32_e32 v105, v105
	v_exp_f32_e32 v106, v106
	v_exp_f32_e32 v107, v107
	s_nop 0
	v_exp_f32_e32 v108, v108
	v_exp_f32_e32 v109, v109
	v_exp_f32_e32 v110, v110
	v_exp_f32_e32 v111, v111
	v_exp_f32_e32 v32, v32
	v_exp_f32_e32 v33, v33
	v_exp_f32_e32 v34, v34
	v_exp_f32_e32 v35, v35
	s_nop 0
	v_exp_f32_e32 v36, v36
	v_exp_f32_e32 v37, v37
	v_exp_f32_e32 v38, v38
	v_exp_f32_e32 v39, v39
	s_nop 0
	v_exp_f32_e32 v40, v40
	v_exp_f32_e32 v41, v41
	v_exp_f32_e32 v42, v42
	v_exp_f32_e32 v43, v43
	s_nop 0
	v_exp_f32_e32 v44, v44
	v_exp_f32_e32 v45, v45
	v_exp_f32_e32 v46, v46
	v_exp_f32_e32 v47, v47
	s_waitcnt lgkmcnt(14)
	v_mfma_f32_32x32x16_bf16 v[48:63], v[160:163], v[144:147], v[48:63]
	v_add_f32_e32 v250, v96, v97
	v_add_f32_e32 v251, v98, v99
	v_add_f32_e32 v252, v100, v101
	v_add_f32_e32 v253, v102, v103
	v_add_f32_e32 v250, v104, v250
	v_add_f32_e32 v251, v105, v251
	v_add_f32_e32 v252, v106, v252
	s_waitcnt lgkmcnt(12)
	v_mfma_f32_32x32x16_bf16 v[64:79], v[160:163], v[112:115], v[64:79]
	v_add_f32_e32 v253, v107, v253
	v_add_f32_e32 v250, v108, v250
	v_add_f32_e32 v251, v109, v251
	v_add_f32_e32 v252, v110, v252
	v_add_f32_e32 v253, v111, v253
	v_add_f32_e32 v250, v32, v250
	v_add_f32_e32 v251, v33, v251
	s_waitcnt lgkmcnt(10)
	v_mfma_f32_32x32x16_bf16 v[48:63], v[10:13], v[148:151], v[48:63]
	v_add_f32_e32 v252, v34, v252
	v_add_f32_e32 v253, v35, v253
	v_add_f32_e32 v250, v36, v250
	v_add_f32_e32 v251, v37, v251
	v_add_f32_e32 v252, v38, v252
	v_add_f32_e32 v253, v39, v253
	v_add_f32_e32 v250, v40, v250
	s_waitcnt lgkmcnt(8)
	v_mfma_f32_32x32x16_bf16 v[64:79], v[10:13], v[116:119], v[64:79]
	v_add_f32_e32 v251, v41, v251
	v_add_f32_e32 v252, v42, v252
	v_add_f32_e32 v253, v43, v253
	v_add_f32_e32 v250, v44, v250
	v_add_f32_e32 v251, v45, v251
	v_add_f32_e32 v252, v46, v252
	v_add_f32_e32 v253, v47, v253
	s_waitcnt lgkmcnt(6)
	v_mfma_f32_32x32x16_bf16 v[48:63], v[6:9], v[120:123], v[48:63]
	v_add_f32_e32 v250, v251, v250
	v_add_f32_e32 v252, v253, v252
	v_add_f32_e32 v89, v252, v250
	v_add_f32_e32 v88, v185, v88
	v_add_f32_e32 v88, v88, v89
	v_cvt_pk_bf16_f32 v90, v96, v97
	v_cvt_pk_bf16_f32 v91, v98, v99
	s_waitcnt lgkmcnt(4)
	v_mfma_f32_32x32x16_bf16 v[64:79], v[6:9], v[80:83], v[64:79]
	v_cvt_pk_bf16_f32 v92, v100, v101
	v_cvt_pk_bf16_f32 v93, v102, v103
	v_cvt_pk_bf16_f32 v10, v104, v105
	v_cvt_pk_bf16_f32 v11, v106, v107
	v_cvt_pk_bf16_f32 v12, v108, v109
	v_cvt_pk_bf16_f32 v13, v110, v111
	v_cvt_pk_bf16_f32 v6, v32, v33
	s_waitcnt lgkmcnt(2)
	v_mfma_f32_32x32x16_bf16 v[48:63], v[2:5], v[124:127], v[48:63]
	v_cvt_pk_bf16_f32 v7, v34, v35
	v_cvt_pk_bf16_f32 v8, v36, v37
	v_cvt_pk_bf16_f32 v9, v38, v39
	v_cvt_pk_bf16_f32 v32, v40, v41
	v_cvt_pk_bf16_f32 v33, v42, v43
	v_cvt_pk_bf16_f32 v34, v44, v45
	v_cvt_pk_bf16_f32 v35, v46, v47
	s_waitcnt lgkmcnt(0)
	v_mfma_f32_32x32x16_bf16 v[64:79], v[2:5], v[84:87], v[64:79]
	v_add_u32_e32 v2, s6, v204
	v_add3_u32 v84, v2, v202, v205
	ds_read_b64_tr_b16 v[2:3],v84 offset:0
	ds_read_b64_tr_b16 v[4:5],v84 offset:512
	ds_read_b64_tr_b16 v[36:37],v84 offset:1024
	ds_read_b64_tr_b16 v[38:39],v84 offset:1536
	ds_read_b64_tr_b16 v[40:41],v84 offset:2048
	ds_read_b64_tr_b16 v[42:43],v84 offset:2560
	ds_read_b64_tr_b16 v[44:45],v84 offset:3072
	ds_read_b64_tr_b16 v[46:47],v84 offset:3584
	s_waitcnt lgkmcnt(0)
	s_nop 0
	v_mfma_f32_32x32x16_bf16 v[48:63], v[90:93], v[2:5], v[48:63]
	ds_read_b64_tr_b16 v[2:3],v84 offset:4096
	ds_read_b64_tr_b16 v[4:5],v84 offset:4608
	v_mfma_f32_32x32x16_bf16 v[48:63], v[10:13], v[36:39], v[48:63]
	ds_read_b64_tr_b16 v[36:37],v84 offset:5120
	ds_read_b64_tr_b16 v[38:39],v84 offset:5632
	v_mfma_f32_32x32x16_bf16 v[48:63], v[6:9], v[40:43], v[48:63]
	ds_read_b64_tr_b16 v[40:41],v84 offset:6144
	ds_read_b64_tr_b16 v[42:43],v84 offset:6656
	ds_read_b64_tr_b16 v[80:81],v84 offset:7168
	ds_read_b64_tr_b16 v[82:83],v84 offset:7680
	s_waitcnt lgkmcnt(0)
	v_mfma_f32_32x32x16_bf16 v[48:63], v[32:35], v[44:47], v[48:63]
	v_mfma_f32_32x32x16_bf16 v[64:79], v[90:93], v[2:5], v[64:79]
	v_mov_b32_e32 v2, v88
	s_nop 1
	v_permlane32_swap_b32_e32 v88, v2
	v_cmp_gt_u32_e32 vcc, 32, v203
	v_mfma_f32_32x32x16_bf16 v[64:79], v[10:13], v[36:39], v[64:79]
	v_mfma_f32_32x32x16_bf16 v[64:79], v[6:9], v[40:43], v[64:79]
	v_mfma_f32_32x32x16_bf16 v[64:79], v[32:35], v[80:83], v[64:79]
	s_and_saveexec_b64 s[6:7], vcc
	v_lshl_add_u32 v3, v200, 2, s31
	v_add_f32_e32 v2, v88, v2
	ds_write_b32 v3, v2 offset:128
	s_or_b64 exec, exec, s[6:7]
	s_waitcnt lgkmcnt(0)
	v_lshl_add_u32 v10, v201, 4, s31
	ds_read_b128 v[2:5], v10 offset:128
	ds_read_b128 v[6:9], v10 offset:160
	s_lshl_b32 s6, s27, 12
	s_add_i32 s6, s6, 0
	s_add_i32 s6, s6, 0x10800
	s_waitcnt lgkmcnt(1)
	v_rcp_f32_e32 v11, v2
	v_rcp_f32_e32 v12, v3
	v_rcp_f32_e32 v13, v4
	v_rcp_f32_e32 v32, v5
	s_waitcnt lgkmcnt(0)
	v_rcp_f32_e32 v33, v6
	ds_read_b128 v[2:5], v10 offset:192
	v_rcp_f32_e32 v34, v7
	v_rcp_f32_e32 v35, v8
	v_rcp_f32_e32 v36, v9
	ds_read_b128 v[6:9], v10 offset:224
	v_lshlrev_b32_e32 v10, 9, v201
	v_lshlrev_b32_e32 v37, 1, v200
	v_add3_u32 v10, s6, v10, v37
	v_mul_f32_e32 v37, v48, v11
	v_mul_f32_e32 v11, v64, v11
	v_cvt_pk_bf16_f32 v11, v11, s0
	ds_write_b16 v10, v11 offset:64
	v_mul_f32_e32 v11, v49, v12
	v_cvt_pk_bf16_f32 v11, v11, s0
	ds_write_b16 v10, v11 offset:128
	v_mul_f32_e32 v11, v65, v12
	v_cvt_pk_bf16_f32 v11, v11, s0
	ds_write_b16 v10, v11 offset:192
	v_mul_f32_e32 v11, v50, v13
	v_cvt_pk_bf16_f32 v11, v11, s0
	ds_write_b16 v10, v11 offset:256
	v_mul_f32_e32 v11, v66, v13
	v_cvt_pk_bf16_f32 v11, v11, s0
	ds_write_b16 v10, v11 offset:320
	v_mul_f32_e32 v11, v51, v32
	v_cvt_pk_bf16_f32 v11, v11, s0
	ds_write_b16 v10, v11 offset:384
	v_mul_f32_e32 v11, v67, v32
	v_cvt_pk_bf16_f32 v11, v11, s0
	ds_write_b16 v10, v11 offset:448
	v_mul_f32_e32 v11, v52, v33
	v_cvt_pk_bf16_f32 v11, v11, s0
	ds_write_b16 v10, v11 offset:1024
	v_mul_f32_e32 v11, v68, v33
	v_cvt_pk_bf16_f32 v11, v11, s0
	ds_write_b16 v10, v11 offset:1088
	v_mul_f32_e32 v11, v53, v34
	v_cvt_pk_bf16_f32 v11, v11, s0
	ds_write_b16 v10, v11 offset:1152
	v_mul_f32_e32 v11, v69, v34
	v_cvt_pk_bf16_f32 v11, v11, s0
	ds_write_b16 v10, v11 offset:1216
	v_mul_f32_e32 v11, v54, v35
	v_cvt_pk_bf16_f32 v11, v11, s0
	ds_write_b16 v10, v11 offset:1280
	v_mul_f32_e32 v11, v70, v35
	v_cvt_pk_bf16_f32 v11, v11, s0
	s_waitcnt lgkmcnt(13)
	v_rcp_f32_e32 v2, v2
	ds_write_b16 v10, v11 offset:1344
	v_mul_f32_e32 v11, v55, v36
	v_cvt_pk_bf16_f32 v11, v11, s0
	v_rcp_f32_e32 v3, v3
	ds_write_b16 v10, v11 offset:1408
	v_mul_f32_e32 v11, v71, v36
	v_cvt_pk_bf16_f32 v11, v11, s0
	ds_write_b16 v10, v11 offset:1472
	v_mul_f32_e32 v11, v56, v2
	v_mul_f32_e32 v2, v72, v2
	v_cvt_pk_bf16_f32 v2, v2, s0
	v_rcp_f32_e32 v4, v4
	ds_write_b16 v10, v2 offset:2112
	v_mul_f32_e32 v2, v57, v3
	v_cvt_pk_bf16_f32 v2, v2, s0
	ds_write_b16 v10, v2 offset:2176
	v_mul_f32_e32 v2, v73, v3
	v_cvt_pk_bf16_f32 v2, v2, s0
	v_rcp_f32_e32 v5, v5
	ds_write_b16 v10, v2 offset:2240
	v_mul_f32_e32 v2, v58, v4
	v_cvt_pk_bf16_f32 v2, v2, s0
	ds_write_b16 v10, v2 offset:2304
	v_mul_f32_e32 v2, v74, v4
	v_cvt_pk_bf16_f32 v2, v2, s0
	s_waitcnt lgkmcnt(14)
	v_rcp_f32_e32 v6, v6
	ds_write_b16 v10, v2 offset:2368
	v_mul_f32_e32 v2, v59, v5
	v_cvt_pk_bf16_f32 v2, v2, s0
	ds_write_b16 v10, v2 offset:2432
	v_mul_f32_e32 v2, v75, v5
	v_cvt_pk_bf16_f32 v2, v2, s0
	v_rcp_f32_e32 v7, v7
	ds_write_b16 v10, v2 offset:2496
	v_mul_f32_e32 v2, v60, v6
	v_cvt_pk_bf16_f32 v2, v2, s0
	ds_write_b16 v10, v2 offset:3072
	v_mul_f32_e32 v2, v76, v6
	v_cvt_pk_bf16_f32 v2, v2, s0
	v_rcp_f32_e32 v8, v8
	ds_write_b16 v10, v2 offset:3136
	v_mul_f32_e32 v2, v61, v7
	v_cvt_pk_bf16_f32 v2, v2, s0
	ds_write_b16 v10, v2 offset:3200
	v_mul_f32_e32 v2, v77, v7
	v_cvt_pk_bf16_f32 v2, v2, s0
	v_rcp_f32_e32 v9, v9
	ds_write_b16 v10, v2 offset:3264
	v_mul_f32_e32 v2, v62, v8
	v_cvt_pk_bf16_f32 v2, v2, s0
	ds_write_b16 v10, v2 offset:3328
	v_mul_f32_e32 v2, v78, v8
	v_cvt_pk_bf16_f32 v2, v2, s0
	ds_write_b16 v10, v2 offset:3392
	v_mul_f32_e32 v2, v63, v9
	s_waitcnt vmcnt(3)
	v_lshlrev_b32_e32 v12, 16, v140
	v_cvt_pk_bf16_f32 v2, v2, s0
	v_and_b32_e32 v13, 0xffff0000, v140
	v_mul_f32_e32 v4, 0xbfb8aa3b, v12
	ds_write_b16 v10, v2 offset:3456
	v_mul_f32_e32 v2, v79, v9
	v_exp_f32_e32 v8, v4
	v_mul_f32_e32 v4, 0xbfb8aa3b, v13
	v_cvt_pk_bf16_f32 v37, v37, s0
	v_cvt_pk_bf16_f32 v11, v11, s0
	v_cvt_pk_bf16_f32 v2, v2, s0
	v_add_u32_e32 v36, s6, v0
	s_add_u32 s6, s50, s8
	v_exp_f32_e32 v9, v4
	ds_write_b16 v10, v37
	ds_write_b16 v10, v11 offset:2048
	ds_write_b16 v10, v2 offset:3520
	s_addc_u32 s7, s51, 0
	s_waitcnt lgkmcnt(0)
	v_lshl_add_u64 v[2:3], s[6:7], 0, v[0:1]
	v_lshl_add_u32 v0, v184, 7, v36
	ds_read_b128 v[4:7], v0
	v_add_f32_e32 v0, 1.0, v8
	v_rcp_f32_e32 v32, v0
	v_add_f32_e32 v0, 1.0, v9
	v_rcp_f32_e32 v33, v0
	s_waitcnt lgkmcnt(0)
	v_lshlrev_b32_e32 v34, 16, v4
	v_and_b32_e32 v35, 0xffff0000, v4
	v_or_b32_e32 v0, 8, v184
	v_pk_mul_f32 v[12:13], v[32:33], v[12:13]
	v_lshlrev_b32_e32 v32, 16, v141
	v_and_b32_e32 v33, 0xffff0000, v141
	v_mul_f32_e32 v4, 0xbfb8aa3b, v32
	v_exp_f32_e32 v4, v4
	v_mul_f32_e32 v37, 0xbfb8aa3b, v33
	v_exp_f32_e32 v37, v37
	v_pk_mul_f32 v[12:13], v[12:13], v[34:35]
	v_add_f32_e32 v4, 1.0, v4
	v_rcp_f32_e32 v34, v4
	v_add_f32_e32 v4, 1.0, v37
	v_rcp_f32_e32 v35, v4
	v_cvt_pk_bf16_f32 v4, v12, v13
	v_lshlrev_b32_e32 v12, 16, v5
	v_and_b32_e32 v13, 0xffff0000, v5
	v_pk_mul_f32 v[32:33], v[34:35], v[32:33]
	v_lshlrev_b32_e32 v34, 16, v142
	v_and_b32_e32 v35, 0xffff0000, v142
	v_mul_f32_e32 v5, 0xbfb8aa3b, v34
	v_exp_f32_e32 v5, v5
	v_mul_f32_e32 v37, 0xbfb8aa3b, v35
	v_exp_f32_e32 v37, v37
	v_pk_mul_f32 v[12:13], v[32:33], v[12:13]
	v_add_f32_e32 v5, 1.0, v5
	v_rcp_f32_e32 v32, v5
	v_add_f32_e32 v5, 1.0, v37
	v_rcp_f32_e32 v33, v5
	v_cvt_pk_bf16_f32 v5, v12, v13
	v_lshlrev_b32_e32 v12, 16, v6
	v_and_b32_e32 v13, 0xffff0000, v6
	v_pk_mul_f32 v[32:33], v[32:33], v[34:35]
	v_lshlrev_b32_e32 v34, 16, v143
	v_and_b32_e32 v35, 0xffff0000, v143
	v_mul_f32_e32 v6, 0xbfb8aa3b, v34
	v_exp_f32_e32 v6, v6
	v_mul_f32_e32 v37, 0xbfb8aa3b, v35
	v_exp_f32_e32 v37, v37
	v_pk_mul_f32 v[12:13], v[32:33], v[12:13]
	v_add_f32_e32 v6, 1.0, v6
	v_rcp_f32_e32 v32, v6
	v_add_f32_e32 v6, 1.0, v37
	v_rcp_f32_e32 v33, v6
	v_cvt_pk_bf16_f32 v6, v12, v13
	v_lshlrev_b32_e32 v12, 16, v7
	v_and_b32_e32 v13, 0xffff0000, v7
	v_pk_mul_f32 v[32:33], v[32:33], v[34:35]
	v_lshl_add_u32 v8, v0, 7, v36
	v_pk_mul_f32 v[12:13], v[32:33], v[12:13]
	ds_read_b128 v[8:11], v8
	v_cvt_pk_bf16_f32 v7, v12, v13
	v_lshl_add_u64 v[12:13], v[2:3], 0, v[14:15]
	global_store_dwordx4 v[12:13], v[4:7], off
	s_waitcnt lgkmcnt(0)
	v_lshlrev_b32_e32 v14, 16, v8
	s_waitcnt vmcnt(3)
	v_lshlrev_b32_e32 v6, 16, v136
	v_and_b32_e32 v7, 0xffff0000, v136
	v_mul_f32_e32 v4, 0xbfb8aa3b, v6
	v_exp_f32_e32 v5, v4
	v_mul_f32_e32 v4, 0xbfb8aa3b, v7
	v_exp_f32_e32 v13, v4
	v_or_b32_e32 v4, s4, v0
	v_add_f32_e32 v0, 1.0, v5
	v_rcp_f32_e32 v12, v0
	v_add_f32_e32 v0, 1.0, v13
	v_rcp_f32_e32 v13, v0
	v_and_b32_e32 v15, 0xffff0000, v8
	v_mov_b32_e32 v5, s5
	v_pk_mul_f32 v[6:7], v[12:13], v[6:7]
	v_lshlrev_b32_e32 v12, 16, v137
	v_and_b32_e32 v13, 0xffff0000, v137
	v_mul_f32_e32 v0, 0xbfb8aa3b, v12
	v_exp_f32_e32 v0, v0
	v_mul_f32_e32 v8, 0xbfb8aa3b, v13
	v_exp_f32_e32 v8, v8
	v_pk_mul_f32 v[6:7], v[6:7], v[14:15]
	v_add_f32_e32 v0, 1.0, v0
	v_rcp_f32_e32 v14, v0
	v_add_f32_e32 v0, 1.0, v8
	v_rcp_f32_e32 v15, v0
	v_cvt_pk_bf16_f32 v6, v6, v7
	v_lshlrev_b32_e32 v8, 16, v9
	v_and_b32_e32 v9, 0xffff0000, v9
	v_pk_mul_f32 v[12:13], v[14:15], v[12:13]
	v_lshlrev_b32_e32 v14, 16, v138
	v_and_b32_e32 v15, 0xffff0000, v138
	v_mul_f32_e32 v0, 0xbfb8aa3b, v14
	v_exp_f32_e32 v0, v0
	v_mul_f32_e32 v7, 0xbfb8aa3b, v15
	v_exp_f32_e32 v7, v7
	v_pk_mul_f32 v[8:9], v[12:13], v[8:9]
	v_add_f32_e32 v0, 1.0, v0
	v_rcp_f32_e32 v12, v0
	v_add_f32_e32 v0, 1.0, v7
	v_rcp_f32_e32 v13, v0
	v_cvt_pk_bf16_f32 v7, v8, v9
	v_lshlrev_b32_e32 v8, 16, v10
	v_and_b32_e32 v9, 0xffff0000, v10
	v_pk_mul_f32 v[12:13], v[12:13], v[14:15]
	v_lshlrev_b32_e32 v14, 16, v139
	v_and_b32_e32 v15, 0xffff0000, v139
	v_mul_f32_e32 v0, 0xbfb8aa3b, v14
	v_exp_f32_e32 v0, v0
	v_mul_f32_e32 v10, 0xbfb8aa3b, v15
	v_exp_f32_e32 v10, v10
	v_pk_mul_f32 v[8:9], v[12:13], v[8:9]
	v_add_f32_e32 v0, 1.0, v0
	v_rcp_f32_e32 v12, v0
	v_add_f32_e32 v0, 1.0, v10
	v_rcp_f32_e32 v13, v0
	v_lshlrev_b32_e32 v10, 16, v11
	v_and_b32_e32 v11, 0xffff0000, v11
	v_cvt_pk_bf16_f32 v8, v8, v9
	v_pk_mul_f32 v[12:13], v[12:13], v[14:15]
	v_or_b32_e32 v0, 16, v184
	v_pk_mul_f32 v[10:11], v[12:13], v[10:11]
	s_waitcnt vmcnt(2)
	v_lshlrev_b32_e32 v14, 16, v132
	v_cvt_pk_bf16_f32 v9, v10, v11
	v_lshlrev_b64 v[10:11], 11, v[4:5]
	v_lshl_add_u64 v[10:11], v[2:3], 0, v[10:11]
	v_lshl_add_u32 v4, v0, 7, v36
	global_store_dwordx4 v[10:11], v[6:9], off
	ds_read_b128 v[6:9], v4
	v_and_b32_e32 v15, 0xffff0000, v132
	v_mul_f32_e32 v4, 0xbfb8aa3b, v14
	v_exp_f32_e32 v10, v4
	v_mul_f32_e32 v4, 0xbfb8aa3b, v15
	v_exp_f32_e32 v11, v4
	v_or_b32_e32 v4, s4, v0
	v_add_f32_e32 v0, 1.0, v10
	v_rcp_f32_e32 v32, v0
	v_add_f32_e32 v0, 1.0, v11
	v_rcp_f32_e32 v33, v0
	v_or_b32_e32 v0, 24, v184
	s_waitcnt lgkmcnt(0)
	v_lshlrev_b32_e32 v34, 16, v6
	v_and_b32_e32 v35, 0xffff0000, v6
	v_pk_mul_f32 v[14:15], v[32:33], v[14:15]
	v_lshlrev_b32_e32 v32, 16, v133
	v_and_b32_e32 v33, 0xffff0000, v133
	v_mul_f32_e32 v6, 0xbfb8aa3b, v32
	v_lshl_add_u32 v10, v0, 7, v36
	v_exp_f32_e32 v6, v6
	v_mul_f32_e32 v36, 0xbfb8aa3b, v33
	v_exp_f32_e32 v36, v36
	v_pk_mul_f32 v[14:15], v[14:15], v[34:35]
	v_add_f32_e32 v6, 1.0, v6
	v_rcp_f32_e32 v34, v6
	v_add_f32_e32 v6, 1.0, v36
	v_rcp_f32_e32 v35, v6
	v_cvt_pk_bf16_f32 v6, v14, v15
	v_lshlrev_b32_e32 v14, 16, v7
	v_and_b32_e32 v15, 0xffff0000, v7
	v_pk_mul_f32 v[32:33], v[34:35], v[32:33]
	v_lshlrev_b32_e32 v34, 16, v134
	v_and_b32_e32 v35, 0xffff0000, v134
	v_mul_f32_e32 v7, 0xbfb8aa3b, v34
	v_exp_f32_e32 v7, v7
	v_mul_f32_e32 v36, 0xbfb8aa3b, v35
	v_exp_f32_e32 v36, v36
	v_pk_mul_f32 v[14:15], v[32:33], v[14:15]
	v_add_f32_e32 v7, 1.0, v7
	v_rcp_f32_e32 v32, v7
	v_add_f32_e32 v7, 1.0, v36
	v_rcp_f32_e32 v33, v7
	v_cvt_pk_bf16_f32 v7, v14, v15
	v_lshlrev_b32_e32 v14, 16, v8
	v_and_b32_e32 v15, 0xffff0000, v8
	v_pk_mul_f32 v[32:33], v[32:33], v[34:35]
	v_lshlrev_b32_e32 v34, 16, v135
	v_and_b32_e32 v35, 0xffff0000, v135
	v_mul_f32_e32 v8, 0xbfb8aa3b, v34
	v_exp_f32_e32 v8, v8
	v_mul_f32_e32 v36, 0xbfb8aa3b, v35
	v_exp_f32_e32 v36, v36
	v_pk_mul_f32 v[14:15], v[32:33], v[14:15]
	v_add_f32_e32 v8, 1.0, v8
	v_rcp_f32_e32 v32, v8
	v_add_f32_e32 v8, 1.0, v36
	v_rcp_f32_e32 v33, v8
	v_cvt_pk_bf16_f32 v8, v14, v15
	v_lshlrev_b32_e32 v14, 16, v9
	v_and_b32_e32 v15, 0xffff0000, v9
	v_pk_mul_f32 v[32:33], v[32:33], v[34:35]
	ds_read_b128 v[10:13], v10
	v_pk_mul_f32 v[14:15], v[32:33], v[14:15]
	s_waitcnt vmcnt(2)
	v_lshlrev_b32_e32 v32, 16, v128
	v_cvt_pk_bf16_f32 v9, v14, v15
	v_lshlrev_b64 v[14:15], 11, v[4:5]
	v_and_b32_e32 v33, 0xffff0000, v128
	v_mul_f32_e32 v4, 0xbfb8aa3b, v32
	v_exp_f32_e32 v4, v4
	v_mul_f32_e32 v34, 0xbfb8aa3b, v33
	v_exp_f32_e32 v34, v34
	v_lshl_add_u64 v[14:15], v[2:3], 0, v[14:15]
	v_add_f32_e32 v4, 1.0, v4
	global_store_dwordx4 v[14:15], v[6:9], off
	v_lshlrev_b32_e32 v14, 16, v129
	v_and_b32_e32 v15, 0xffff0000, v129
	v_rcp_f32_e32 v6, v4
	v_add_f32_e32 v4, 1.0, v34
	v_rcp_f32_e32 v7, v4
	v_or_b32_e32 v4, s4, v0
	v_mul_f32_e32 v0, 0xbfb8aa3b, v14
	s_waitcnt lgkmcnt(0)
	v_lshlrev_b32_e32 v8, 16, v10
	v_and_b32_e32 v9, 0xffff0000, v10
	v_exp_f32_e32 v0, v0
	v_mul_f32_e32 v10, 0xbfb8aa3b, v15
	v_exp_f32_e32 v10, v10
	v_pk_mul_f32 v[6:7], v[6:7], v[32:33]
	v_add_f32_e32 v0, 1.0, v0
	v_pk_mul_f32 v[6:7], v[6:7], v[8:9]
	v_rcp_f32_e32 v8, v0
	v_add_f32_e32 v0, 1.0, v10
	v_rcp_f32_e32 v9, v0
	v_cvt_pk_bf16_f32 v6, v6, v7
	v_lshlrev_b32_e32 v10, 16, v11
	v_and_b32_e32 v11, 0xffff0000, v11
	v_pk_mul_f32 v[8:9], v[8:9], v[14:15]
	v_lshlrev_b32_e32 v14, 16, v130
	v_and_b32_e32 v15, 0xffff0000, v130
	v_mul_f32_e32 v0, 0xbfb8aa3b, v14
	v_exp_f32_e32 v0, v0
	v_mul_f32_e32 v7, 0xbfb8aa3b, v15
	v_exp_f32_e32 v7, v7
	v_pk_mul_f32 v[8:9], v[8:9], v[10:11]
	v_add_f32_e32 v0, 1.0, v0
	v_rcp_f32_e32 v10, v0
	v_add_f32_e32 v0, 1.0, v7
	v_rcp_f32_e32 v11, v0
	v_cvt_pk_bf16_f32 v7, v8, v9
	v_lshlrev_b32_e32 v8, 16, v12
	v_and_b32_e32 v9, 0xffff0000, v12
	v_pk_mul_f32 v[10:11], v[10:11], v[14:15]
	v_lshlrev_b32_e32 v14, 16, v131
	v_and_b32_e32 v15, 0xffff0000, v131
	v_mul_f32_e32 v0, 0xbfb8aa3b, v14
	v_exp_f32_e32 v0, v0
	v_mul_f32_e32 v12, 0xbfb8aa3b, v15
	v_exp_f32_e32 v12, v12
	v_pk_mul_f32 v[8:9], v[10:11], v[8:9]
	v_add_f32_e32 v0, 1.0, v0
	v_rcp_f32_e32 v10, v0
	v_add_f32_e32 v0, 1.0, v12
	v_rcp_f32_e32 v11, v0
	v_lshlrev_b32_e32 v12, 16, v13
	v_and_b32_e32 v13, 0xffff0000, v13
	v_lshlrev_b64 v[4:5], 11, v[4:5]
	v_pk_mul_f32 v[10:11], v[10:11], v[14:15]
	v_cvt_pk_bf16_f32 v8, v8, v9
	v_pk_mul_f32 v[10:11], v[10:11], v[12:13]
	v_lshl_add_u64 v[2:3], v[2:3], 0, v[4:5]
	v_cvt_pk_bf16_f32 v9, v10, v11
	global_store_dwordx4 v[2:3], v[6:9], off
	s_waitcnt vmcnt(0) lgkmcnt(0)
	s_barrier
	s_mov_b64 s[4:5], 0

.LBB0_1319:
	s_mov_b32 s20, s42
	s_mov_b32 s21, s31
	v_add_u32_e32 v208, s21, v222
	ds_read_b64_tr_b16 v[196:197], v208 offset:32768
	ds_read_b64_tr_b16 v[198:199], v208 offset:33280
	s_waitcnt lgkmcnt(9)
	v_mfma_f32_32x32x16_bf16 v[128:143], v[112:115], v[172:175], v[64:79]
	v_add_f32_e32 v250, v96, v97
	v_add_f32_e32 v251, v98, v99
	v_add_f32_e32 v252, v100, v101
	v_add_f32_e32 v253, v102, v103
	v_add_f32_e32 v250, v104, v250
	v_cvt_pk_bf16_f32 v176, v96, v97
	v_cvt_pk_bf16_f32 v177, v98, v99
	ds_read_b64_tr_b16 v[192:193], v208 offset:36864
	ds_read_b64_tr_b16 v[194:195], v208 offset:37376
	s_waitcnt lgkmcnt(10)
	v_mfma_f32_32x32x16_bf16 v[112:127], v[188:191], v[172:175], v[64:79]
	v_add_f32_e32 v251, v105, v251
	v_add_f32_e32 v252, v106, v252
	v_add_f32_e32 v253, v107, v253
	v_add_f32_e32 v250, v108, v250
	v_cvt_pk_bf16_f32 v178, v100, v101
	v_cvt_pk_bf16_f32 v179, v102, v103
	ds_read_b64_tr_b16 v[96:97], v208 offset:33792
	ds_read_b64_tr_b16 v[98:99], v208 offset:34304
	s_waitcnt lgkmcnt(11)
	v_mfma_f32_32x32x16_bf16 v[128:143], v[184:187], v[168:171], v[128:143]
	v_add_f32_e32 v251, v109, v251
	v_add_f32_e32 v252, v110, v252
	v_add_f32_e32 v253, v111, v253
	v_add_f32_e32 v250, v80, v250
	v_cvt_pk_bf16_f32 v164, v104, v105
	v_cvt_pk_bf16_f32 v165, v106, v107
	ds_read_b64_tr_b16 v[100:101], v208 offset:37888
	ds_read_b64_tr_b16 v[102:103], v208 offset:38400
	s_waitcnt lgkmcnt(12)
	v_mfma_f32_32x32x16_bf16 v[112:127], v[180:183], v[168:171], v[112:127]
	v_add_f32_e32 v251, v81, v251
	v_add_f32_e32 v252, v82, v252
	v_add_f32_e32 v253, v83, v253
	v_add_f32_e32 v250, v84, v250
	v_cvt_pk_bf16_f32 v166, v108, v109
	v_cvt_pk_bf16_f32 v167, v110, v111
	ds_read_b64_tr_b16 v[104:105], v208 offset:34816
	ds_read_b64_tr_b16 v[106:107], v208 offset:35328
	s_waitcnt lgkmcnt(13)
	v_mfma_f32_32x32x16_bf16 v[128:143], v[156:159], v[10:13], v[128:143]
	v_add_f32_e32 v251, v85, v251
	v_add_f32_e32 v252, v86, v252
	v_add_f32_e32 v253, v87, v253
	v_add_f32_e32 v250, v88, v250
	v_cvt_pk_bf16_f32 v160, v80, v81
	v_cvt_pk_bf16_f32 v161, v82, v83
	ds_read_b64_tr_b16 v[80:81], v208 offset:38912
	ds_read_b64_tr_b16 v[82:83], v208 offset:39424
	s_waitcnt lgkmcnt(14)
	v_mfma_f32_32x32x16_bf16 v[112:127], v[152:155], v[10:13], v[112:127]
	v_add_f32_e32 v251, v89, v251
	v_add_f32_e32 v252, v90, v252
	v_add_f32_e32 v253, v91, v253
	v_add_f32_e32 v250, v92, v250
	v_cvt_pk_bf16_f32 v162, v84, v85
	v_cvt_pk_bf16_f32 v163, v86, v87
	ds_read_b64_tr_b16 v[84:85], v208 offset:35840
	ds_read_b64_tr_b16 v[86:87], v208 offset:36352
	s_waitcnt lgkmcnt(14)
	v_mfma_f32_32x32x16_bf16 v[128:143], v[148:151], v[2:5], v[128:143]
	v_add_f32_e32 v251, v93, v251
	v_add_f32_e32 v252, v94, v252
	v_add_f32_e32 v253, v95, v253
	v_add_f32_e32 v250, v251, v250
	v_cvt_pk_bf16_f32 v6, v88, v89
	v_cvt_pk_bf16_f32 v7, v90, v91
	ds_read_b64_tr_b16 v[88:89], v208 offset:39936
	ds_read_b64_tr_b16 v[90:91], v208 offset:40448
	v_mfma_f32_32x32x16_bf16 v[112:127], v[144:147], v[2:5], v[112:127]
	v_add_f32_e32 v252, v253, v252
	v_add_f32_e32 v108, v252, v250
	v_cvt_pk_bf16_f32 v8, v92, v93
	v_cvt_pk_bf16_f32 v9, v94, v95
	v_lshl_add_u64 v[92:93], v[204:205], 0, s[14:15]
	s_add_i32 s28, s42, s46
	s_mov_b32 s29, m0
	s_mov_b32 m0, s28
	s_nop 0
	global_load_lds_dwordx4 v[92:93], off
	s_mov_b32 m0, s29
	v_max_f32_e32 v92, v128, v128
	v_max_f32_e32 v92, 0xff800000, v92
	v_max3_f32 v93, v130, s69, v131
	s_nop 2
	v_max3_f32 v92, v92, v129, v112
	v_max3_f32 v93, v93, v114, v115
	v_max3_f32 v92, v92, v113, v132
	v_max3_f32 v93, v93, v134, v135
	v_max3_f32 v92, v92, v133, v116
	v_max3_f32 v93, v93, v118, v119
	v_max3_f32 v92, v92, v117, v136
	v_max3_f32 v93, v93, v138, v139
	v_max3_f32 v92, v92, v137, v120
	v_max3_f32 v93, v93, v122, v123
	v_max3_f32 v92, v92, v121, v140
	v_max3_f32 v93, v93, v142, v143
	v_max3_f32 v92, v92, v141, v124
	v_max3_f32 v93, v93, v126, v127
	v_max3_f32 v92, v92, v125, v93
	v_mov_b32_e32 v93, v92
	s_nop 1
	v_permlane32_swap_b32_e32 v92, v93
	v_max3_f32 v92, v92, s69, v93
	s_add_i32 s28, s62, s47
	s_mov_b32 s29, m0
	s_mov_b32 m0, s28
	s_nop 0
	global_load_lds_dwordx4 v[202:203], off
	s_mov_b32 m0, s29
	v_cmp_lt_f32_e32 vcc, s72, v92
	s_cmp_lg_u64 vcc, 0
	v_add_f32_e32 v0, v0, v108
	s_cselect_b64 s[28:29], -1, 0
	s_cbranch_vccnz .LBB0_1327

.LBB0_1322:
	v_add_u32_e32 v208, s20, v222
	ds_read_b64_tr_b16 v[148:149], v208 offset:32768
	ds_read_b64_tr_b16 v[150:151], v208 offset:33280
	s_waitcnt lgkmcnt(9)
	v_mfma_f32_32x32x16_bf16 v[96:111], v[92:95], v[172:175], v[64:79]
	v_add_f32_e32 v250, v128, v129
	v_add_f32_e32 v251, v130, v131
	v_add_f32_e32 v252, v132, v133
	v_add_f32_e32 v253, v134, v135
	v_add_f32_e32 v250, v136, v250
	v_cvt_pk_bf16_f32 v176, v128, v129
	v_cvt_pk_bf16_f32 v177, v130, v131
	ds_read_b64_tr_b16 v[144:145], v208 offset:36864
	ds_read_b64_tr_b16 v[146:147], v208 offset:37376
	s_waitcnt lgkmcnt(10)
	v_mfma_f32_32x32x16_bf16 v[80:95], v[192:195], v[172:175], v[64:79]
	v_add_f32_e32 v251, v137, v251
	v_add_f32_e32 v252, v138, v252
	v_add_f32_e32 v253, v139, v253
	v_add_f32_e32 v250, v140, v250
	v_cvt_pk_bf16_f32 v178, v132, v133
	v_cvt_pk_bf16_f32 v179, v134, v135
	ds_read_b64_tr_b16 v[128:129], v208 offset:33792
	ds_read_b64_tr_b16 v[130:131], v208 offset:34304
	s_waitcnt lgkmcnt(11)
	v_mfma_f32_32x32x16_bf16 v[96:111], v[196:199], v[168:171], v[96:111]
	v_add_f32_e32 v251, v141, v251
	v_add_f32_e32 v252, v142, v252
	v_add_f32_e32 v253, v143, v253
	v_add_f32_e32 v250, v112, v250
	v_cvt_pk_bf16_f32 v164, v136, v137
	v_cvt_pk_bf16_f32 v165, v138, v139
	ds_read_b64_tr_b16 v[132:133], v208 offset:37888
	ds_read_b64_tr_b16 v[134:135], v208 offset:38400
	s_waitcnt lgkmcnt(12)
	v_mfma_f32_32x32x16_bf16 v[80:95], v[188:191], v[168:171], v[80:95]
	v_add_f32_e32 v251, v113, v251
	v_add_f32_e32 v252, v114, v252
	v_add_f32_e32 v253, v115, v253
	v_add_f32_e32 v250, v116, v250
	v_cvt_pk_bf16_f32 v166, v140, v141
	v_cvt_pk_bf16_f32 v167, v142, v143
	ds_read_b64_tr_b16 v[136:137], v208 offset:34816
	ds_read_b64_tr_b16 v[138:139], v208 offset:35328
	s_waitcnt lgkmcnt(13)
	v_mfma_f32_32x32x16_bf16 v[96:111], v[184:187], v[10:13], v[96:111]
	v_add_f32_e32 v251, v117, v251
	v_add_f32_e32 v252, v118, v252
	v_add_f32_e32 v253, v119, v253
	v_add_f32_e32 v250, v120, v250
	v_cvt_pk_bf16_f32 v160, v112, v113
	v_cvt_pk_bf16_f32 v161, v114, v115
	ds_read_b64_tr_b16 v[140:141], v208 offset:38912
	ds_read_b64_tr_b16 v[142:143], v208 offset:39424
	s_waitcnt lgkmcnt(14)
	v_mfma_f32_32x32x16_bf16 v[80:95], v[180:183], v[10:13], v[80:95]
	v_add_f32_e32 v251, v121, v251
	v_add_f32_e32 v252, v122, v252
	v_add_f32_e32 v253, v123, v253
	v_add_f32_e32 v250, v124, v250
	v_cvt_pk_bf16_f32 v162, v116, v117
	v_cvt_pk_bf16_f32 v163, v118, v119
	ds_read_b64_tr_b16 v[116:117], v208 offset:35840
	ds_read_b64_tr_b16 v[118:119], v208 offset:36352
	s_waitcnt lgkmcnt(14)
	v_mfma_f32_32x32x16_bf16 v[96:111], v[156:159], v[2:5], v[96:111]
	v_add_f32_e32 v251, v125, v251
	v_add_f32_e32 v252, v126, v252
	v_add_f32_e32 v253, v127, v253
	v_add_f32_e32 v250, v251, v250
	v_cvt_pk_bf16_f32 v6, v120, v121
	v_cvt_pk_bf16_f32 v7, v122, v123
	ds_read_b64_tr_b16 v[120:121], v208 offset:39936
	ds_read_b64_tr_b16 v[122:123], v208 offset:40448
	v_mfma_f32_32x32x16_bf16 v[80:95], v[152:155], v[2:5], v[80:95]
	v_add_f32_e32 v252, v253, v252
	v_add_f32_e32 v114, v252, v250
	v_cvt_pk_bf16_f32 v8, v124, v125
	v_cvt_pk_bf16_f32 v9, v126, v127
	v_lshl_add_u64 v[112:113], v[204:205], 0, s[40:41]
	s_add_i32 s28, s61, s46
	s_mov_b32 s29, m0
	s_mov_b32 m0, s28
	s_nop 0
	global_load_lds_dwordx4 v[112:113], off
	s_mov_b32 m0, s29
	v_lshl_add_u64 v[112:113], v[206:207], 0, s[24:25]
	s_add_i32 s28, s21, s47
	s_mov_b32 s29, m0
	s_mov_b32 m0, s28
	s_nop 0
	global_load_lds_dwordx4 v[112:113], off
	s_mov_b32 m0, s29
	v_max_f32_e32 v112, v96, v96
	v_max_f32_e32 v112, 0xff800000, v112
	v_max3_f32 v113, v98, s69, v99
	s_nop 0
	v_max3_f32 v112, v112, v97, v80
	v_max3_f32 v113, v113, v82, v83
	v_max3_f32 v112, v112, v81, v100
	v_max3_f32 v113, v113, v102, v103
	v_max3_f32 v112, v112, v101, v84
	v_max3_f32 v113, v113, v86, v87
	v_max3_f32 v112, v112, v85, v104
	v_max3_f32 v113, v113, v106, v107
	v_max3_f32 v112, v112, v105, v88
	v_max3_f32 v113, v113, v90, v91
	v_max3_f32 v112, v112, v89, v108
	v_max3_f32 v113, v113, v110, v111
	v_max3_f32 v112, v112, v109, v92
	v_max3_f32 v113, v113, v94, v95
	v_max3_f32 v112, v112, v93, v113
	v_mov_b32_e32 v113, v112
	s_nop 1
	v_permlane32_swap_b32_e32 v112, v113
	v_max3_f32 v112, v112, s69, v113
	v_cmp_lt_f32_e32 vcc, s72, v112
	s_cmp_lg_u64 vcc, 0
	v_add_f32_e32 v0, v0, v114
	s_cselect_b64 s[28:29], -1, 0
	s_cbranch_vccnz .LBB0_1330

.LBB0_1339:
	ds_read_b64_tr_b16 v[196:197], v222 offset:49152
	ds_read_b64_tr_b16 v[198:199], v222 offset:49664
	s_waitcnt lgkmcnt(9)
	v_mfma_f32_32x32x16_bf16 v[128:143], v[112:115], v[172:175], v[64:79]
	v_add_f32_e32 v250, v96, v97
	v_add_f32_e32 v251, v98, v99
	v_add_f32_e32 v252, v100, v101
	v_add_f32_e32 v253, v102, v103
	v_add_f32_e32 v250, v104, v250
	v_cvt_pk_bf16_f32 v176, v96, v97
	v_cvt_pk_bf16_f32 v177, v98, v99
	ds_read_b64_tr_b16 v[192:193], v222 offset:53248
	ds_read_b64_tr_b16 v[194:195], v222 offset:53760
	s_waitcnt lgkmcnt(10)
	v_mfma_f32_32x32x16_bf16 v[112:127], v[188:191], v[172:175], v[64:79]
	v_add_f32_e32 v251, v105, v251
	v_add_f32_e32 v252, v106, v252
	v_add_f32_e32 v253, v107, v253
	v_add_f32_e32 v250, v108, v250
	v_cvt_pk_bf16_f32 v178, v100, v101
	v_cvt_pk_bf16_f32 v179, v102, v103
	ds_read_b64_tr_b16 v[96:97], v222 offset:50176
	ds_read_b64_tr_b16 v[98:99], v222 offset:50688
	s_waitcnt lgkmcnt(11)
	v_mfma_f32_32x32x16_bf16 v[128:143], v[184:187], v[168:171], v[128:143]
	v_add_f32_e32 v251, v109, v251
	v_add_f32_e32 v252, v110, v252
	v_add_f32_e32 v253, v111, v253
	v_add_f32_e32 v250, v80, v250
	v_cvt_pk_bf16_f32 v164, v104, v105
	v_cvt_pk_bf16_f32 v165, v106, v107
	ds_read_b64_tr_b16 v[100:101], v222 offset:54272
	ds_read_b64_tr_b16 v[102:103], v222 offset:54784
	s_waitcnt lgkmcnt(12)
	v_mfma_f32_32x32x16_bf16 v[112:127], v[180:183], v[168:171], v[112:127]
	v_add_f32_e32 v251, v81, v251
	v_add_f32_e32 v252, v82, v252
	v_add_f32_e32 v253, v83, v253
	v_add_f32_e32 v250, v84, v250
	v_cvt_pk_bf16_f32 v166, v108, v109
	v_cvt_pk_bf16_f32 v167, v110, v111
	ds_read_b64_tr_b16 v[104:105], v222 offset:51200
	ds_read_b64_tr_b16 v[106:107], v222 offset:51712
	s_waitcnt lgkmcnt(13)
	v_mfma_f32_32x32x16_bf16 v[128:143], v[156:159], v[10:13], v[128:143]
	v_add_f32_e32 v251, v85, v251
	v_add_f32_e32 v252, v86, v252
	v_add_f32_e32 v253, v87, v253
	v_add_f32_e32 v250, v88, v250
	v_cvt_pk_bf16_f32 v160, v80, v81
	v_cvt_pk_bf16_f32 v161, v82, v83
	ds_read_b64_tr_b16 v[80:81], v222 offset:55296
	ds_read_b64_tr_b16 v[82:83], v222 offset:55808
	s_waitcnt lgkmcnt(14)
	v_mfma_f32_32x32x16_bf16 v[112:127], v[152:155], v[10:13], v[112:127]
	v_add_f32_e32 v251, v89, v251
	v_add_f32_e32 v252, v90, v252
	v_add_f32_e32 v253, v91, v253
	v_add_f32_e32 v250, v92, v250
	v_cvt_pk_bf16_f32 v162, v84, v85
	v_cvt_pk_bf16_f32 v163, v86, v87
	ds_read_b64_tr_b16 v[84:85], v222 offset:52224
	ds_read_b64_tr_b16 v[86:87], v222 offset:52736
	s_waitcnt lgkmcnt(14)
	v_mfma_f32_32x32x16_bf16 v[128:143], v[148:151], v[2:5], v[128:143]
	v_add_f32_e32 v251, v93, v251
	v_add_f32_e32 v252, v94, v252
	v_add_f32_e32 v253, v95, v253
	v_add_f32_e32 v250, v251, v250
	v_cvt_pk_bf16_f32 v6, v88, v89
	v_cvt_pk_bf16_f32 v7, v90, v91
	ds_read_b64_tr_b16 v[88:89], v222 offset:56320
	ds_read_b64_tr_b16 v[90:91], v222 offset:56832
	v_mfma_f32_32x32x16_bf16 v[112:127], v[144:147], v[2:5], v[112:127]
	v_add_f32_e32 v252, v253, v252
	v_add_f32_e32 v108, v252, v250
	v_cvt_pk_bf16_f32 v8, v92, v93
	v_cvt_pk_bf16_f32 v9, v94, v95
	v_lshl_add_u64 v[92:93], v[200:201], 0, s[80:81]
	s_mov_b32 s20, m0
	s_mov_b32 m0, s45
	s_nop 0
	global_load_lds_dwordx4 v[92:93], off
	s_mov_b32 m0, s20
	s_mov_b64 s[20:21], 0x104000
	s_cmp_lg_u32 0, -1
	v_lshl_add_u64 v[92:93], v[14:15], 0, s[20:21]
	s_cselect_b32 s20, 0, 0
	s_add_i32 s20, s20, s8
	s_add_i32 s20, s20, 0xa000
	s_mov_b32 s21, m0
	s_mov_b32 m0, s20
	s_nop 0
	global_load_lds_dwordx4 v[92:93], off
	s_mov_b32 m0, s21
	v_max_f32_e32 v92, v128, v128
	v_max_f32_e32 v92, 0xff800000, v92
	v_max3_f32 v93, v130, s69, v131
	v_max3_f32 v92, v92, v129, v112
	v_max3_f32 v93, v93, v114, v115
	v_max3_f32 v92, v92, v113, v132
	v_max3_f32 v93, v93, v134, v135
	v_max3_f32 v92, v92, v133, v116
	v_max3_f32 v93, v93, v118, v119
	v_max3_f32 v92, v92, v117, v136
	v_max3_f32 v93, v93, v138, v139
	v_max3_f32 v92, v92, v137, v120
	v_max3_f32 v93, v93, v122, v123
	v_max3_f32 v92, v92, v121, v140
	v_max3_f32 v93, v93, v142, v143
	v_max3_f32 v92, v92, v141, v124
	v_max3_f32 v93, v93, v126, v127
	v_max3_f32 v92, v92, v125, v93
	v_mov_b32_e32 v93, v92
	s_nop 1
	v_permlane32_swap_b32_e32 v92, v93
	v_max3_f32 v92, v92, s69, v93
	v_cmp_lt_f32_e32 vcc, s72, v92
	s_cmp_lg_u64 vcc, 0
	v_add_f32_e32 v0, v0, v108
	s_cselect_b64 s[28:29], -1, 0
	s_cbranch_vccnz .LBB0_1371

.LBB0_1342:
	ds_read_b64_tr_b16 v[180:181], v222 offset:57344
	ds_read_b64_tr_b16 v[182:183], v222 offset:57856
	s_waitcnt lgkmcnt(9)
	v_mfma_f32_32x32x16_bf16 v[144:159], v[92:95], v[172:175], v[64:79]
	v_add_f32_e32 v250, v128, v129
	v_add_f32_e32 v251, v130, v131
	v_add_f32_e32 v252, v132, v133
	v_add_f32_e32 v253, v134, v135
	v_add_f32_e32 v250, v136, v250
	v_cvt_pk_bf16_f32 v176, v128, v129
	v_cvt_pk_bf16_f32 v177, v130, v131
	ds_read_b64_tr_b16 v[108:109], v222 offset:61440
	ds_read_b64_tr_b16 v[110:111], v222 offset:61952
	s_waitcnt lgkmcnt(10)
	v_mfma_f32_32x32x16_bf16 v[80:95], v[204:207], v[172:175], v[64:79]
	v_add_f32_e32 v251, v137, v251
	v_add_f32_e32 v252, v138, v252
	v_add_f32_e32 v253, v139, v253
	v_add_f32_e32 v250, v140, v250
	v_cvt_pk_bf16_f32 v178, v132, v133
	v_cvt_pk_bf16_f32 v179, v134, v135
	ds_read_b64_tr_b16 v[96:97], v222 offset:58368
	ds_read_b64_tr_b16 v[98:99], v222 offset:58880
	s_waitcnt lgkmcnt(11)
	v_mfma_f32_32x32x16_bf16 v[144:159], v[208:211], v[168:171], v[144:159]
	v_add_f32_e32 v251, v141, v251
	v_add_f32_e32 v252, v142, v252
	v_add_f32_e32 v253, v143, v253
	v_add_f32_e32 v250, v112, v250
	v_cvt_pk_bf16_f32 v164, v136, v137
	v_cvt_pk_bf16_f32 v165, v138, v139
	ds_read_b64_tr_b16 v[100:101], v222 offset:62464
	ds_read_b64_tr_b16 v[102:103], v222 offset:62976
	s_waitcnt lgkmcnt(12)
	v_mfma_f32_32x32x16_bf16 v[80:95], v[200:203], v[168:171], v[80:95]
	v_add_f32_e32 v251, v113, v251
	v_add_f32_e32 v252, v114, v252
	v_add_f32_e32 v253, v115, v253
	v_add_f32_e32 v250, v116, v250
	v_cvt_pk_bf16_f32 v166, v140, v141
	v_cvt_pk_bf16_f32 v167, v142, v143
	ds_read_b64_tr_b16 v[104:105], v222 offset:59392
	ds_read_b64_tr_b16 v[106:107], v222 offset:59904
	s_waitcnt lgkmcnt(13)
	v_mfma_f32_32x32x16_bf16 v[144:159], v[196:199], v[10:13], v[144:159]
	v_add_f32_e32 v251, v117, v251
	v_add_f32_e32 v252, v118, v252
	v_add_f32_e32 v253, v119, v253
	v_add_f32_e32 v250, v120, v250
	v_cvt_pk_bf16_f32 v160, v112, v113
	v_cvt_pk_bf16_f32 v161, v114, v115
	ds_read_b64_tr_b16 v[112:113], v222 offset:63488
	ds_read_b64_tr_b16 v[114:115], v222 offset:64000
	s_waitcnt lgkmcnt(14)
	v_mfma_f32_32x32x16_bf16 v[80:95], v[192:195], v[10:13], v[80:95]
	v_add_f32_e32 v251, v121, v251
	v_add_f32_e32 v252, v122, v252
	v_add_f32_e32 v253, v123, v253
	v_add_f32_e32 v250, v124, v250
	v_cvt_pk_bf16_f32 v162, v116, v117
	v_cvt_pk_bf16_f32 v163, v118, v119
	ds_read_b64_tr_b16 v[116:117], v222 offset:60416
	ds_read_b64_tr_b16 v[118:119], v222 offset:60928
	s_waitcnt lgkmcnt(14)
	v_mfma_f32_32x32x16_bf16 v[144:159], v[188:191], v[2:5], v[144:159]
	v_add_f32_e32 v251, v125, v251
	v_add_f32_e32 v252, v126, v252
	v_add_f32_e32 v253, v127, v253
	v_add_f32_e32 v250, v251, v250
	v_cvt_pk_bf16_f32 v6, v120, v121
	v_cvt_pk_bf16_f32 v7, v122, v123
	ds_read_b64_tr_b16 v[120:121], v222 offset:64512
	ds_read_b64_tr_b16 v[122:123], v222 offset:65024
	v_mfma_f32_32x32x16_bf16 v[80:95], v[184:187], v[2:5], v[80:95]
	v_add_f32_e32 v252, v253, v252
	v_add_f32_e32 v128, v252, v250
	v_cvt_pk_bf16_f32 v8, v124, v125
	v_cvt_pk_bf16_f32 v9, v126, v127
	s_mov_b64 s[20:21], 0x108000
	s_cmp_lg_u32 0, -1
	v_lshl_add_u64 v[124:125], v[14:15], 0, s[20:21]
	s_cselect_b32 s20, 0, 0
	s_add_i32 s20, s20, s8
	s_add_i32 s20, s20, 0xc000
	s_mov_b32 s21, m0
	s_mov_b32 m0, s20
	s_nop 0
	global_load_lds_dwordx4 v[124:125], off
	s_mov_b32 m0, s21
	v_max_f32_e32 v124, v144, v144
	v_max_f32_e32 v124, 0xff800000, v124
	v_max3_f32 v125, v146, s69, v147
	v_max3_f32 v124, v124, v145, v80
	v_max3_f32 v125, v125, v82, v83
	v_max3_f32 v124, v124, v81, v148
	v_max3_f32 v125, v125, v150, v151
	v_max3_f32 v124, v124, v149, v84
	v_max3_f32 v125, v125, v86, v87
	v_max3_f32 v124, v124, v85, v152
	v_max3_f32 v125, v125, v154, v155
	v_max3_f32 v124, v124, v153, v88
	v_max3_f32 v125, v125, v90, v91
	v_max3_f32 v124, v124, v89, v156
	v_max3_f32 v125, v125, v158, v159
	v_max3_f32 v124, v124, v157, v92
	v_max3_f32 v125, v125, v94, v95
	v_max3_f32 v124, v124, v93, v125
	v_mov_b32_e32 v125, v124
	s_nop 1
	v_permlane32_swap_b32_e32 v124, v125
	v_max3_f32 v124, v124, s69, v125
	v_cmp_lt_f32_e32 vcc, s72, v124
	s_cmp_lg_u64 vcc, 0
	v_add_f32_e32 v0, v0, v128
	s_cselect_b64 s[28:29], -1, 0
	s_cbranch_vccnz .LBB0_1374

.LBB0_1345:
	ds_read_b64_tr_b16 v[180:181], v222 offset:32768
	ds_read_b64_tr_b16 v[182:183], v222 offset:33280
	s_waitcnt lgkmcnt(9)
	v_mfma_f32_32x32x16_bf16 v[128:143], v[108:111], v[172:175], v[64:79]
	v_add_f32_e32 v250, v144, v145
	v_add_f32_e32 v251, v146, v147
	v_add_f32_e32 v252, v148, v149
	v_add_f32_e32 v253, v150, v151
	v_add_f32_e32 v250, v152, v250
	v_cvt_pk_bf16_f32 v176, v144, v145
	v_cvt_pk_bf16_f32 v177, v146, v147
	ds_read_b64_tr_b16 v[124:125], v222 offset:36864
	ds_read_b64_tr_b16 v[126:127], v222 offset:37376
	s_waitcnt lgkmcnt(10)
	v_mfma_f32_32x32x16_bf16 v[96:111], v[204:207], v[172:175], v[64:79]
	v_add_f32_e32 v251, v153, v251
	v_add_f32_e32 v252, v154, v252
	v_add_f32_e32 v253, v155, v253
	v_add_f32_e32 v250, v156, v250
	v_cvt_pk_bf16_f32 v178, v148, v149
	v_cvt_pk_bf16_f32 v179, v150, v151
	ds_read_b64_tr_b16 v[112:113], v222 offset:33792
	ds_read_b64_tr_b16 v[114:115], v222 offset:34304
	s_waitcnt lgkmcnt(11)
	v_mfma_f32_32x32x16_bf16 v[128:143], v[208:211], v[168:171], v[128:143]
	v_add_f32_e32 v251, v157, v251
	v_add_f32_e32 v252, v158, v252
	v_add_f32_e32 v253, v159, v253
	v_add_f32_e32 v250, v80, v250
	v_cvt_pk_bf16_f32 v164, v152, v153
	v_cvt_pk_bf16_f32 v165, v154, v155
	ds_read_b64_tr_b16 v[116:117], v222 offset:37888
	ds_read_b64_tr_b16 v[118:119], v222 offset:38400
	s_waitcnt lgkmcnt(12)
	v_mfma_f32_32x32x16_bf16 v[96:111], v[200:203], v[168:171], v[96:111]
	v_add_f32_e32 v251, v81, v251
	v_add_f32_e32 v252, v82, v252
	v_add_f32_e32 v253, v83, v253
	v_add_f32_e32 v250, v84, v250
	v_cvt_pk_bf16_f32 v166, v156, v157
	v_cvt_pk_bf16_f32 v167, v158, v159
	ds_read_b64_tr_b16 v[120:121], v222 offset:34816
	ds_read_b64_tr_b16 v[122:123], v222 offset:35328
	s_waitcnt lgkmcnt(13)
	v_mfma_f32_32x32x16_bf16 v[128:143], v[196:199], v[10:13], v[128:143]
	v_add_f32_e32 v251, v85, v251
	v_add_f32_e32 v252, v86, v252
	v_add_f32_e32 v253, v87, v253
	v_add_f32_e32 v250, v88, v250
	v_cvt_pk_bf16_f32 v160, v80, v81
	v_cvt_pk_bf16_f32 v161, v82, v83
	ds_read_b64_tr_b16 v[80:81], v222 offset:38912
	ds_read_b64_tr_b16 v[82:83], v222 offset:39424
	s_waitcnt lgkmcnt(14)
	v_mfma_f32_32x32x16_bf16 v[96:111], v[192:195], v[10:13], v[96:111]
	v_add_f32_e32 v251, v89, v251
	v_add_f32_e32 v252, v90, v252
	v_add_f32_e32 v253, v91, v253
	v_add_f32_e32 v250, v92, v250
	v_cvt_pk_bf16_f32 v162, v84, v85
	v_cvt_pk_bf16_f32 v163, v86, v87
	ds_read_b64_tr_b16 v[84:85], v222 offset:35840
	ds_read_b64_tr_b16 v[86:87], v222 offset:36352
	s_waitcnt lgkmcnt(14)
	v_mfma_f32_32x32x16_bf16 v[128:143], v[188:191], v[2:5], v[128:143]
	v_add_f32_e32 v251, v93, v251
	v_add_f32_e32 v252, v94, v252
	v_add_f32_e32 v253, v95, v253
	v_add_f32_e32 v250, v251, v250
	v_cvt_pk_bf16_f32 v6, v88, v89
	v_cvt_pk_bf16_f32 v7, v90, v91
	ds_read_b64_tr_b16 v[88:89], v222 offset:39936
	ds_read_b64_tr_b16 v[90:91], v222 offset:40448
	v_mfma_f32_32x32x16_bf16 v[96:111], v[184:187], v[2:5], v[96:111]
	v_add_f32_e32 v252, v253, v252
	v_add_f32_e32 v144, v252, v250
	v_cvt_pk_bf16_f32 v8, v92, v93
	v_cvt_pk_bf16_f32 v9, v94, v95
	s_cmp_lg_u32 0, -1
	s_cselect_b32 s20, 0, 0
	v_lshl_add_u64 v[14:15], v[14:15], 0, s[80:81]
	s_add_i32 s8, s20, s8
	s_add_i32 s8, s8, 0xe000
	s_mov_b32 s20, m0
	s_mov_b32 m0, s8
	s_nop 0
	global_load_lds_dwordx4 v[14:15], off
	s_mov_b32 m0, s20
	v_max_f32_e32 v14, v128, v128
	v_max_f32_e32 v14, 0xff800000, v14
	v_max3_f32 v15, v130, s69, v131
	v_max3_f32 v14, v14, v129, v96
	v_max3_f32 v15, v15, v98, v99
	v_max3_f32 v14, v14, v97, v132
	v_max3_f32 v15, v15, v134, v135
	v_max3_f32 v14, v14, v133, v100
	v_max3_f32 v15, v15, v102, v103
	v_max3_f32 v14, v14, v101, v136
	v_max3_f32 v15, v15, v138, v139
	v_max3_f32 v14, v14, v137, v104
	v_max3_f32 v15, v15, v106, v107
	v_max3_f32 v14, v14, v105, v140
	v_max3_f32 v15, v15, v142, v143
	v_max3_f32 v14, v14, v141, v108
	v_max3_f32 v15, v15, v110, v111
	v_max3_f32 v14, v14, v109, v15
	v_mov_b32_e32 v15, v14
	s_nop 1
	v_permlane32_swap_b32_e32 v14, v15
	v_max3_f32 v14, v14, s69, v15
	v_cmp_lt_f32_e32 vcc, s72, v14
	s_cmp_lg_u64 vcc, 0
	v_add_f32_e32 v0, v0, v144
	s_cselect_b64 s[28:29], -1, 0
	s_cbranch_vccnz .LBB0_1377

.LBB0_1348:
	ds_read_b64_tr_b16 v[152:153], v222 offset:40960
	ds_read_b64_tr_b16 v[154:155], v222 offset:41472
	s_waitcnt lgkmcnt(9)
	v_mfma_f32_32x32x16_bf16 v[112:127], v[92:95], v[172:175], v[64:79]
	v_add_f32_e32 v250, v128, v129
	v_add_f32_e32 v251, v130, v131
	v_add_f32_e32 v252, v132, v133
	v_add_f32_e32 v253, v134, v135
	v_add_f32_e32 v250, v136, v250
	v_cvt_pk_bf16_f32 v176, v128, v129
	v_cvt_pk_bf16_f32 v177, v130, v131
	ds_read_b64_tr_b16 v[148:149], v222 offset:45056
	ds_read_b64_tr_b16 v[150:151], v222 offset:45568
	s_waitcnt lgkmcnt(10)
	v_mfma_f32_32x32x16_bf16 v[80:95], v[192:195], v[172:175], v[64:79]
	v_add_f32_e32 v251, v137, v251
	v_add_f32_e32 v252, v138, v252
	v_add_f32_e32 v253, v139, v253
	v_add_f32_e32 v250, v140, v250
	v_cvt_pk_bf16_f32 v178, v132, v133
	v_cvt_pk_bf16_f32 v179, v134, v135
	ds_read_b64_tr_b16 v[128:129], v222 offset:41984
	ds_read_b64_tr_b16 v[130:131], v222 offset:42496
	s_waitcnt lgkmcnt(11)
	v_mfma_f32_32x32x16_bf16 v[112:127], v[196:199], v[168:171], v[112:127]
	v_add_f32_e32 v251, v141, v251
	v_add_f32_e32 v252, v142, v252
	v_add_f32_e32 v253, v143, v253
	v_add_f32_e32 v250, v96, v250
	v_cvt_pk_bf16_f32 v164, v136, v137
	v_cvt_pk_bf16_f32 v165, v138, v139
	ds_read_b64_tr_b16 v[132:133], v222 offset:46080
	ds_read_b64_tr_b16 v[134:135], v222 offset:46592
	s_waitcnt lgkmcnt(12)
	v_mfma_f32_32x32x16_bf16 v[80:95], v[188:191], v[168:171], v[80:95]
	v_add_f32_e32 v251, v97, v251
	v_add_f32_e32 v252, v98, v252
	v_add_f32_e32 v253, v99, v253
	v_add_f32_e32 v250, v100, v250
	v_cvt_pk_bf16_f32 v166, v140, v141
	v_cvt_pk_bf16_f32 v167, v142, v143
	ds_read_b64_tr_b16 v[136:137], v222 offset:43008
	ds_read_b64_tr_b16 v[138:139], v222 offset:43520
	s_waitcnt lgkmcnt(13)
	v_mfma_f32_32x32x16_bf16 v[112:127], v[184:187], v[10:13], v[112:127]
	v_add_f32_e32 v251, v101, v251
	v_add_f32_e32 v252, v102, v252
	v_add_f32_e32 v253, v103, v253
	v_add_f32_e32 v250, v104, v250
	v_cvt_pk_bf16_f32 v160, v96, v97
	v_cvt_pk_bf16_f32 v161, v98, v99
	ds_read_b64_tr_b16 v[96:97], v222 offset:47104
	ds_read_b64_tr_b16 v[98:99], v222 offset:47616
	s_waitcnt lgkmcnt(14)
	v_mfma_f32_32x32x16_bf16 v[80:95], v[180:183], v[10:13], v[80:95]
	v_add_f32_e32 v251, v105, v251
	v_add_f32_e32 v252, v106, v252
	v_add_f32_e32 v253, v107, v253
	v_add_f32_e32 v250, v108, v250
	v_cvt_pk_bf16_f32 v162, v100, v101
	v_cvt_pk_bf16_f32 v163, v102, v103
	ds_read_b64_tr_b16 v[100:101], v222 offset:44032
	ds_read_b64_tr_b16 v[102:103], v222 offset:44544
	s_waitcnt lgkmcnt(14)
	v_mfma_f32_32x32x16_bf16 v[112:127], v[156:159], v[2:5], v[112:127]
	v_add_f32_e32 v251, v109, v251
	v_add_f32_e32 v252, v110, v252
	v_add_f32_e32 v253, v111, v253
	v_add_f32_e32 v250, v251, v250
	v_cvt_pk_bf16_f32 v6, v104, v105
	v_cvt_pk_bf16_f32 v7, v106, v107
	ds_read_b64_tr_b16 v[104:105], v222 offset:48128
	ds_read_b64_tr_b16 v[106:107], v222 offset:48640
	v_mfma_f32_32x32x16_bf16 v[80:95], v[144:147], v[2:5], v[80:95]
	v_add_f32_e32 v252, v253, v252
	v_add_f32_e32 v14, v252, v250
	v_cvt_pk_bf16_f32 v8, v108, v109
	v_cvt_pk_bf16_f32 v9, v110, v111
	s_nop 0
	v_add_f32_e32 v201, v0, v14
	v_max_f32_e32 v0, v112, v112
	v_max_f32_e32 v0, 0xff800000, v0
	v_max3_f32 v14, v114, s69, v115
	s_nop 2
	v_max3_f32 v0, v0, v113, v80
	v_max3_f32 v14, v14, v82, v83
	v_max3_f32 v0, v0, v81, v116
	v_max3_f32 v14, v14, v118, v119
	v_max3_f32 v0, v0, v117, v84
	v_max3_f32 v14, v14, v86, v87
	v_max3_f32 v0, v0, v85, v120
	v_max3_f32 v14, v14, v122, v123
	v_max3_f32 v0, v0, v121, v88
	v_max3_f32 v14, v14, v90, v91
	v_max3_f32 v0, v0, v89, v124
	v_max3_f32 v14, v14, v126, v127
	v_max3_f32 v0, v0, v125, v92
	v_max3_f32 v14, v14, v94, v95
	v_max3_f32 v0, v0, v93, v14
	v_mov_b32_e32 v14, v0
	s_nop 1
	v_permlane32_swap_b32_e32 v0, v14
	v_max3_f32 v0, v0, s69, v14
	v_cmp_lt_f32_e32 vcc, s72, v0
	s_cmp_lg_u64 vcc, 0
	s_cselect_b64 s[28:29], -1, 0
	s_cbranch_vccnz .LBB0_1380

.LBB0_1351:
	v_lshrrev_b32_e32 v200, 3, v221
	v_or_b32_e32 v6, s6, v200
	v_mov_b32_e32 v7, s7
	v_lshlrev_b64 v[14:15], 11, v[6:7]
	v_lshl_add_u64 v[6:7], s[48:49], 0, v[14:15]
	s_lshl_b32 s8, s26, 1
	v_and_b32_e32 v0, 56, v220
	v_lshl_add_u64 v[6:7], v[6:7], 0, s[8:9]
	v_lshlrev_b32_e32 v0, 1, v0
	v_lshl_add_u64 v[6:7], v[6:7], 0, v[0:1]
	v_add_co_u32_e32 v96, vcc, s67, v6
	s_nop 1
	v_addc_co_u32_e32 v97, vcc, 0, v7, vcc
	global_load_dwordx4 v[140:143], v[6:7], off
	global_load_dwordx4 v[136:139], v[96:97], off
	v_add_co_u32_e32 v96, vcc, s66, v6
	s_nop 1
	v_addc_co_u32_e32 v97, vcc, 0, v7, vcc
	v_add_co_u32_e32 v6, vcc, s63, v6
	s_nop 1
	v_addc_co_u32_e32 v7, vcc, 0, v7, vcc
	global_load_dwordx4 v[132:135], v[96:97], off
	global_load_dwordx4 v[128:131], v[6:7], off
	ds_read_b64_tr_b16 v[148:149], v222 offset:49152
	ds_read_b64_tr_b16 v[150:151], v222 offset:49664
	s_waitcnt lgkmcnt(9)
	v_mfma_f32_32x32x16_bf16 v[96:111], v[196:199], v[172:175], v[64:79]
	v_add_f32_e32 v250, v112, v113
	v_add_f32_e32 v251, v114, v115
	v_add_f32_e32 v252, v116, v117
	v_add_f32_e32 v253, v118, v119
	v_add_f32_e32 v250, v120, v250
	v_cvt_pk_bf16_f32 v176, v112, v113
	v_cvt_pk_bf16_f32 v177, v114, v115
	ds_read_b64_tr_b16 v[112:113], v222 offset:53248
	ds_read_b64_tr_b16 v[114:115], v222 offset:53760
	s_waitcnt lgkmcnt(10)
	v_mfma_f32_32x32x16_bf16 v[64:79], v[192:195], v[172:175], v[64:79]
	v_add_f32_e32 v251, v121, v251
	v_add_f32_e32 v252, v122, v252
	v_add_f32_e32 v253, v123, v253
	v_add_f32_e32 v250, v124, v250
	v_cvt_pk_bf16_f32 v178, v116, v117
	v_cvt_pk_bf16_f32 v179, v118, v119
	ds_read_b64_tr_b16 v[116:117], v222 offset:50176
	ds_read_b64_tr_b16 v[118:119], v222 offset:50688
	s_waitcnt lgkmcnt(11)
	v_mfma_f32_32x32x16_bf16 v[96:111], v[188:191], v[168:171], v[96:111]
	v_add_f32_e32 v251, v125, v251
	v_add_f32_e32 v252, v126, v252
	v_add_f32_e32 v253, v127, v253
	v_add_f32_e32 v250, v80, v250
	v_cvt_pk_bf16_f32 v164, v120, v121
	v_cvt_pk_bf16_f32 v165, v122, v123
	ds_read_b64_tr_b16 v[120:121], v222 offset:54272
	ds_read_b64_tr_b16 v[122:123], v222 offset:54784
	s_waitcnt lgkmcnt(12)
	v_mfma_f32_32x32x16_bf16 v[64:79], v[184:187], v[168:171], v[64:79]
	v_add_f32_e32 v251, v81, v251
	v_add_f32_e32 v252, v82, v252
	v_add_f32_e32 v253, v83, v253
	v_add_f32_e32 v250, v84, v250
	v_cvt_pk_bf16_f32 v166, v124, v125
	v_cvt_pk_bf16_f32 v167, v126, v127
	ds_read_b64_tr_b16 v[124:125], v222 offset:51200
	ds_read_b64_tr_b16 v[126:127], v222 offset:51712
	s_waitcnt lgkmcnt(13)
	v_mfma_f32_32x32x16_bf16 v[96:111], v[180:183], v[10:13], v[96:111]
	v_add_f32_e32 v251, v85, v251
	v_add_f32_e32 v252, v86, v252
	v_add_f32_e32 v253, v87, v253
	v_add_f32_e32 v250, v88, v250
	v_cvt_pk_bf16_f32 v160, v80, v81
	v_cvt_pk_bf16_f32 v161, v82, v83
	ds_read_b64_tr_b16 v[168:169], v222 offset:55296
	ds_read_b64_tr_b16 v[170:171], v222 offset:55808
	s_waitcnt lgkmcnt(14)
	v_mfma_f32_32x32x16_bf16 v[64:79], v[156:159], v[10:13], v[64:79]
	v_add_f32_e32 v251, v89, v251
	v_add_f32_e32 v252, v90, v252
	v_add_f32_e32 v253, v91, v253
	v_add_f32_e32 v250, v92, v250
	v_cvt_pk_bf16_f32 v162, v84, v85
	v_cvt_pk_bf16_f32 v163, v86, v87
	ds_read_b64_tr_b16 v[10:11], v222 offset:52224
	ds_read_b64_tr_b16 v[12:13], v222 offset:52736
	s_waitcnt lgkmcnt(14)
	v_mfma_f32_32x32x16_bf16 v[96:111], v[152:155], v[2:5], v[96:111]
	v_add_f32_e32 v251, v93, v251
	v_add_f32_e32 v252, v94, v252
	v_add_f32_e32 v253, v95, v253
	v_add_f32_e32 v250, v251, v250
	v_cvt_pk_bf16_f32 v6, v88, v89
	v_cvt_pk_bf16_f32 v7, v90, v91
	ds_read_b64_tr_b16 v[152:153], v222 offset:56320
	ds_read_b64_tr_b16 v[154:155], v222 offset:56832
	v_mfma_f32_32x32x16_bf16 v[64:79], v[144:147], v[2:5], v[64:79]
	v_add_f32_e32 v252, v253, v252
	v_add_f32_e32 v80, v252, v250
	v_cvt_pk_bf16_f32 v8, v92, v93
	v_cvt_pk_bf16_f32 v9, v94, v95
	v_max_f32_e32 v2, v96, v96
	v_max_f32_e32 v2, 0xff800000, v2
	v_max3_f32 v3, v98, s69, v99
	s_nop 4
	v_max3_f32 v2, v2, v97, v64
	v_max3_f32 v3, v3, v66, v67
	v_max3_f32 v2, v2, v65, v100
	v_max3_f32 v3, v3, v102, v103
	v_max3_f32 v2, v2, v101, v68
	v_max3_f32 v3, v3, v70, v71
	v_max3_f32 v2, v2, v69, v104
	v_max3_f32 v3, v3, v106, v107
	v_max3_f32 v2, v2, v105, v72
	v_max3_f32 v3, v3, v74, v75
	v_max3_f32 v2, v2, v73, v108
	v_max3_f32 v3, v3, v110, v111
	v_max3_f32 v4, v2, v109, v76
	v_max3_f32 v3, v3, v78, v79
	v_max3_f32 v3, v4, v77, v3
	v_mov_b32_e32 v4, v3
	s_nop 1
	v_permlane32_swap_b32_e32 v3, v4
	v_max3_f32 v3, v3, s69, v4
	v_cmp_lt_f32_e32 vcc, s72, v3
	s_cmp_lg_u64 vcc, 0
	v_add_f32_e32 v2, v201, v80
	s_cselect_b64 s[28:29], -1, 0
	s_cbranch_vccnz .LBB0_1383

.LBB0_1354:
	v_add_f32_e32 v250, v96, v97
	v_add_f32_e32 v251, v98, v99
	v_add_f32_e32 v252, v100, v101
	v_add_f32_e32 v253, v102, v103
	v_add_f32_e32 v250, v104, v250
	v_add_f32_e32 v251, v105, v251
	v_add_f32_e32 v252, v106, v252
	v_add_f32_e32 v253, v107, v253
	v_add_f32_e32 v250, v108, v250
	v_add_f32_e32 v251, v109, v251
	v_add_f32_e32 v252, v110, v252
	v_add_f32_e32 v253, v111, v253
	v_add_f32_e32 v250, v64, v250
	v_add_f32_e32 v251, v65, v251
	v_add_f32_e32 v252, v66, v252
	v_add_f32_e32 v253, v67, v253
	v_add_f32_e32 v250, v68, v250
	v_add_f32_e32 v251, v69, v251
	v_add_f32_e32 v252, v70, v252
	v_add_f32_e32 v253, v71, v253
	v_add_f32_e32 v250, v72, v250
	v_add_f32_e32 v251, v73, v251
	v_add_f32_e32 v252, v74, v252
	v_add_f32_e32 v253, v75, v253
	v_add_f32_e32 v250, v76, v250
	v_add_f32_e32 v251, v77, v251
	v_add_f32_e32 v252, v78, v252
	v_add_f32_e32 v253, v79, v253
	v_add_f32_e32 v250, v251, v250
	v_add_f32_e32 v252, v253, v252
	v_add_f32_e32 v3, v252, v250
	v_add_f32_e32 v2, v2, v3
	v_cvt_pk_bf16_f32 v4, v96, v97
	v_cvt_pk_bf16_f32 v5, v98, v99
	v_cvt_pk_bf16_f32 v6, v100, v101
	v_cvt_pk_bf16_f32 v7, v102, v103
	v_cvt_pk_bf16_f32 v8, v104, v105
	v_cvt_pk_bf16_f32 v9, v106, v107
	v_cvt_pk_bf16_f32 v10, v108, v109
	v_cvt_pk_bf16_f32 v11, v110, v111
	v_cvt_pk_bf16_f32 v64, v64, v65
	v_cvt_pk_bf16_f32 v65, v66, v67
	v_cvt_pk_bf16_f32 v66, v68, v69
	v_cvt_pk_bf16_f32 v67, v70, v71
	v_cvt_pk_bf16_f32 v68, v72, v73
	v_cvt_pk_bf16_f32 v69, v74, v75
	v_cvt_pk_bf16_f32 v70, v76, v77
	v_cvt_pk_bf16_f32 v71, v78, v79
	s_cmp_lg_u32 0, -1
	s_cselect_b32 s20, 0, 0
	s_add_i32 s20, s20, 0xe000
	v_add_u32_e32 v3, s20, v216
	v_add3_u32 v3, v3, v213, v217
	ds_read_b64_tr_b16 v[72:73],v3 offset:0
	ds_read_b64_tr_b16 v[74:75],v3 offset:512
	ds_read_b64_tr_b16 v[76:77],v3 offset:1024
	ds_read_b64_tr_b16 v[78:79],v3 offset:1536
	ds_read_b64_tr_b16 v[80:81],v3 offset:2048
	ds_read_b64_tr_b16 v[82:83],v3 offset:2560
	ds_read_b64_tr_b16 v[84:85],v3 offset:3072
	ds_read_b64_tr_b16 v[86:87],v3 offset:3584
	s_waitcnt lgkmcnt(0)
	s_nop 0
	v_mfma_f32_32x32x16_bf16 v[32:47], v[4:7], v[72:75], v[32:47]
	ds_read_b64_tr_b16 v[72:73],v3 offset:4096
	ds_read_b64_tr_b16 v[74:75],v3 offset:4608
	v_mfma_f32_32x32x16_bf16 v[32:47], v[8:11], v[76:79], v[32:47]
	ds_read_b64_tr_b16 v[76:77],v3 offset:5120
	ds_read_b64_tr_b16 v[78:79],v3 offset:5632
	v_mfma_f32_32x32x16_bf16 v[32:47], v[64:67], v[80:83], v[32:47]
	ds_read_b64_tr_b16 v[80:81],v3 offset:6144
	ds_read_b64_tr_b16 v[82:83],v3 offset:6656
	ds_read_b64_tr_b16 v[88:89],v3 offset:7168
	ds_read_b64_tr_b16 v[90:91],v3 offset:7680
	s_waitcnt lgkmcnt(0)
	v_mfma_f32_32x32x16_bf16 v[32:47], v[68:71], v[84:87], v[32:47]
	v_mfma_f32_32x32x16_bf16 v[48:63], v[4:7], v[72:75], v[48:63]
	v_mov_b32_e32 v3, v2
	s_nop 1
	v_permlane32_swap_b32_e32 v2, v3
	v_mfma_f32_32x32x16_bf16 v[48:63], v[8:11], v[76:79], v[48:63]
	v_mfma_f32_32x32x16_bf16 v[48:63], v[64:67], v[80:83], v[48:63]
	v_mfma_f32_32x32x16_bf16 v[48:63], v[68:71], v[88:91], v[48:63]
	s_and_saveexec_b64 s[28:29], s[4:5]
	s_cbranch_execz .LBB0_1232
	v_add_f32_e32 v2, v2, v3
	ds_write_b32 v218, v2 offset:128
	s_branch .LBB0_1232
